# P2c keeps AF rows 56..127 of its chunk in VGPRs across the grid barrier and P2d reuses them (P2d loads AF only for rows 0..55)
# baseline (speedup 1.0000x reference)
; __device__ __forceinline__ float bf_lo(unsigned w) { return __uint_as_float(w << 16); }
; __device__ __forceinline__ float bf_hi(unsigned w) { return __uint_as_float(w & 0xffff0000u); }
; __global__ void __launch_bounds__(NTHR, 2) hybrid_block_fwd(Args a) {
;     ...
;         const int c2 = gtid & 1023, chunk = (gtid >> 10) & (NCH - 1), b = gtid >> 16;
;         const size_t r0 = (size_t)b * SEQ + (size_t)chunk * CH_L;
;         const u32x2* pab = (const u32x2*)((const unsigned*)AF + r0 * LW) + c2;
;         f32x2 P = (f32x2){1.f, 1.f}, H = (f32x2){0.f, 0.f};
; #pragma unroll 32
;         for (int i = 0; i < CH_L; ++i) { const u32x2 q = pab[(size_t)i * (LW / 2)];
;             const f32x2 av = (f32x2){__builtin_amdgcn_exp2f(bf_lo(q.x)), __builtin_amdgcn_exp2f(bf_lo(q.y))}, bv = (f32x2){bf_hi(q.x), bf_hi(q.y)}; P = P * av; H = av * H + bv; }
;         ((f32x2*)(AGGP + (size_t)(b * NCH + chunk) * LW))[c2] = P; ((f32x2*)(AGGH + (size_t)(b * NCH + chunk) * LW))[c2] = H;
.LBB0_613:
	s_or_b64 exec, exec, s[0:1]
	s_waitcnt lgkmcnt(0)
	v_mov_b32_e32 v0, v212
	v_readlane_b32 s0, v248, 8
	s_barrier
	s_nop 1
	v_add_u32_e32 v1, s0, v0
	v_and_b32_e32 v1, 0x3ff, v1
	v_lshlrev_b32_e32 v2, 3, v1
	v_add_u32_e32 v6, 0x100000, v2
	s_lshr_b32 s9, s0, 10
	s_lshl_b32 s10, s9, 20
	s_add_u32 s12, s92, s10
	s_addc_u32 s13, s93, 0
	global_load_dwordx2 v[18:19], v2, s[12:13]
	s_add_u32 s12, s12, 0x2000
	s_addc_u32 s13, s13, 0
	global_load_dwordx2 v[20:21], v2, s[12:13]
	s_add_u32 s12, s12, 0x2000
	s_addc_u32 s13, s13, 0
	global_load_dwordx2 v[22:23], v2, s[12:13]
	s_add_u32 s12, s12, 0x2000
	s_addc_u32 s13, s13, 0
	global_load_dwordx2 v[24:25], v2, s[12:13]
	s_add_u32 s12, s12, 0x2000
	s_addc_u32 s13, s13, 0
	global_load_dwordx2 v[26:27], v2, s[12:13]
	s_add_u32 s12, s12, 0x2000
	s_addc_u32 s13, s13, 0
	global_load_dwordx2 v[28:29], v2, s[12:13]
	s_add_u32 s12, s12, 0x2000
	s_addc_u32 s13, s13, 0
	global_load_dwordx2 v[30:31], v2, s[12:13]
	s_add_u32 s12, s12, 0x2000
	s_addc_u32 s13, s13, 0
	global_load_dwordx2 v[32:33], v2, s[12:13]
	s_add_u32 s12, s12, 0x2000
	s_addc_u32 s13, s13, 0
	global_load_dwordx2 v[34:35], v2, s[12:13]
	s_add_u32 s12, s12, 0x2000
	s_addc_u32 s13, s13, 0
	global_load_dwordx2 v[36:37], v2, s[12:13]
	s_add_u32 s12, s12, 0x2000
	s_addc_u32 s13, s13, 0
	global_load_dwordx2 v[38:39], v2, s[12:13]
	s_add_u32 s12, s12, 0x2000
	s_addc_u32 s13, s13, 0
	global_load_dwordx2 v[40:41], v2, s[12:13]
	s_add_u32 s12, s12, 0x2000
	s_addc_u32 s13, s13, 0
	global_load_dwordx2 v[42:43], v2, s[12:13]
	s_add_u32 s12, s12, 0x2000
	s_addc_u32 s13, s13, 0
	global_load_dwordx2 v[44:45], v2, s[12:13]
	s_add_u32 s12, s12, 0x2000
	s_addc_u32 s13, s13, 0
	global_load_dwordx2 v[46:47], v2, s[12:13]
	s_add_u32 s12, s12, 0x2000
	s_addc_u32 s13, s13, 0
	global_load_dwordx2 v[48:49], v2, s[12:13]
	s_add_u32 s12, s12, 0x2000
	s_addc_u32 s13, s13, 0
	global_load_dwordx2 v[50:51], v2, s[12:13]
	s_add_u32 s12, s12, 0x2000
	s_addc_u32 s13, s13, 0
	global_load_dwordx2 v[52:53], v2, s[12:13]
	s_add_u32 s12, s12, 0x2000
	s_addc_u32 s13, s13, 0
	global_load_dwordx2 v[54:55], v2, s[12:13]
	s_add_u32 s12, s12, 0x2000
	s_addc_u32 s13, s13, 0
	global_load_dwordx2 v[56:57], v2, s[12:13]
	s_add_u32 s12, s12, 0x2000
	s_addc_u32 s13, s13, 0
	global_load_dwordx2 v[58:59], v2, s[12:13]
	s_add_u32 s12, s12, 0x2000
	s_addc_u32 s13, s13, 0
	global_load_dwordx2 v[60:61], v2, s[12:13]
	s_add_u32 s12, s12, 0x2000
	s_addc_u32 s13, s13, 0
	global_load_dwordx2 v[62:63], v2, s[12:13]
	s_add_u32 s12, s12, 0x2000
	s_addc_u32 s13, s13, 0
	global_load_dwordx2 v[216:217], v2, s[12:13]
	s_add_u32 s12, s12, 0x2000
	s_addc_u32 s13, s13, 0
	global_load_dwordx2 v[218:219], v2, s[12:13]
	s_add_u32 s12, s12, 0x2000
	s_addc_u32 s13, s13, 0
	global_load_dwordx2 v[220:221], v2, s[12:13]
	s_add_u32 s12, s12, 0x2000
	s_addc_u32 s13, s13, 0
	global_load_dwordx2 v[222:223], v2, s[12:13]
	s_add_u32 s12, s12, 0x2000
	s_addc_u32 s13, s13, 0
	global_load_dwordx2 v[224:225], v2, s[12:13]
	s_add_u32 s12, s12, 0x2000
	s_addc_u32 s13, s13, 0
	global_load_dwordx2 v[226:227], v2, s[12:13]
	s_add_u32 s12, s12, 0x2000
	s_addc_u32 s13, s13, 0
	global_load_dwordx2 v[228:229], v2, s[12:13]
	s_add_u32 s12, s12, 0x2000
	s_addc_u32 s13, s13, 0
	global_load_dwordx2 v[230:231], v2, s[12:13]
	s_add_u32 s12, s12, 0x2000
	s_addc_u32 s13, s13, 0
	v_mov_b32_e32 v8, 1.0
	v_mov_b32_e32 v9, 1.0
	v_mov_b32_e32 v10, 0
	v_mov_b32_e32 v11, 0
	s_waitcnt vmcnt(30)
	v_lshlrev_b32_e32 v12, 16, v18
	v_lshlrev_b32_e32 v13, 16, v19
	v_exp_f32_e32 v12, v12
	v_exp_f32_e32 v13, v13
	v_and_b32_e32 v14, 0xffff0000, v18
	v_and_b32_e32 v15, 0xffff0000, v19
	global_load_dwordx2 v[18:19], v2, s[12:13]
	s_add_u32 s12, s12, 0x2000
	s_addc_u32 s13, s13, 0
	v_pk_mul_f32 v[8:9], v[8:9], v[12:13]
	v_pk_fma_f32 v[10:11], v[10:11], v[12:13], v[14:15]
	s_waitcnt vmcnt(30)
	v_lshlrev_b32_e32 v16, 16, v20
	v_lshlrev_b32_e32 v17, 16, v21
	v_exp_f32_e32 v16, v16
	v_exp_f32_e32 v17, v17
	v_and_b32_e32 v4, 0xffff0000, v20
	v_and_b32_e32 v5, 0xffff0000, v21
	global_load_dwordx2 v[20:21], v2, s[12:13]
	s_add_u32 s12, s12, 0x2000
	s_addc_u32 s13, s13, 0
	v_pk_mul_f32 v[8:9], v[8:9], v[16:17]
	v_pk_fma_f32 v[10:11], v[10:11], v[16:17], v[4:5]
	s_waitcnt vmcnt(30)
	v_lshlrev_b32_e32 v12, 16, v22
	v_lshlrev_b32_e32 v13, 16, v23
	v_exp_f32_e32 v12, v12
	v_exp_f32_e32 v13, v13
	v_and_b32_e32 v14, 0xffff0000, v22
	v_and_b32_e32 v15, 0xffff0000, v23
	global_load_dwordx2 v[22:23], v2, s[12:13]
	s_add_u32 s12, s12, 0x2000
	s_addc_u32 s13, s13, 0
	v_pk_mul_f32 v[8:9], v[8:9], v[12:13]
	v_pk_fma_f32 v[10:11], v[10:11], v[12:13], v[14:15]
	s_waitcnt vmcnt(30)
	v_lshlrev_b32_e32 v16, 16, v24
	v_lshlrev_b32_e32 v17, 16, v25
	v_exp_f32_e32 v16, v16
	v_exp_f32_e32 v17, v17
	v_and_b32_e32 v4, 0xffff0000, v24
	v_and_b32_e32 v5, 0xffff0000, v25
	global_load_dwordx2 v[24:25], v2, s[12:13]
	s_add_u32 s12, s12, 0x2000
	s_addc_u32 s13, s13, 0
	v_pk_mul_f32 v[8:9], v[8:9], v[16:17]
	v_pk_fma_f32 v[10:11], v[10:11], v[16:17], v[4:5]
	s_waitcnt vmcnt(30)
	v_lshlrev_b32_e32 v12, 16, v26
	v_lshlrev_b32_e32 v13, 16, v27
	v_exp_f32_e32 v12, v12
	v_exp_f32_e32 v13, v13
	v_and_b32_e32 v14, 0xffff0000, v26
	v_and_b32_e32 v15, 0xffff0000, v27
	global_load_dwordx2 v[26:27], v2, s[12:13]
	s_add_u32 s12, s12, 0x2000
	s_addc_u32 s13, s13, 0
	v_pk_mul_f32 v[8:9], v[8:9], v[12:13]
	v_pk_fma_f32 v[10:11], v[10:11], v[12:13], v[14:15]
	s_waitcnt vmcnt(30)
	v_lshlrev_b32_e32 v16, 16, v28
	v_lshlrev_b32_e32 v17, 16, v29
	v_exp_f32_e32 v16, v16
	v_exp_f32_e32 v17, v17
	v_and_b32_e32 v4, 0xffff0000, v28
	v_and_b32_e32 v5, 0xffff0000, v29
	global_load_dwordx2 v[28:29], v2, s[12:13]
	s_add_u32 s12, s12, 0x2000
	s_addc_u32 s13, s13, 0
	v_pk_mul_f32 v[8:9], v[8:9], v[16:17]
	v_pk_fma_f32 v[10:11], v[10:11], v[16:17], v[4:5]
	s_waitcnt vmcnt(30)
; __device__ __forceinline__ float bf_lo(unsigned w) { return __uint_as_float(w << 16); }
; __device__ __forceinline__ float bf_hi(unsigned w) { return __uint_as_float(w & 0xffff0000u); }
; __global__ void __launch_bounds__(NTHR, 2) hybrid_block_fwd(Args a) {
;     ...
;         for (int i = 0; i < CH_L; ++i) { const u32x2 q = pab[(size_t)i * (LW / 2)];
;             const f32x2 av = (f32x2){__builtin_amdgcn_exp2f(bf_lo(q.x)), __builtin_amdgcn_exp2f(bf_lo(q.y))}, bv = (f32x2){bf_hi(q.x), bf_hi(q.y)}; P = P * av; H = av * H + bv; }
	v_lshlrev_b32_e32 v12, 16, v30
	v_lshlrev_b32_e32 v13, 16, v31
	v_exp_f32_e32 v12, v12
	v_exp_f32_e32 v13, v13
	v_and_b32_e32 v14, 0xffff0000, v30
	v_and_b32_e32 v15, 0xffff0000, v31
	global_load_dwordx2 v[30:31], v2, s[12:13]
	s_add_u32 s12, s12, 0x2000
	s_addc_u32 s13, s13, 0
	v_pk_mul_f32 v[8:9], v[8:9], v[12:13]
	v_pk_fma_f32 v[10:11], v[10:11], v[12:13], v[14:15]
	s_waitcnt vmcnt(30)
	v_lshlrev_b32_e32 v16, 16, v32
	v_lshlrev_b32_e32 v17, 16, v33
	v_exp_f32_e32 v16, v16
	v_exp_f32_e32 v17, v17
	v_and_b32_e32 v4, 0xffff0000, v32
	v_and_b32_e32 v5, 0xffff0000, v33
	global_load_dwordx2 v[32:33], v2, s[12:13]
	s_add_u32 s12, s12, 0x2000
	s_addc_u32 s13, s13, 0
	v_pk_mul_f32 v[8:9], v[8:9], v[16:17]
	v_pk_fma_f32 v[10:11], v[10:11], v[16:17], v[4:5]
	s_waitcnt vmcnt(30)
	v_lshlrev_b32_e32 v12, 16, v34
	v_lshlrev_b32_e32 v13, 16, v35
	v_exp_f32_e32 v12, v12
	v_exp_f32_e32 v13, v13
	v_and_b32_e32 v14, 0xffff0000, v34
	v_and_b32_e32 v15, 0xffff0000, v35
	global_load_dwordx2 v[34:35], v2, s[12:13]
	s_add_u32 s12, s12, 0x2000
	s_addc_u32 s13, s13, 0
	v_pk_mul_f32 v[8:9], v[8:9], v[12:13]
	v_pk_fma_f32 v[10:11], v[10:11], v[12:13], v[14:15]
	s_waitcnt vmcnt(30)
	v_lshlrev_b32_e32 v16, 16, v36
	v_lshlrev_b32_e32 v17, 16, v37
	v_exp_f32_e32 v16, v16
	v_exp_f32_e32 v17, v17
	v_and_b32_e32 v4, 0xffff0000, v36
	v_and_b32_e32 v5, 0xffff0000, v37
	global_load_dwordx2 v[36:37], v2, s[12:13]
	s_add_u32 s12, s12, 0x2000
	s_addc_u32 s13, s13, 0
	v_pk_mul_f32 v[8:9], v[8:9], v[16:17]
	v_pk_fma_f32 v[10:11], v[10:11], v[16:17], v[4:5]
	s_waitcnt vmcnt(30)
	v_lshlrev_b32_e32 v12, 16, v38
	v_lshlrev_b32_e32 v13, 16, v39
	v_exp_f32_e32 v12, v12
	v_exp_f32_e32 v13, v13
	v_and_b32_e32 v14, 0xffff0000, v38
	v_and_b32_e32 v15, 0xffff0000, v39
	global_load_dwordx2 v[38:39], v2, s[12:13]
	s_add_u32 s12, s12, 0x2000
	s_addc_u32 s13, s13, 0
	v_pk_mul_f32 v[8:9], v[8:9], v[12:13]
	v_pk_fma_f32 v[10:11], v[10:11], v[12:13], v[14:15]
	s_waitcnt vmcnt(30)
	v_lshlrev_b32_e32 v16, 16, v40
	v_lshlrev_b32_e32 v17, 16, v41
	v_exp_f32_e32 v16, v16
	v_exp_f32_e32 v17, v17
	v_and_b32_e32 v4, 0xffff0000, v40
	v_and_b32_e32 v5, 0xffff0000, v41
	global_load_dwordx2 v[40:41], v2, s[12:13]
	s_add_u32 s12, s12, 0x2000
	s_addc_u32 s13, s13, 0
	v_pk_mul_f32 v[8:9], v[8:9], v[16:17]
	v_pk_fma_f32 v[10:11], v[10:11], v[16:17], v[4:5]
	s_waitcnt vmcnt(30)
	v_lshlrev_b32_e32 v12, 16, v42
	v_lshlrev_b32_e32 v13, 16, v43
	v_exp_f32_e32 v12, v12
	v_exp_f32_e32 v13, v13
	v_and_b32_e32 v14, 0xffff0000, v42
	v_and_b32_e32 v15, 0xffff0000, v43
	global_load_dwordx2 v[42:43], v2, s[12:13]
	s_add_u32 s12, s12, 0x2000
	s_addc_u32 s13, s13, 0
	v_pk_mul_f32 v[8:9], v[8:9], v[12:13]
	v_pk_fma_f32 v[10:11], v[10:11], v[12:13], v[14:15]
	s_waitcnt vmcnt(30)
	v_lshlrev_b32_e32 v16, 16, v44
	v_lshlrev_b32_e32 v17, 16, v45
	v_exp_f32_e32 v16, v16
	v_exp_f32_e32 v17, v17
	v_and_b32_e32 v4, 0xffff0000, v44
	v_and_b32_e32 v5, 0xffff0000, v45
	global_load_dwordx2 v[44:45], v2, s[12:13]
	s_add_u32 s12, s12, 0x2000
	s_addc_u32 s13, s13, 0
	v_pk_mul_f32 v[8:9], v[8:9], v[16:17]
	v_pk_fma_f32 v[10:11], v[10:11], v[16:17], v[4:5]
	s_waitcnt vmcnt(30)
	v_lshlrev_b32_e32 v12, 16, v46
	v_lshlrev_b32_e32 v13, 16, v47
	v_exp_f32_e32 v12, v12
	v_exp_f32_e32 v13, v13
	v_and_b32_e32 v14, 0xffff0000, v46
	v_and_b32_e32 v15, 0xffff0000, v47
	global_load_dwordx2 v[46:47], v2, s[12:13]
	s_add_u32 s12, s12, 0x2000
	s_addc_u32 s13, s13, 0
	v_pk_mul_f32 v[8:9], v[8:9], v[12:13]
	v_pk_fma_f32 v[10:11], v[10:11], v[12:13], v[14:15]
	s_waitcnt vmcnt(30)
	v_lshlrev_b32_e32 v16, 16, v48
	v_lshlrev_b32_e32 v17, 16, v49
	v_exp_f32_e32 v16, v16
	v_exp_f32_e32 v17, v17
	v_and_b32_e32 v4, 0xffff0000, v48
	v_and_b32_e32 v5, 0xffff0000, v49
	global_load_dwordx2 v[48:49], v2, s[12:13]
	s_add_u32 s12, s12, 0x2000
	s_addc_u32 s13, s13, 0
	v_pk_mul_f32 v[8:9], v[8:9], v[16:17]
	v_pk_fma_f32 v[10:11], v[10:11], v[16:17], v[4:5]
	s_waitcnt vmcnt(30)
	v_lshlrev_b32_e32 v12, 16, v50
	v_lshlrev_b32_e32 v13, 16, v51
	v_exp_f32_e32 v12, v12
	v_exp_f32_e32 v13, v13
	v_and_b32_e32 v14, 0xffff0000, v50
	v_and_b32_e32 v15, 0xffff0000, v51
	global_load_dwordx2 v[50:51], v2, s[12:13]
	s_add_u32 s12, s12, 0x2000
	s_addc_u32 s13, s13, 0
	v_pk_mul_f32 v[8:9], v[8:9], v[12:13]
	v_pk_fma_f32 v[10:11], v[10:11], v[12:13], v[14:15]
	s_waitcnt vmcnt(30)
	v_lshlrev_b32_e32 v16, 16, v52
	v_lshlrev_b32_e32 v17, 16, v53
	v_exp_f32_e32 v16, v16
	v_exp_f32_e32 v17, v17
	v_and_b32_e32 v4, 0xffff0000, v52
	v_and_b32_e32 v5, 0xffff0000, v53
	global_load_dwordx2 v[52:53], v2, s[12:13]
	s_add_u32 s12, s12, 0x2000
	s_addc_u32 s13, s13, 0
	v_pk_mul_f32 v[8:9], v[8:9], v[16:17]
	v_pk_fma_f32 v[10:11], v[10:11], v[16:17], v[4:5]
	s_waitcnt vmcnt(30)
	v_lshlrev_b32_e32 v12, 16, v54
	v_lshlrev_b32_e32 v13, 16, v55
	v_exp_f32_e32 v12, v12
	v_exp_f32_e32 v13, v13
	v_and_b32_e32 v14, 0xffff0000, v54
	v_and_b32_e32 v15, 0xffff0000, v55
	global_load_dwordx2 v[54:55], v2, s[12:13]
	s_add_u32 s12, s12, 0x2000
	s_addc_u32 s13, s13, 0
	v_pk_mul_f32 v[8:9], v[8:9], v[12:13]
	v_pk_fma_f32 v[10:11], v[10:11], v[12:13], v[14:15]
	s_waitcnt vmcnt(30)
	v_lshlrev_b32_e32 v16, 16, v56
	v_lshlrev_b32_e32 v17, 16, v57
	v_exp_f32_e32 v16, v16
	v_exp_f32_e32 v17, v17
	v_and_b32_e32 v4, 0xffff0000, v56
	v_and_b32_e32 v5, 0xffff0000, v57
	global_load_dwordx2 v[56:57], v2, s[12:13]
	s_add_u32 s12, s12, 0x2000
	s_addc_u32 s13, s13, 0
	v_pk_mul_f32 v[8:9], v[8:9], v[16:17]
	v_pk_fma_f32 v[10:11], v[10:11], v[16:17], v[4:5]
	s_waitcnt vmcnt(30)
; __device__ __forceinline__ float bf_lo(unsigned w) { return __uint_as_float(w << 16); }
; __device__ __forceinline__ float bf_hi(unsigned w) { return __uint_as_float(w & 0xffff0000u); }
; __global__ void __launch_bounds__(NTHR, 2) hybrid_block_fwd(Args a) {
;     ...
;         for (int i = 0; i < CH_L; ++i) { const u32x2 q = pab[(size_t)i * (LW / 2)];
;             const f32x2 av = (f32x2){__builtin_amdgcn_exp2f(bf_lo(q.x)), __builtin_amdgcn_exp2f(bf_lo(q.y))}, bv = (f32x2){bf_hi(q.x), bf_hi(q.y)}; P = P * av; H = av * H + bv; }
	v_lshlrev_b32_e32 v12, 16, v58
	v_lshlrev_b32_e32 v13, 16, v59
	v_exp_f32_e32 v12, v12
	v_exp_f32_e32 v13, v13
	v_and_b32_e32 v14, 0xffff0000, v58
	v_and_b32_e32 v15, 0xffff0000, v59
	global_load_dwordx2 v[58:59], v2, s[12:13]
	s_add_u32 s12, s12, 0x2000
	s_addc_u32 s13, s13, 0
	v_pk_mul_f32 v[8:9], v[8:9], v[12:13]
	v_pk_fma_f32 v[10:11], v[10:11], v[12:13], v[14:15]
	s_waitcnt vmcnt(30)
	v_lshlrev_b32_e32 v16, 16, v60
	v_lshlrev_b32_e32 v17, 16, v61
	v_exp_f32_e32 v16, v16
	v_exp_f32_e32 v17, v17
	v_and_b32_e32 v4, 0xffff0000, v60
	v_and_b32_e32 v5, 0xffff0000, v61
	global_load_dwordx2 v[60:61], v2, s[12:13]
	s_add_u32 s12, s12, 0x2000
	s_addc_u32 s13, s13, 0
	v_pk_mul_f32 v[8:9], v[8:9], v[16:17]
	v_pk_fma_f32 v[10:11], v[10:11], v[16:17], v[4:5]
	s_waitcnt vmcnt(30)
	v_lshlrev_b32_e32 v12, 16, v62
	v_lshlrev_b32_e32 v13, 16, v63
	v_exp_f32_e32 v12, v12
	v_exp_f32_e32 v13, v13
	v_and_b32_e32 v14, 0xffff0000, v62
	v_and_b32_e32 v15, 0xffff0000, v63
	global_load_dwordx2 v[62:63], v2, s[12:13]
	s_add_u32 s12, s12, 0x2000
	s_addc_u32 s13, s13, 0
	v_pk_mul_f32 v[8:9], v[8:9], v[12:13]
	v_pk_fma_f32 v[10:11], v[10:11], v[12:13], v[14:15]
	s_waitcnt vmcnt(30)
	v_lshlrev_b32_e32 v16, 16, v216
	v_lshlrev_b32_e32 v17, 16, v217
	v_exp_f32_e32 v16, v16
	v_exp_f32_e32 v17, v17
	v_and_b32_e32 v4, 0xffff0000, v216
	v_and_b32_e32 v5, 0xffff0000, v217
	global_load_dwordx2 v[216:217], v2, s[12:13]
	s_add_u32 s12, s12, 0x2000
	s_addc_u32 s13, s13, 0
	v_pk_mul_f32 v[8:9], v[8:9], v[16:17]
	v_pk_fma_f32 v[10:11], v[10:11], v[16:17], v[4:5]
	s_waitcnt vmcnt(30)
	v_lshlrev_b32_e32 v12, 16, v218
	v_lshlrev_b32_e32 v13, 16, v219
	v_exp_f32_e32 v12, v12
	v_exp_f32_e32 v13, v13
	v_and_b32_e32 v14, 0xffff0000, v218
	v_and_b32_e32 v15, 0xffff0000, v219
	global_load_dwordx2 v[218:219], v2, s[12:13]
	s_add_u32 s12, s12, 0x2000
	s_addc_u32 s13, s13, 0
	v_pk_mul_f32 v[8:9], v[8:9], v[12:13]
	v_pk_fma_f32 v[10:11], v[10:11], v[12:13], v[14:15]
	s_waitcnt vmcnt(30)
	v_lshlrev_b32_e32 v16, 16, v220
	v_lshlrev_b32_e32 v17, 16, v221
	v_exp_f32_e32 v16, v16
	v_exp_f32_e32 v17, v17
	v_and_b32_e32 v4, 0xffff0000, v220
	v_and_b32_e32 v5, 0xffff0000, v221
	global_load_dwordx2 v[64:65], v2, s[12:13]
	s_add_u32 s12, s12, 0x2000
	s_addc_u32 s13, s13, 0
	v_pk_mul_f32 v[8:9], v[8:9], v[16:17]
	v_pk_fma_f32 v[10:11], v[10:11], v[16:17], v[4:5]
	s_waitcnt vmcnt(30)
	v_lshlrev_b32_e32 v12, 16, v222
	v_lshlrev_b32_e32 v13, 16, v223
	v_exp_f32_e32 v12, v12
	v_exp_f32_e32 v13, v13
	v_and_b32_e32 v14, 0xffff0000, v222
	v_and_b32_e32 v15, 0xffff0000, v223
	global_load_dwordx2 v[66:67], v2, s[12:13]
	s_add_u32 s12, s12, 0x2000
	s_addc_u32 s13, s13, 0
	v_pk_mul_f32 v[8:9], v[8:9], v[12:13]
	v_pk_fma_f32 v[10:11], v[10:11], v[12:13], v[14:15]
	s_waitcnt vmcnt(30)
	v_lshlrev_b32_e32 v16, 16, v224
	v_lshlrev_b32_e32 v17, 16, v225
	v_exp_f32_e32 v16, v16
	v_exp_f32_e32 v17, v17
	v_and_b32_e32 v4, 0xffff0000, v224
	v_and_b32_e32 v5, 0xffff0000, v225
	global_load_dwordx2 v[68:69], v2, s[12:13]
	s_add_u32 s12, s12, 0x2000
	s_addc_u32 s13, s13, 0
	v_pk_mul_f32 v[8:9], v[8:9], v[16:17]
	v_pk_fma_f32 v[10:11], v[10:11], v[16:17], v[4:5]
	s_waitcnt vmcnt(30)
	v_lshlrev_b32_e32 v12, 16, v226
	v_lshlrev_b32_e32 v13, 16, v227
	v_exp_f32_e32 v12, v12
	v_exp_f32_e32 v13, v13
	v_and_b32_e32 v14, 0xffff0000, v226
	v_and_b32_e32 v15, 0xffff0000, v227
	global_load_dwordx2 v[70:71], v2, s[12:13]
	s_add_u32 s12, s12, 0x2000
	s_addc_u32 s13, s13, 0
	v_pk_mul_f32 v[8:9], v[8:9], v[12:13]
	v_pk_fma_f32 v[10:11], v[10:11], v[12:13], v[14:15]
	s_waitcnt vmcnt(30)
	v_lshlrev_b32_e32 v16, 16, v228
	v_lshlrev_b32_e32 v17, 16, v229
	v_exp_f32_e32 v16, v16
	v_exp_f32_e32 v17, v17
	v_and_b32_e32 v4, 0xffff0000, v228
	v_and_b32_e32 v5, 0xffff0000, v229
	global_load_dwordx2 v[72:73], v2, s[12:13]
	s_add_u32 s12, s12, 0x2000
	s_addc_u32 s13, s13, 0
	v_pk_mul_f32 v[8:9], v[8:9], v[16:17]
	v_pk_fma_f32 v[10:11], v[10:11], v[16:17], v[4:5]
	s_waitcnt vmcnt(30)
	v_lshlrev_b32_e32 v12, 16, v230
	v_lshlrev_b32_e32 v13, 16, v231
	v_exp_f32_e32 v12, v12
	v_exp_f32_e32 v13, v13
	v_and_b32_e32 v14, 0xffff0000, v230
	v_and_b32_e32 v15, 0xffff0000, v231
	global_load_dwordx2 v[74:75], v2, s[12:13]
	s_add_u32 s12, s12, 0x2000
	s_addc_u32 s13, s13, 0
	v_pk_mul_f32 v[8:9], v[8:9], v[12:13]
	v_pk_fma_f32 v[10:11], v[10:11], v[12:13], v[14:15]
	s_waitcnt vmcnt(30)
	v_lshlrev_b32_e32 v16, 16, v18
	v_lshlrev_b32_e32 v17, 16, v19
	v_exp_f32_e32 v16, v16
	v_exp_f32_e32 v17, v17
	v_and_b32_e32 v4, 0xffff0000, v18
	v_and_b32_e32 v5, 0xffff0000, v19
	global_load_dwordx2 v[76:77], v2, s[12:13]
	s_add_u32 s12, s12, 0x2000
	s_addc_u32 s13, s13, 0
	v_pk_mul_f32 v[8:9], v[8:9], v[16:17]
	v_pk_fma_f32 v[10:11], v[10:11], v[16:17], v[4:5]
	s_waitcnt vmcnt(30)
	v_lshlrev_b32_e32 v12, 16, v20
	v_lshlrev_b32_e32 v13, 16, v21
	v_exp_f32_e32 v12, v12
	v_exp_f32_e32 v13, v13
	v_and_b32_e32 v14, 0xffff0000, v20
	v_and_b32_e32 v15, 0xffff0000, v21
	global_load_dwordx2 v[78:79], v2, s[12:13]
	s_add_u32 s12, s12, 0x2000
	s_addc_u32 s13, s13, 0
	v_pk_mul_f32 v[8:9], v[8:9], v[12:13]
	v_pk_fma_f32 v[10:11], v[10:11], v[12:13], v[14:15]
	s_waitcnt vmcnt(30)
	v_lshlrev_b32_e32 v16, 16, v22
	v_lshlrev_b32_e32 v17, 16, v23
	v_exp_f32_e32 v16, v16
	v_exp_f32_e32 v17, v17
	v_and_b32_e32 v4, 0xffff0000, v22
	v_and_b32_e32 v5, 0xffff0000, v23
	global_load_dwordx2 v[80:81], v2, s[12:13]
	s_add_u32 s12, s12, 0x2000
	s_addc_u32 s13, s13, 0
	v_pk_mul_f32 v[8:9], v[8:9], v[16:17]
	v_pk_fma_f32 v[10:11], v[10:11], v[16:17], v[4:5]
	s_waitcnt vmcnt(30)
; __device__ __forceinline__ float bf_lo(unsigned w) { return __uint_as_float(w << 16); }
; __device__ __forceinline__ float bf_hi(unsigned w) { return __uint_as_float(w & 0xffff0000u); }
; __global__ void __launch_bounds__(NTHR, 2) hybrid_block_fwd(Args a) {
;     ...
;         for (int i = 0; i < CH_L; ++i) { const u32x2 q = pab[(size_t)i * (LW / 2)];
;             const f32x2 av = (f32x2){__builtin_amdgcn_exp2f(bf_lo(q.x)), __builtin_amdgcn_exp2f(bf_lo(q.y))}, bv = (f32x2){bf_hi(q.x), bf_hi(q.y)}; P = P * av; H = av * H + bv; }
	v_lshlrev_b32_e32 v12, 16, v24
	v_lshlrev_b32_e32 v13, 16, v25
	v_exp_f32_e32 v12, v12
	v_exp_f32_e32 v13, v13
	v_and_b32_e32 v14, 0xffff0000, v24
	v_and_b32_e32 v15, 0xffff0000, v25
	global_load_dwordx2 v[82:83], v2, s[12:13]
	s_add_u32 s12, s12, 0x2000
	s_addc_u32 s13, s13, 0
	v_pk_mul_f32 v[8:9], v[8:9], v[12:13]
	v_pk_fma_f32 v[10:11], v[10:11], v[12:13], v[14:15]
	s_waitcnt vmcnt(30)
	v_lshlrev_b32_e32 v16, 16, v26
	v_lshlrev_b32_e32 v17, 16, v27
	v_exp_f32_e32 v16, v16
	v_exp_f32_e32 v17, v17
	v_and_b32_e32 v4, 0xffff0000, v26
	v_and_b32_e32 v5, 0xffff0000, v27
	global_load_dwordx2 v[84:85], v2, s[12:13]
	s_add_u32 s12, s12, 0x2000
	s_addc_u32 s13, s13, 0
	v_pk_mul_f32 v[8:9], v[8:9], v[16:17]
	v_pk_fma_f32 v[10:11], v[10:11], v[16:17], v[4:5]
	s_waitcnt vmcnt(30)
	v_lshlrev_b32_e32 v12, 16, v28
	v_lshlrev_b32_e32 v13, 16, v29
	v_exp_f32_e32 v12, v12
	v_exp_f32_e32 v13, v13
	v_and_b32_e32 v14, 0xffff0000, v28
	v_and_b32_e32 v15, 0xffff0000, v29
	global_load_dwordx2 v[86:87], v2, s[12:13]
	s_add_u32 s12, s12, 0x2000
	s_addc_u32 s13, s13, 0
	v_pk_mul_f32 v[8:9], v[8:9], v[12:13]
	v_pk_fma_f32 v[10:11], v[10:11], v[12:13], v[14:15]
	s_waitcnt vmcnt(30)
	v_lshlrev_b32_e32 v16, 16, v30
	v_lshlrev_b32_e32 v17, 16, v31
	v_exp_f32_e32 v16, v16
	v_exp_f32_e32 v17, v17
	v_and_b32_e32 v4, 0xffff0000, v30
	v_and_b32_e32 v5, 0xffff0000, v31
	global_load_dwordx2 v[88:89], v2, s[12:13]
	s_add_u32 s12, s12, 0x2000
	s_addc_u32 s13, s13, 0
	v_pk_mul_f32 v[8:9], v[8:9], v[16:17]
	v_pk_fma_f32 v[10:11], v[10:11], v[16:17], v[4:5]
	s_waitcnt vmcnt(30)
	v_lshlrev_b32_e32 v12, 16, v32
	v_lshlrev_b32_e32 v13, 16, v33
	v_exp_f32_e32 v12, v12
	v_exp_f32_e32 v13, v13
	v_and_b32_e32 v14, 0xffff0000, v32
	v_and_b32_e32 v15, 0xffff0000, v33
	global_load_dwordx2 v[90:91], v2, s[12:13]
	s_add_u32 s12, s12, 0x2000
	s_addc_u32 s13, s13, 0
	v_pk_mul_f32 v[8:9], v[8:9], v[12:13]
	v_pk_fma_f32 v[10:11], v[10:11], v[12:13], v[14:15]
	s_waitcnt vmcnt(30)
	v_lshlrev_b32_e32 v16, 16, v34
	v_lshlrev_b32_e32 v17, 16, v35
	v_exp_f32_e32 v16, v16
	v_exp_f32_e32 v17, v17
	v_and_b32_e32 v4, 0xffff0000, v34
	v_and_b32_e32 v5, 0xffff0000, v35
	global_load_dwordx2 v[92:93], v2, s[12:13]
	s_add_u32 s12, s12, 0x2000
	s_addc_u32 s13, s13, 0
	v_pk_mul_f32 v[8:9], v[8:9], v[16:17]
	v_pk_fma_f32 v[10:11], v[10:11], v[16:17], v[4:5]
	s_waitcnt vmcnt(30)
	v_lshlrev_b32_e32 v12, 16, v36
	v_lshlrev_b32_e32 v13, 16, v37
	v_exp_f32_e32 v12, v12
	v_exp_f32_e32 v13, v13
	v_and_b32_e32 v14, 0xffff0000, v36
	v_and_b32_e32 v15, 0xffff0000, v37
	global_load_dwordx2 v[94:95], v2, s[12:13]
	s_add_u32 s12, s12, 0x2000
	s_addc_u32 s13, s13, 0
	v_pk_mul_f32 v[8:9], v[8:9], v[12:13]
	v_pk_fma_f32 v[10:11], v[10:11], v[12:13], v[14:15]
	s_waitcnt vmcnt(30)
	v_lshlrev_b32_e32 v16, 16, v38
	v_lshlrev_b32_e32 v17, 16, v39
	v_exp_f32_e32 v16, v16
	v_exp_f32_e32 v17, v17
	v_and_b32_e32 v4, 0xffff0000, v38
	v_and_b32_e32 v5, 0xffff0000, v39
	global_load_dwordx2 v[96:97], v2, s[12:13]
	s_add_u32 s12, s12, 0x2000
	s_addc_u32 s13, s13, 0
	v_pk_mul_f32 v[8:9], v[8:9], v[16:17]
	v_pk_fma_f32 v[10:11], v[10:11], v[16:17], v[4:5]
	s_waitcnt vmcnt(30)
	v_lshlrev_b32_e32 v12, 16, v40
	v_lshlrev_b32_e32 v13, 16, v41
	v_exp_f32_e32 v12, v12
	v_exp_f32_e32 v13, v13
	v_and_b32_e32 v14, 0xffff0000, v40
	v_and_b32_e32 v15, 0xffff0000, v41
	global_load_dwordx2 v[98:99], v2, s[12:13]
	s_add_u32 s12, s12, 0x2000
	s_addc_u32 s13, s13, 0
	v_pk_mul_f32 v[8:9], v[8:9], v[12:13]
	v_pk_fma_f32 v[10:11], v[10:11], v[12:13], v[14:15]
	s_waitcnt vmcnt(30)
	v_lshlrev_b32_e32 v16, 16, v42
	v_lshlrev_b32_e32 v17, 16, v43
	v_exp_f32_e32 v16, v16
	v_exp_f32_e32 v17, v17
	v_and_b32_e32 v4, 0xffff0000, v42
	v_and_b32_e32 v5, 0xffff0000, v43
	global_load_dwordx2 v[100:101], v2, s[12:13]
	s_add_u32 s12, s12, 0x2000
	s_addc_u32 s13, s13, 0
	v_pk_mul_f32 v[8:9], v[8:9], v[16:17]
	v_pk_fma_f32 v[10:11], v[10:11], v[16:17], v[4:5]
	s_waitcnt vmcnt(30)
	v_lshlrev_b32_e32 v12, 16, v44
	v_lshlrev_b32_e32 v13, 16, v45
	v_exp_f32_e32 v12, v12
	v_exp_f32_e32 v13, v13
	v_and_b32_e32 v14, 0xffff0000, v44
	v_and_b32_e32 v15, 0xffff0000, v45
	global_load_dwordx2 v[102:103], v2, s[12:13]
	s_add_u32 s12, s12, 0x2000
	s_addc_u32 s13, s13, 0
	v_pk_mul_f32 v[8:9], v[8:9], v[12:13]
	v_pk_fma_f32 v[10:11], v[10:11], v[12:13], v[14:15]
	s_waitcnt vmcnt(30)
	v_lshlrev_b32_e32 v16, 16, v46
	v_lshlrev_b32_e32 v17, 16, v47
	v_exp_f32_e32 v16, v16
	v_exp_f32_e32 v17, v17
	v_and_b32_e32 v4, 0xffff0000, v46
	v_and_b32_e32 v5, 0xffff0000, v47
	global_load_dwordx2 v[104:105], v2, s[12:13]
	s_add_u32 s12, s12, 0x2000
	s_addc_u32 s13, s13, 0
	v_pk_mul_f32 v[8:9], v[8:9], v[16:17]
	v_pk_fma_f32 v[10:11], v[10:11], v[16:17], v[4:5]
	s_waitcnt vmcnt(30)
	v_lshlrev_b32_e32 v12, 16, v48
	v_lshlrev_b32_e32 v13, 16, v49
	v_exp_f32_e32 v12, v12
	v_exp_f32_e32 v13, v13
	v_and_b32_e32 v14, 0xffff0000, v48
	v_and_b32_e32 v15, 0xffff0000, v49
	global_load_dwordx2 v[106:107], v2, s[12:13]
	s_add_u32 s12, s12, 0x2000
	s_addc_u32 s13, s13, 0
	v_pk_mul_f32 v[8:9], v[8:9], v[12:13]
	v_pk_fma_f32 v[10:11], v[10:11], v[12:13], v[14:15]
	s_waitcnt vmcnt(30)
	v_lshlrev_b32_e32 v16, 16, v50
	v_lshlrev_b32_e32 v17, 16, v51
	v_exp_f32_e32 v16, v16
	v_exp_f32_e32 v17, v17
	v_and_b32_e32 v4, 0xffff0000, v50
	v_and_b32_e32 v5, 0xffff0000, v51
	global_load_dwordx2 v[108:109], v2, s[12:13]
	s_add_u32 s12, s12, 0x2000
	s_addc_u32 s13, s13, 0
	v_pk_mul_f32 v[8:9], v[8:9], v[16:17]
	v_pk_fma_f32 v[10:11], v[10:11], v[16:17], v[4:5]
	s_waitcnt vmcnt(30)
; __device__ __forceinline__ float bf_lo(unsigned w) { return __uint_as_float(w << 16); }
; __device__ __forceinline__ float bf_hi(unsigned w) { return __uint_as_float(w & 0xffff0000u); }
; __global__ void __launch_bounds__(NTHR, 2) hybrid_block_fwd(Args a) {
;     ...
;         for (int i = 0; i < CH_L; ++i) { const u32x2 q = pab[(size_t)i * (LW / 2)];
;             const f32x2 av = (f32x2){__builtin_amdgcn_exp2f(bf_lo(q.x)), __builtin_amdgcn_exp2f(bf_lo(q.y))}, bv = (f32x2){bf_hi(q.x), bf_hi(q.y)}; P = P * av; H = av * H + bv; }
	v_lshlrev_b32_e32 v12, 16, v52
	v_lshlrev_b32_e32 v13, 16, v53
	v_exp_f32_e32 v12, v12
	v_exp_f32_e32 v13, v13
	v_and_b32_e32 v14, 0xffff0000, v52
	v_and_b32_e32 v15, 0xffff0000, v53
	global_load_dwordx2 v[110:111], v2, s[12:13]
	s_add_u32 s12, s12, 0x2000
	s_addc_u32 s13, s13, 0
	v_pk_mul_f32 v[8:9], v[8:9], v[12:13]
	v_pk_fma_f32 v[10:11], v[10:11], v[12:13], v[14:15]
	s_waitcnt vmcnt(30)
	v_lshlrev_b32_e32 v16, 16, v54
	v_lshlrev_b32_e32 v17, 16, v55
	v_exp_f32_e32 v16, v16
	v_exp_f32_e32 v17, v17
	v_and_b32_e32 v4, 0xffff0000, v54
	v_and_b32_e32 v5, 0xffff0000, v55
	global_load_dwordx2 v[112:113], v2, s[12:13]
	s_add_u32 s12, s12, 0x2000
	s_addc_u32 s13, s13, 0
	v_pk_mul_f32 v[8:9], v[8:9], v[16:17]
	v_pk_fma_f32 v[10:11], v[10:11], v[16:17], v[4:5]
	s_waitcnt vmcnt(30)
	v_lshlrev_b32_e32 v12, 16, v56
	v_lshlrev_b32_e32 v13, 16, v57
	v_exp_f32_e32 v12, v12
	v_exp_f32_e32 v13, v13
	v_and_b32_e32 v14, 0xffff0000, v56
	v_and_b32_e32 v15, 0xffff0000, v57
	global_load_dwordx2 v[114:115], v2, s[12:13]
	s_add_u32 s12, s12, 0x2000
	s_addc_u32 s13, s13, 0
	v_pk_mul_f32 v[8:9], v[8:9], v[12:13]
	v_pk_fma_f32 v[10:11], v[10:11], v[12:13], v[14:15]
	s_waitcnt vmcnt(30)
	v_lshlrev_b32_e32 v16, 16, v58
	v_lshlrev_b32_e32 v17, 16, v59
	v_exp_f32_e32 v16, v16
	v_exp_f32_e32 v17, v17
	v_and_b32_e32 v4, 0xffff0000, v58
	v_and_b32_e32 v5, 0xffff0000, v59
	global_load_dwordx2 v[116:117], v2, s[12:13]
	s_add_u32 s12, s12, 0x2000
	s_addc_u32 s13, s13, 0
	v_pk_mul_f32 v[8:9], v[8:9], v[16:17]
	v_pk_fma_f32 v[10:11], v[10:11], v[16:17], v[4:5]
	s_waitcnt vmcnt(30)
	v_lshlrev_b32_e32 v12, 16, v60
	v_lshlrev_b32_e32 v13, 16, v61
	v_exp_f32_e32 v12, v12
	v_exp_f32_e32 v13, v13
	v_and_b32_e32 v14, 0xffff0000, v60
	v_and_b32_e32 v15, 0xffff0000, v61
	global_load_dwordx2 v[118:119], v2, s[12:13]
	s_add_u32 s12, s12, 0x2000
	s_addc_u32 s13, s13, 0
	v_pk_mul_f32 v[8:9], v[8:9], v[12:13]
	v_pk_fma_f32 v[10:11], v[10:11], v[12:13], v[14:15]
	s_waitcnt vmcnt(30)
	v_lshlrev_b32_e32 v16, 16, v62
	v_lshlrev_b32_e32 v17, 16, v63
	v_exp_f32_e32 v16, v16
	v_exp_f32_e32 v17, v17
	v_and_b32_e32 v4, 0xffff0000, v62
	v_and_b32_e32 v5, 0xffff0000, v63
	global_load_dwordx2 v[120:121], v2, s[12:13]
	s_add_u32 s12, s12, 0x2000
	s_addc_u32 s13, s13, 0
	v_pk_mul_f32 v[8:9], v[8:9], v[16:17]
	v_pk_fma_f32 v[10:11], v[10:11], v[16:17], v[4:5]
	s_waitcnt vmcnt(30)
	v_lshlrev_b32_e32 v12, 16, v216
	v_lshlrev_b32_e32 v13, 16, v217
	v_exp_f32_e32 v12, v12
	v_exp_f32_e32 v13, v13
	v_and_b32_e32 v14, 0xffff0000, v216
	v_and_b32_e32 v15, 0xffff0000, v217
	global_load_dwordx2 v[122:123], v2, s[12:13]
	s_add_u32 s12, s12, 0x2000
	s_addc_u32 s13, s13, 0
	v_pk_mul_f32 v[8:9], v[8:9], v[12:13]
	v_pk_fma_f32 v[10:11], v[10:11], v[12:13], v[14:15]
	s_waitcnt vmcnt(30)
	v_lshlrev_b32_e32 v16, 16, v218
	v_lshlrev_b32_e32 v17, 16, v219
	v_exp_f32_e32 v16, v16
	v_exp_f32_e32 v17, v17
	v_and_b32_e32 v4, 0xffff0000, v218
	v_and_b32_e32 v5, 0xffff0000, v219
	global_load_dwordx2 v[124:125], v2, s[12:13]
	s_add_u32 s12, s12, 0x2000
	s_addc_u32 s13, s13, 0
	v_pk_mul_f32 v[8:9], v[8:9], v[16:17]
	v_pk_fma_f32 v[10:11], v[10:11], v[16:17], v[4:5]
	s_waitcnt vmcnt(30)
	v_lshlrev_b32_e32 v12, 16, v64
	v_lshlrev_b32_e32 v13, 16, v65
	v_exp_f32_e32 v12, v12
	v_exp_f32_e32 v13, v13
	v_and_b32_e32 v14, 0xffff0000, v64
	v_and_b32_e32 v15, 0xffff0000, v65
	global_load_dwordx2 v[126:127], v2, s[12:13]
	s_add_u32 s12, s12, 0x2000
	s_addc_u32 s13, s13, 0
	v_pk_mul_f32 v[8:9], v[8:9], v[12:13]
	v_pk_fma_f32 v[10:11], v[10:11], v[12:13], v[14:15]
	s_waitcnt vmcnt(30)
	v_lshlrev_b32_e32 v16, 16, v66
	v_lshlrev_b32_e32 v17, 16, v67
	v_exp_f32_e32 v16, v16
	v_exp_f32_e32 v17, v17
	v_and_b32_e32 v4, 0xffff0000, v66
	v_and_b32_e32 v5, 0xffff0000, v67
	global_load_dwordx2 v[128:129], v2, s[12:13]
	s_add_u32 s12, s12, 0x2000
	s_addc_u32 s13, s13, 0
	v_pk_mul_f32 v[8:9], v[8:9], v[16:17]
	v_pk_fma_f32 v[10:11], v[10:11], v[16:17], v[4:5]
	s_waitcnt vmcnt(30)
	v_lshlrev_b32_e32 v12, 16, v68
	v_lshlrev_b32_e32 v13, 16, v69
	v_exp_f32_e32 v12, v12
	v_exp_f32_e32 v13, v13
	v_and_b32_e32 v14, 0xffff0000, v68
	v_and_b32_e32 v15, 0xffff0000, v69
	global_load_dwordx2 v[130:131], v2, s[12:13]
	s_add_u32 s12, s12, 0x2000
	s_addc_u32 s13, s13, 0
	v_pk_mul_f32 v[8:9], v[8:9], v[12:13]
	v_pk_fma_f32 v[10:11], v[10:11], v[12:13], v[14:15]
	s_waitcnt vmcnt(30)
	v_lshlrev_b32_e32 v16, 16, v70
	v_lshlrev_b32_e32 v17, 16, v71
	v_exp_f32_e32 v16, v16
	v_exp_f32_e32 v17, v17
	v_and_b32_e32 v4, 0xffff0000, v70
	v_and_b32_e32 v5, 0xffff0000, v71
	global_load_dwordx2 v[132:133], v2, s[12:13]
	s_add_u32 s12, s12, 0x2000
	s_addc_u32 s13, s13, 0
	v_pk_mul_f32 v[8:9], v[8:9], v[16:17]
	v_pk_fma_f32 v[10:11], v[10:11], v[16:17], v[4:5]
	s_waitcnt vmcnt(30)
	v_lshlrev_b32_e32 v12, 16, v72
	v_lshlrev_b32_e32 v13, 16, v73
	v_exp_f32_e32 v12, v12
	v_exp_f32_e32 v13, v13
	v_and_b32_e32 v14, 0xffff0000, v72
	v_and_b32_e32 v15, 0xffff0000, v73
	global_load_dwordx2 v[134:135], v2, s[12:13]
	s_add_u32 s12, s12, 0x2000
	s_addc_u32 s13, s13, 0
	v_pk_mul_f32 v[8:9], v[8:9], v[12:13]
	v_pk_fma_f32 v[10:11], v[10:11], v[12:13], v[14:15]
	s_waitcnt vmcnt(30)
	v_lshlrev_b32_e32 v16, 16, v74
	v_lshlrev_b32_e32 v17, 16, v75
	v_exp_f32_e32 v16, v16
	v_exp_f32_e32 v17, v17
	v_and_b32_e32 v4, 0xffff0000, v74
	v_and_b32_e32 v5, 0xffff0000, v75
	global_load_dwordx2 v[136:137], v2, s[12:13]
	s_add_u32 s12, s12, 0x2000
	s_addc_u32 s13, s13, 0
	v_pk_mul_f32 v[8:9], v[8:9], v[16:17]
	v_pk_fma_f32 v[10:11], v[10:11], v[16:17], v[4:5]
	s_waitcnt vmcnt(30)
; __device__ __forceinline__ float bf_lo(unsigned w) { return __uint_as_float(w << 16); }
; __device__ __forceinline__ float bf_hi(unsigned w) { return __uint_as_float(w & 0xffff0000u); }
; __global__ void __launch_bounds__(NTHR, 2) hybrid_block_fwd(Args a) {
;     ...
;         for (int i = 0; i < CH_L; ++i) { const u32x2 q = pab[(size_t)i * (LW / 2)];
;             const f32x2 av = (f32x2){__builtin_amdgcn_exp2f(bf_lo(q.x)), __builtin_amdgcn_exp2f(bf_lo(q.y))}, bv = (f32x2){bf_hi(q.x), bf_hi(q.y)}; P = P * av; H = av * H + bv; }
	v_lshlrev_b32_e32 v12, 16, v76
	v_lshlrev_b32_e32 v13, 16, v77
	v_exp_f32_e32 v12, v12
	v_exp_f32_e32 v13, v13
	v_and_b32_e32 v14, 0xffff0000, v76
	v_and_b32_e32 v15, 0xffff0000, v77
	global_load_dwordx2 v[138:139], v2, s[12:13]
	s_add_u32 s12, s12, 0x2000
	s_addc_u32 s13, s13, 0
	v_pk_mul_f32 v[8:9], v[8:9], v[12:13]
	v_pk_fma_f32 v[10:11], v[10:11], v[12:13], v[14:15]
	s_waitcnt vmcnt(30)
	v_lshlrev_b32_e32 v16, 16, v78
	v_lshlrev_b32_e32 v17, 16, v79
	v_exp_f32_e32 v16, v16
	v_exp_f32_e32 v17, v17
	v_and_b32_e32 v4, 0xffff0000, v78
	v_and_b32_e32 v5, 0xffff0000, v79
	global_load_dwordx2 v[140:141], v2, s[12:13]
	s_add_u32 s12, s12, 0x2000
	s_addc_u32 s13, s13, 0
	v_pk_mul_f32 v[8:9], v[8:9], v[16:17]
	v_pk_fma_f32 v[10:11], v[10:11], v[16:17], v[4:5]
	s_waitcnt vmcnt(30)
	v_lshlrev_b32_e32 v12, 16, v80
	v_lshlrev_b32_e32 v13, 16, v81
	v_exp_f32_e32 v12, v12
	v_exp_f32_e32 v13, v13
	v_and_b32_e32 v14, 0xffff0000, v80
	v_and_b32_e32 v15, 0xffff0000, v81
	global_load_dwordx2 v[142:143], v2, s[12:13]
	s_add_u32 s12, s12, 0x2000
	s_addc_u32 s13, s13, 0
	v_pk_mul_f32 v[8:9], v[8:9], v[12:13]
	v_pk_fma_f32 v[10:11], v[10:11], v[12:13], v[14:15]
	s_waitcnt vmcnt(30)
	v_lshlrev_b32_e32 v16, 16, v82
	v_lshlrev_b32_e32 v17, 16, v83
	v_exp_f32_e32 v16, v16
	v_exp_f32_e32 v17, v17
	v_and_b32_e32 v4, 0xffff0000, v82
	v_and_b32_e32 v5, 0xffff0000, v83
	global_load_dwordx2 v[144:145], v2, s[12:13]
	s_add_u32 s12, s12, 0x2000
	s_addc_u32 s13, s13, 0
	v_pk_mul_f32 v[8:9], v[8:9], v[16:17]
	v_pk_fma_f32 v[10:11], v[10:11], v[16:17], v[4:5]
	s_waitcnt vmcnt(30)
	v_lshlrev_b32_e32 v12, 16, v84
	v_lshlrev_b32_e32 v13, 16, v85
	v_exp_f32_e32 v12, v12
	v_exp_f32_e32 v13, v13
	v_and_b32_e32 v14, 0xffff0000, v84
	v_and_b32_e32 v15, 0xffff0000, v85
	global_load_dwordx2 v[146:147], v2, s[12:13]
	s_add_u32 s12, s12, 0x2000
	s_addc_u32 s13, s13, 0
	v_pk_mul_f32 v[8:9], v[8:9], v[12:13]
	v_pk_fma_f32 v[10:11], v[10:11], v[12:13], v[14:15]
	s_waitcnt vmcnt(30)
	v_lshlrev_b32_e32 v16, 16, v86
	v_lshlrev_b32_e32 v17, 16, v87
	v_exp_f32_e32 v16, v16
	v_exp_f32_e32 v17, v17
	v_and_b32_e32 v4, 0xffff0000, v86
	v_and_b32_e32 v5, 0xffff0000, v87
	global_load_dwordx2 v[148:149], v2, s[12:13]
	s_add_u32 s12, s12, 0x2000
	s_addc_u32 s13, s13, 0
	v_pk_mul_f32 v[8:9], v[8:9], v[16:17]
	v_pk_fma_f32 v[10:11], v[10:11], v[16:17], v[4:5]
	s_waitcnt vmcnt(30)
	v_lshlrev_b32_e32 v12, 16, v88
	v_lshlrev_b32_e32 v13, 16, v89
	v_exp_f32_e32 v12, v12
	v_exp_f32_e32 v13, v13
	v_and_b32_e32 v14, 0xffff0000, v88
	v_and_b32_e32 v15, 0xffff0000, v89
	global_load_dwordx2 v[150:151], v2, s[12:13]
	s_add_u32 s12, s12, 0x2000
	s_addc_u32 s13, s13, 0
	v_pk_mul_f32 v[8:9], v[8:9], v[12:13]
	v_pk_fma_f32 v[10:11], v[10:11], v[12:13], v[14:15]
	s_waitcnt vmcnt(30)
	v_lshlrev_b32_e32 v16, 16, v90
	v_lshlrev_b32_e32 v17, 16, v91
	v_exp_f32_e32 v16, v16
	v_exp_f32_e32 v17, v17
	v_and_b32_e32 v4, 0xffff0000, v90
	v_and_b32_e32 v5, 0xffff0000, v91
	global_load_dwordx2 v[152:153], v2, s[12:13]
	s_add_u32 s12, s12, 0x2000
	s_addc_u32 s13, s13, 0
	v_pk_mul_f32 v[8:9], v[8:9], v[16:17]
	v_pk_fma_f32 v[10:11], v[10:11], v[16:17], v[4:5]
	s_waitcnt vmcnt(30)
	v_lshlrev_b32_e32 v12, 16, v92
	v_lshlrev_b32_e32 v13, 16, v93
	v_exp_f32_e32 v12, v12
	v_exp_f32_e32 v13, v13
	v_and_b32_e32 v14, 0xffff0000, v92
	v_and_b32_e32 v15, 0xffff0000, v93
	global_load_dwordx2 v[154:155], v2, s[12:13]
	s_add_u32 s12, s12, 0x2000
	s_addc_u32 s13, s13, 0
	v_pk_mul_f32 v[8:9], v[8:9], v[12:13]
	v_pk_fma_f32 v[10:11], v[10:11], v[12:13], v[14:15]
	s_waitcnt vmcnt(30)
	v_lshlrev_b32_e32 v16, 16, v94
	v_lshlrev_b32_e32 v17, 16, v95
	v_exp_f32_e32 v16, v16
	v_exp_f32_e32 v17, v17
	v_and_b32_e32 v4, 0xffff0000, v94
	v_and_b32_e32 v5, 0xffff0000, v95
	global_load_dwordx2 v[156:157], v2, s[12:13]
	s_add_u32 s12, s12, 0x2000
	s_addc_u32 s13, s13, 0
	v_pk_mul_f32 v[8:9], v[8:9], v[16:17]
	v_pk_fma_f32 v[10:11], v[10:11], v[16:17], v[4:5]
	s_waitcnt vmcnt(30)
	v_lshlrev_b32_e32 v12, 16, v96
	v_lshlrev_b32_e32 v13, 16, v97
	v_exp_f32_e32 v12, v12
	v_exp_f32_e32 v13, v13
	v_and_b32_e32 v14, 0xffff0000, v96
	v_and_b32_e32 v15, 0xffff0000, v97
	global_load_dwordx2 v[158:159], v2, s[12:13]
	s_add_u32 s12, s12, 0x2000
	s_addc_u32 s13, s13, 0
	v_pk_mul_f32 v[8:9], v[8:9], v[12:13]
	v_pk_fma_f32 v[10:11], v[10:11], v[12:13], v[14:15]
	s_waitcnt vmcnt(30)
	v_lshlrev_b32_e32 v16, 16, v98
	v_lshlrev_b32_e32 v17, 16, v99
	v_exp_f32_e32 v16, v16
	v_exp_f32_e32 v17, v17
	v_and_b32_e32 v4, 0xffff0000, v98
	v_and_b32_e32 v5, 0xffff0000, v99
	global_load_dwordx2 v[160:161], v2, s[12:13]
	s_add_u32 s12, s12, 0x2000
	s_addc_u32 s13, s13, 0
	v_pk_mul_f32 v[8:9], v[8:9], v[16:17]
	v_pk_fma_f32 v[10:11], v[10:11], v[16:17], v[4:5]
	s_waitcnt vmcnt(30)
	v_lshlrev_b32_e32 v12, 16, v100
	v_lshlrev_b32_e32 v13, 16, v101
	v_exp_f32_e32 v12, v12
	v_exp_f32_e32 v13, v13
	v_and_b32_e32 v14, 0xffff0000, v100
	v_and_b32_e32 v15, 0xffff0000, v101
	global_load_dwordx2 v[162:163], v2, s[12:13]
	s_add_u32 s12, s12, 0x2000
	s_addc_u32 s13, s13, 0
	v_pk_mul_f32 v[8:9], v[8:9], v[12:13]
	v_pk_fma_f32 v[10:11], v[10:11], v[12:13], v[14:15]
	s_waitcnt vmcnt(30)
	v_lshlrev_b32_e32 v16, 16, v102
	v_lshlrev_b32_e32 v17, 16, v103
	v_exp_f32_e32 v16, v16
	v_exp_f32_e32 v17, v17
	v_and_b32_e32 v4, 0xffff0000, v102
	v_and_b32_e32 v5, 0xffff0000, v103
	global_load_dwordx2 v[164:165], v2, s[12:13]
	s_add_u32 s12, s12, 0x2000
	s_addc_u32 s13, s13, 0
	v_pk_mul_f32 v[8:9], v[8:9], v[16:17]
	v_pk_fma_f32 v[10:11], v[10:11], v[16:17], v[4:5]
	s_waitcnt vmcnt(30)
; __device__ __forceinline__ float bf_lo(unsigned w) { return __uint_as_float(w << 16); }
; __device__ __forceinline__ float bf_hi(unsigned w) { return __uint_as_float(w & 0xffff0000u); }
; __global__ void __launch_bounds__(NTHR, 2) hybrid_block_fwd(Args a) {
;     ...
;         for (int i = 0; i < CH_L; ++i) { const u32x2 q = pab[(size_t)i * (LW / 2)];
;             const f32x2 av = (f32x2){__builtin_amdgcn_exp2f(bf_lo(q.x)), __builtin_amdgcn_exp2f(bf_lo(q.y))}, bv = (f32x2){bf_hi(q.x), bf_hi(q.y)}; P = P * av; H = av * H + bv; }
	v_lshlrev_b32_e32 v12, 16, v104
	v_lshlrev_b32_e32 v13, 16, v105
	v_exp_f32_e32 v12, v12
	v_exp_f32_e32 v13, v13
	v_and_b32_e32 v14, 0xffff0000, v104
	v_and_b32_e32 v15, 0xffff0000, v105
	global_load_dwordx2 v[166:167], v2, s[12:13]
	s_add_u32 s12, s12, 0x2000
	s_addc_u32 s13, s13, 0
	v_pk_mul_f32 v[8:9], v[8:9], v[12:13]
	v_pk_fma_f32 v[10:11], v[10:11], v[12:13], v[14:15]
	s_waitcnt vmcnt(30)
	v_lshlrev_b32_e32 v16, 16, v106
	v_lshlrev_b32_e32 v17, 16, v107
	v_exp_f32_e32 v16, v16
	v_exp_f32_e32 v17, v17
	v_and_b32_e32 v4, 0xffff0000, v106
	v_and_b32_e32 v5, 0xffff0000, v107
	global_load_dwordx2 v[168:169], v2, s[12:13]
	s_add_u32 s12, s12, 0x2000
	s_addc_u32 s13, s13, 0
	v_pk_mul_f32 v[8:9], v[8:9], v[16:17]
	v_pk_fma_f32 v[10:11], v[10:11], v[16:17], v[4:5]
	s_waitcnt vmcnt(30)
	v_lshlrev_b32_e32 v12, 16, v108
	v_lshlrev_b32_e32 v13, 16, v109
	v_exp_f32_e32 v12, v12
	v_exp_f32_e32 v13, v13
	v_and_b32_e32 v14, 0xffff0000, v108
	v_and_b32_e32 v15, 0xffff0000, v109
	global_load_dwordx2 v[170:171], v2, s[12:13]
	s_add_u32 s12, s12, 0x2000
	s_addc_u32 s13, s13, 0
	v_pk_mul_f32 v[8:9], v[8:9], v[12:13]
	v_pk_fma_f32 v[10:11], v[10:11], v[12:13], v[14:15]
	s_waitcnt vmcnt(30)
	v_lshlrev_b32_e32 v16, 16, v110
	v_lshlrev_b32_e32 v17, 16, v111
	v_exp_f32_e32 v16, v16
	v_exp_f32_e32 v17, v17
	v_and_b32_e32 v4, 0xffff0000, v110
	v_and_b32_e32 v5, 0xffff0000, v111
	global_load_dwordx2 v[172:173], v2, s[12:13]
	s_add_u32 s12, s12, 0x2000
	s_addc_u32 s13, s13, 0
	v_pk_mul_f32 v[8:9], v[8:9], v[16:17]
	v_pk_fma_f32 v[10:11], v[10:11], v[16:17], v[4:5]
	s_waitcnt vmcnt(30)
	v_lshlrev_b32_e32 v12, 16, v112
	v_lshlrev_b32_e32 v13, 16, v113
	v_exp_f32_e32 v12, v12
	v_exp_f32_e32 v13, v13
	v_and_b32_e32 v14, 0xffff0000, v112
	v_and_b32_e32 v15, 0xffff0000, v113
	global_load_dwordx2 v[174:175], v2, s[12:13]
	s_add_u32 s12, s12, 0x2000
	s_addc_u32 s13, s13, 0
	v_pk_mul_f32 v[8:9], v[8:9], v[12:13]
	v_pk_fma_f32 v[10:11], v[10:11], v[12:13], v[14:15]
	s_waitcnt vmcnt(30)
	v_lshlrev_b32_e32 v16, 16, v114
	v_lshlrev_b32_e32 v17, 16, v115
	v_exp_f32_e32 v16, v16
	v_exp_f32_e32 v17, v17
	v_and_b32_e32 v4, 0xffff0000, v114
	v_and_b32_e32 v5, 0xffff0000, v115
	global_load_dwordx2 v[176:177], v2, s[12:13]
	s_add_u32 s12, s12, 0x2000
	s_addc_u32 s13, s13, 0
	v_pk_mul_f32 v[8:9], v[8:9], v[16:17]
	v_pk_fma_f32 v[10:11], v[10:11], v[16:17], v[4:5]
	s_waitcnt vmcnt(30)
	v_lshlrev_b32_e32 v12, 16, v116
	v_lshlrev_b32_e32 v13, 16, v117
	v_exp_f32_e32 v12, v12
	v_exp_f32_e32 v13, v13
	v_and_b32_e32 v14, 0xffff0000, v116
	v_and_b32_e32 v15, 0xffff0000, v117
	global_load_dwordx2 v[178:179], v2, s[12:13]
	s_add_u32 s12, s12, 0x2000
	s_addc_u32 s13, s13, 0
	v_pk_mul_f32 v[8:9], v[8:9], v[12:13]
	v_pk_fma_f32 v[10:11], v[10:11], v[12:13], v[14:15]
	s_waitcnt vmcnt(30)
	v_lshlrev_b32_e32 v16, 16, v118
	v_lshlrev_b32_e32 v17, 16, v119
	v_exp_f32_e32 v16, v16
	v_exp_f32_e32 v17, v17
	v_and_b32_e32 v4, 0xffff0000, v118
	v_and_b32_e32 v5, 0xffff0000, v119
	global_load_dwordx2 v[180:181], v2, s[12:13]
	s_add_u32 s12, s12, 0x2000
	s_addc_u32 s13, s13, 0
	v_pk_mul_f32 v[8:9], v[8:9], v[16:17]
	v_pk_fma_f32 v[10:11], v[10:11], v[16:17], v[4:5]
	s_waitcnt vmcnt(30)
	v_lshlrev_b32_e32 v12, 16, v120
	v_lshlrev_b32_e32 v13, 16, v121
	v_exp_f32_e32 v12, v12
	v_exp_f32_e32 v13, v13
	v_and_b32_e32 v14, 0xffff0000, v120
	v_and_b32_e32 v15, 0xffff0000, v121
	global_load_dwordx2 v[182:183], v2, s[12:13]
	s_add_u32 s12, s12, 0x2000
	s_addc_u32 s13, s13, 0
	v_pk_mul_f32 v[8:9], v[8:9], v[12:13]
	v_pk_fma_f32 v[10:11], v[10:11], v[12:13], v[14:15]
	s_waitcnt vmcnt(30)
	v_lshlrev_b32_e32 v16, 16, v122
	v_lshlrev_b32_e32 v17, 16, v123
	v_exp_f32_e32 v16, v16
	v_exp_f32_e32 v17, v17
	v_and_b32_e32 v4, 0xffff0000, v122
	v_and_b32_e32 v5, 0xffff0000, v123
	global_load_dwordx2 v[184:185], v2, s[12:13]
	s_add_u32 s12, s12, 0x2000
	s_addc_u32 s13, s13, 0
	v_pk_mul_f32 v[8:9], v[8:9], v[16:17]
	v_pk_fma_f32 v[10:11], v[10:11], v[16:17], v[4:5]
	s_waitcnt vmcnt(30)
	v_lshlrev_b32_e32 v12, 16, v124
	v_lshlrev_b32_e32 v13, 16, v125
	v_exp_f32_e32 v12, v12
	v_exp_f32_e32 v13, v13
	v_and_b32_e32 v14, 0xffff0000, v124
	v_and_b32_e32 v15, 0xffff0000, v125
	global_load_dwordx2 v[186:187], v2, s[12:13]
	s_add_u32 s12, s12, 0x2000
	s_addc_u32 s13, s13, 0
	v_pk_mul_f32 v[8:9], v[8:9], v[12:13]
	v_pk_fma_f32 v[10:11], v[10:11], v[12:13], v[14:15]
	s_waitcnt vmcnt(30)
	v_lshlrev_b32_e32 v16, 16, v126
	v_lshlrev_b32_e32 v17, 16, v127
	v_exp_f32_e32 v16, v16
	v_exp_f32_e32 v17, v17
	v_and_b32_e32 v4, 0xffff0000, v126
	v_and_b32_e32 v5, 0xffff0000, v127
	global_load_dwordx2 v[188:189], v2, s[12:13]
	s_add_u32 s12, s12, 0x2000
	s_addc_u32 s13, s13, 0
	v_pk_mul_f32 v[8:9], v[8:9], v[16:17]
	v_pk_fma_f32 v[10:11], v[10:11], v[16:17], v[4:5]
	s_waitcnt vmcnt(30)
	v_lshlrev_b32_e32 v12, 16, v128
	v_lshlrev_b32_e32 v13, 16, v129
	v_exp_f32_e32 v12, v12
	v_exp_f32_e32 v13, v13
	v_and_b32_e32 v14, 0xffff0000, v128
	v_and_b32_e32 v15, 0xffff0000, v129
	global_load_dwordx2 v[190:191], v2, s[12:13]
	s_add_u32 s12, s12, 0x2000
	s_addc_u32 s13, s13, 0
	v_pk_mul_f32 v[8:9], v[8:9], v[12:13]
	v_pk_fma_f32 v[10:11], v[10:11], v[12:13], v[14:15]
	s_waitcnt vmcnt(30)
	v_lshlrev_b32_e32 v16, 16, v130
	v_lshlrev_b32_e32 v17, 16, v131
	v_exp_f32_e32 v16, v16
	v_exp_f32_e32 v17, v17
	v_and_b32_e32 v4, 0xffff0000, v130
	v_and_b32_e32 v5, 0xffff0000, v131
	global_load_dwordx2 v[192:193], v2, s[12:13]
	s_add_u32 s12, s12, 0x2000
	s_addc_u32 s13, s13, 0
	v_pk_mul_f32 v[8:9], v[8:9], v[16:17]
	v_pk_fma_f32 v[10:11], v[10:11], v[16:17], v[4:5]
	s_waitcnt vmcnt(30)
; __device__ __forceinline__ float bf_lo(unsigned w) { return __uint_as_float(w << 16); }
; __device__ __forceinline__ float bf_hi(unsigned w) { return __uint_as_float(w & 0xffff0000u); }
; __global__ void __launch_bounds__(NTHR, 2) hybrid_block_fwd(Args a) {
;     ...
;         for (int i = 0; i < CH_L; ++i) { const u32x2 q = pab[(size_t)i * (LW / 2)];
;             const f32x2 av = (f32x2){__builtin_amdgcn_exp2f(bf_lo(q.x)), __builtin_amdgcn_exp2f(bf_lo(q.y))}, bv = (f32x2){bf_hi(q.x), bf_hi(q.y)}; P = P * av; H = av * H + bv; }
	v_lshlrev_b32_e32 v12, 16, v132
	v_lshlrev_b32_e32 v13, 16, v133
	v_exp_f32_e32 v12, v12
	v_exp_f32_e32 v13, v13
	v_and_b32_e32 v14, 0xffff0000, v132
	v_and_b32_e32 v15, 0xffff0000, v133
	global_load_dwordx2 v[194:195], v2, s[12:13]
	s_add_u32 s12, s12, 0x2000
	s_addc_u32 s13, s13, 0
	v_pk_mul_f32 v[8:9], v[8:9], v[12:13]
	v_pk_fma_f32 v[10:11], v[10:11], v[12:13], v[14:15]
	s_waitcnt vmcnt(30)
	v_lshlrev_b32_e32 v16, 16, v134
	v_lshlrev_b32_e32 v17, 16, v135
	v_exp_f32_e32 v16, v16
	v_exp_f32_e32 v17, v17
	v_and_b32_e32 v4, 0xffff0000, v134
	v_and_b32_e32 v5, 0xffff0000, v135
	global_load_dwordx2 v[196:197], v2, s[12:13]
	s_add_u32 s12, s12, 0x2000
	s_addc_u32 s13, s13, 0
	v_pk_mul_f32 v[8:9], v[8:9], v[16:17]
	v_pk_fma_f32 v[10:11], v[10:11], v[16:17], v[4:5]
	s_waitcnt vmcnt(30)
	v_lshlrev_b32_e32 v12, 16, v136
	v_lshlrev_b32_e32 v13, 16, v137
	v_exp_f32_e32 v12, v12
	v_exp_f32_e32 v13, v13
	v_and_b32_e32 v14, 0xffff0000, v136
	v_and_b32_e32 v15, 0xffff0000, v137
	global_load_dwordx2 v[198:199], v2, s[12:13]
	s_add_u32 s12, s12, 0x2000
	s_addc_u32 s13, s13, 0
	v_pk_mul_f32 v[8:9], v[8:9], v[12:13]
	v_pk_fma_f32 v[10:11], v[10:11], v[12:13], v[14:15]
	s_waitcnt vmcnt(30)
	v_lshlrev_b32_e32 v16, 16, v138
	v_lshlrev_b32_e32 v17, 16, v139
	v_exp_f32_e32 v16, v16
	v_exp_f32_e32 v17, v17
	v_and_b32_e32 v4, 0xffff0000, v138
	v_and_b32_e32 v5, 0xffff0000, v139
	global_load_dwordx2 v[200:201], v2, s[12:13]
	s_add_u32 s12, s12, 0x2000
	s_addc_u32 s13, s13, 0
	v_pk_mul_f32 v[8:9], v[8:9], v[16:17]
	v_pk_fma_f32 v[10:11], v[10:11], v[16:17], v[4:5]
	s_waitcnt vmcnt(30)
	v_lshlrev_b32_e32 v12, 16, v140
	v_lshlrev_b32_e32 v13, 16, v141
	v_exp_f32_e32 v12, v12
	v_exp_f32_e32 v13, v13
	v_and_b32_e32 v14, 0xffff0000, v140
	v_and_b32_e32 v15, 0xffff0000, v141
	global_load_dwordx2 v[202:203], v2, s[12:13]
	s_add_u32 s12, s12, 0x2000
	s_addc_u32 s13, s13, 0
	v_pk_mul_f32 v[8:9], v[8:9], v[12:13]
	v_pk_fma_f32 v[10:11], v[10:11], v[12:13], v[14:15]
	s_waitcnt vmcnt(30)
	v_lshlrev_b32_e32 v16, 16, v142
	v_lshlrev_b32_e32 v17, 16, v143
	v_exp_f32_e32 v16, v16
	v_exp_f32_e32 v17, v17
	v_and_b32_e32 v4, 0xffff0000, v142
	v_and_b32_e32 v5, 0xffff0000, v143
	global_load_dwordx2 v[204:205], v2, s[12:13]
	s_add_u32 s12, s12, 0x2000
	s_addc_u32 s13, s13, 0
	v_pk_mul_f32 v[8:9], v[8:9], v[16:17]
	v_pk_fma_f32 v[10:11], v[10:11], v[16:17], v[4:5]
	s_waitcnt vmcnt(30)
	v_lshlrev_b32_e32 v12, 16, v144
	v_lshlrev_b32_e32 v13, 16, v145
	v_exp_f32_e32 v12, v12
	v_exp_f32_e32 v13, v13
	v_and_b32_e32 v14, 0xffff0000, v144
	v_and_b32_e32 v15, 0xffff0000, v145
	global_load_dwordx2 v[206:207], v2, s[12:13]
	s_add_u32 s12, s12, 0x2000
	s_addc_u32 s13, s13, 0
	v_pk_mul_f32 v[8:9], v[8:9], v[12:13]
	v_pk_fma_f32 v[10:11], v[10:11], v[12:13], v[14:15]
	s_waitcnt vmcnt(30)
	v_lshlrev_b32_e32 v16, 16, v146
	v_lshlrev_b32_e32 v17, 16, v147
	v_exp_f32_e32 v16, v16
	v_exp_f32_e32 v17, v17
	v_and_b32_e32 v4, 0xffff0000, v146
	v_and_b32_e32 v5, 0xffff0000, v147
	v_pk_mul_f32 v[8:9], v[8:9], v[16:17]
	v_pk_fma_f32 v[10:11], v[10:11], v[16:17], v[4:5]
	s_waitcnt vmcnt(29)
	v_lshlrev_b32_e32 v12, 16, v148
	v_lshlrev_b32_e32 v13, 16, v149
	v_exp_f32_e32 v12, v12
	v_exp_f32_e32 v13, v13
	v_and_b32_e32 v14, 0xffff0000, v148
	v_and_b32_e32 v15, 0xffff0000, v149
	v_pk_mul_f32 v[8:9], v[8:9], v[12:13]
	v_pk_fma_f32 v[10:11], v[10:11], v[12:13], v[14:15]
	s_waitcnt vmcnt(28)
	v_lshlrev_b32_e32 v16, 16, v150
	v_lshlrev_b32_e32 v17, 16, v151
	v_exp_f32_e32 v16, v16
	v_exp_f32_e32 v17, v17
	v_and_b32_e32 v4, 0xffff0000, v150
	v_and_b32_e32 v5, 0xffff0000, v151
	v_pk_mul_f32 v[8:9], v[8:9], v[16:17]
	v_pk_fma_f32 v[10:11], v[10:11], v[16:17], v[4:5]
	s_waitcnt vmcnt(27)
	v_lshlrev_b32_e32 v12, 16, v152
	v_lshlrev_b32_e32 v13, 16, v153
	v_exp_f32_e32 v12, v12
	v_exp_f32_e32 v13, v13
	v_and_b32_e32 v14, 0xffff0000, v152
	v_and_b32_e32 v15, 0xffff0000, v153
	v_pk_mul_f32 v[8:9], v[8:9], v[12:13]
	v_pk_fma_f32 v[10:11], v[10:11], v[12:13], v[14:15]
	s_waitcnt vmcnt(26)
	v_lshlrev_b32_e32 v16, 16, v154
	v_lshlrev_b32_e32 v17, 16, v155
	v_exp_f32_e32 v16, v16
	v_exp_f32_e32 v17, v17
	v_and_b32_e32 v4, 0xffff0000, v154
	v_and_b32_e32 v5, 0xffff0000, v155
	v_pk_mul_f32 v[8:9], v[8:9], v[16:17]
	v_pk_fma_f32 v[10:11], v[10:11], v[16:17], v[4:5]
	s_waitcnt vmcnt(25)
	v_lshlrev_b32_e32 v12, 16, v156
	v_lshlrev_b32_e32 v13, 16, v157
	v_exp_f32_e32 v12, v12
	v_exp_f32_e32 v13, v13
	v_and_b32_e32 v14, 0xffff0000, v156
	v_and_b32_e32 v15, 0xffff0000, v157
	v_pk_mul_f32 v[8:9], v[8:9], v[12:13]
	v_pk_fma_f32 v[10:11], v[10:11], v[12:13], v[14:15]
	s_waitcnt vmcnt(24)
	v_lshlrev_b32_e32 v16, 16, v158
	v_lshlrev_b32_e32 v17, 16, v159
	v_exp_f32_e32 v16, v16
	v_exp_f32_e32 v17, v17
	v_and_b32_e32 v4, 0xffff0000, v158
	v_and_b32_e32 v5, 0xffff0000, v159
	v_pk_mul_f32 v[8:9], v[8:9], v[16:17]
	v_pk_fma_f32 v[10:11], v[10:11], v[16:17], v[4:5]
	s_waitcnt vmcnt(23)
	v_lshlrev_b32_e32 v12, 16, v160
	v_lshlrev_b32_e32 v13, 16, v161
	v_exp_f32_e32 v12, v12
	v_exp_f32_e32 v13, v13
	v_and_b32_e32 v14, 0xffff0000, v160
	v_and_b32_e32 v15, 0xffff0000, v161
	v_pk_mul_f32 v[8:9], v[8:9], v[12:13]
	v_pk_fma_f32 v[10:11], v[10:11], v[12:13], v[14:15]
	s_waitcnt vmcnt(22)
	v_lshlrev_b32_e32 v16, 16, v162
	v_lshlrev_b32_e32 v17, 16, v163
	v_exp_f32_e32 v16, v16
	v_exp_f32_e32 v17, v17
	v_and_b32_e32 v4, 0xffff0000, v162
	v_and_b32_e32 v5, 0xffff0000, v163
	v_pk_mul_f32 v[8:9], v[8:9], v[16:17]
	v_pk_fma_f32 v[10:11], v[10:11], v[16:17], v[4:5]
	s_waitcnt vmcnt(21)
	v_lshlrev_b32_e32 v12, 16, v164
	v_lshlrev_b32_e32 v13, 16, v165
	v_exp_f32_e32 v12, v12
	v_exp_f32_e32 v13, v13
	v_and_b32_e32 v14, 0xffff0000, v164
	v_and_b32_e32 v15, 0xffff0000, v165
	v_pk_mul_f32 v[8:9], v[8:9], v[12:13]
	v_pk_fma_f32 v[10:11], v[10:11], v[12:13], v[14:15]
	s_waitcnt vmcnt(20)
; __device__ __forceinline__ float bf_lo(unsigned w) { return __uint_as_float(w << 16); }
; __device__ __forceinline__ float bf_hi(unsigned w) { return __uint_as_float(w & 0xffff0000u); }
; __device__ __forceinline__ void xcd_barrier(const XcdBarrier& b) {
;     asm volatile("s_waitcnt vmcnt(0)" ::: "memory");
;     __syncthreads();
; __global__ void __launch_bounds__(NTHR, 2) hybrid_block_fwd(Args a) {
;     ...
;         for (int i = 0; i < CH_L; ++i) { const u32x2 q = pab[(size_t)i * (LW / 2)];
;             const f32x2 av = (f32x2){__builtin_amdgcn_exp2f(bf_lo(q.x)), __builtin_amdgcn_exp2f(bf_lo(q.y))}, bv = (f32x2){bf_hi(q.x), bf_hi(q.y)}; P = P * av; H = av * H + bv; }
;         ((f32x2*)(AGGP + (size_t)(b * NCH + chunk) * LW))[c2] = P; ((f32x2*)(AGGH + (size_t)(b * NCH + chunk) * LW))[c2] = H;
	v_lshlrev_b32_e32 v16, 16, v166
	v_lshlrev_b32_e32 v17, 16, v167
	v_exp_f32_e32 v16, v16
	v_exp_f32_e32 v17, v17
	v_and_b32_e32 v4, 0xffff0000, v166
	v_and_b32_e32 v5, 0xffff0000, v167
	v_pk_mul_f32 v[8:9], v[8:9], v[16:17]
	v_pk_fma_f32 v[10:11], v[10:11], v[16:17], v[4:5]
	s_waitcnt vmcnt(19)
	v_lshlrev_b32_e32 v12, 16, v168
	v_lshlrev_b32_e32 v13, 16, v169
	v_exp_f32_e32 v12, v12
	v_exp_f32_e32 v13, v13
	v_and_b32_e32 v14, 0xffff0000, v168
	v_and_b32_e32 v15, 0xffff0000, v169
	v_pk_mul_f32 v[8:9], v[8:9], v[12:13]
	v_pk_fma_f32 v[10:11], v[10:11], v[12:13], v[14:15]
	s_waitcnt vmcnt(18)
	v_lshlrev_b32_e32 v16, 16, v170
	v_lshlrev_b32_e32 v17, 16, v171
	v_exp_f32_e32 v16, v16
	v_exp_f32_e32 v17, v17
	v_and_b32_e32 v4, 0xffff0000, v170
	v_and_b32_e32 v5, 0xffff0000, v171
	v_pk_mul_f32 v[8:9], v[8:9], v[16:17]
	v_pk_fma_f32 v[10:11], v[10:11], v[16:17], v[4:5]
	s_waitcnt vmcnt(17)
	v_lshlrev_b32_e32 v12, 16, v172
	v_lshlrev_b32_e32 v13, 16, v173
	v_exp_f32_e32 v12, v12
	v_exp_f32_e32 v13, v13
	v_and_b32_e32 v14, 0xffff0000, v172
	v_and_b32_e32 v15, 0xffff0000, v173
	v_pk_mul_f32 v[8:9], v[8:9], v[12:13]
	v_pk_fma_f32 v[10:11], v[10:11], v[12:13], v[14:15]
	s_waitcnt vmcnt(16)
	v_lshlrev_b32_e32 v16, 16, v174
	v_lshlrev_b32_e32 v17, 16, v175
	v_exp_f32_e32 v16, v16
	v_exp_f32_e32 v17, v17
	v_and_b32_e32 v4, 0xffff0000, v174
	v_and_b32_e32 v5, 0xffff0000, v175
	v_pk_mul_f32 v[8:9], v[8:9], v[16:17]
	v_pk_fma_f32 v[10:11], v[10:11], v[16:17], v[4:5]
	s_waitcnt vmcnt(15)
	v_lshlrev_b32_e32 v12, 16, v176
	v_lshlrev_b32_e32 v13, 16, v177
	v_exp_f32_e32 v12, v12
	v_exp_f32_e32 v13, v13
	v_and_b32_e32 v14, 0xffff0000, v176
	v_and_b32_e32 v15, 0xffff0000, v177
	v_pk_mul_f32 v[8:9], v[8:9], v[12:13]
	v_pk_fma_f32 v[10:11], v[10:11], v[12:13], v[14:15]
	s_waitcnt vmcnt(14)
	v_lshlrev_b32_e32 v16, 16, v178
	v_lshlrev_b32_e32 v17, 16, v179
	v_exp_f32_e32 v16, v16
	v_exp_f32_e32 v17, v17
	v_and_b32_e32 v4, 0xffff0000, v178
	v_and_b32_e32 v5, 0xffff0000, v179
	v_pk_mul_f32 v[8:9], v[8:9], v[16:17]
	v_pk_fma_f32 v[10:11], v[10:11], v[16:17], v[4:5]
	s_waitcnt vmcnt(13)
	v_lshlrev_b32_e32 v12, 16, v180
	v_lshlrev_b32_e32 v13, 16, v181
	v_exp_f32_e32 v12, v12
	v_exp_f32_e32 v13, v13
	v_and_b32_e32 v14, 0xffff0000, v180
	v_and_b32_e32 v15, 0xffff0000, v181
	v_pk_mul_f32 v[8:9], v[8:9], v[12:13]
	v_pk_fma_f32 v[10:11], v[10:11], v[12:13], v[14:15]
	s_waitcnt vmcnt(12)
	v_lshlrev_b32_e32 v16, 16, v182
	v_lshlrev_b32_e32 v17, 16, v183
	v_exp_f32_e32 v16, v16
	v_exp_f32_e32 v17, v17
	v_and_b32_e32 v4, 0xffff0000, v182
	v_and_b32_e32 v5, 0xffff0000, v183
	v_pk_mul_f32 v[8:9], v[8:9], v[16:17]
	v_pk_fma_f32 v[10:11], v[10:11], v[16:17], v[4:5]
	s_waitcnt vmcnt(11)
	v_lshlrev_b32_e32 v12, 16, v184
	v_lshlrev_b32_e32 v13, 16, v185
	v_exp_f32_e32 v12, v12
	v_exp_f32_e32 v13, v13
	v_and_b32_e32 v14, 0xffff0000, v184
	v_and_b32_e32 v15, 0xffff0000, v185
	v_pk_mul_f32 v[8:9], v[8:9], v[12:13]
	v_pk_fma_f32 v[10:11], v[10:11], v[12:13], v[14:15]
	s_waitcnt vmcnt(10)
	v_lshlrev_b32_e32 v16, 16, v186
	v_lshlrev_b32_e32 v17, 16, v187
	v_exp_f32_e32 v16, v16
	v_exp_f32_e32 v17, v17
	v_and_b32_e32 v4, 0xffff0000, v186
	v_and_b32_e32 v5, 0xffff0000, v187
	v_pk_mul_f32 v[8:9], v[8:9], v[16:17]
	v_pk_fma_f32 v[10:11], v[10:11], v[16:17], v[4:5]
	s_waitcnt vmcnt(9)
	v_lshlrev_b32_e32 v12, 16, v188
	v_lshlrev_b32_e32 v13, 16, v189
	v_exp_f32_e32 v12, v12
	v_exp_f32_e32 v13, v13
	v_and_b32_e32 v14, 0xffff0000, v188
	v_and_b32_e32 v15, 0xffff0000, v189
	v_pk_mul_f32 v[8:9], v[8:9], v[12:13]
	v_pk_fma_f32 v[10:11], v[10:11], v[12:13], v[14:15]
	s_waitcnt vmcnt(8)
	v_lshlrev_b32_e32 v16, 16, v190
	v_lshlrev_b32_e32 v17, 16, v191
	v_exp_f32_e32 v16, v16
	v_exp_f32_e32 v17, v17
	v_and_b32_e32 v4, 0xffff0000, v190
	v_and_b32_e32 v5, 0xffff0000, v191
	v_pk_mul_f32 v[8:9], v[8:9], v[16:17]
	v_pk_fma_f32 v[10:11], v[10:11], v[16:17], v[4:5]
	s_waitcnt vmcnt(7)
	v_lshlrev_b32_e32 v12, 16, v192
	v_lshlrev_b32_e32 v13, 16, v193
	v_exp_f32_e32 v12, v12
	v_exp_f32_e32 v13, v13
	v_and_b32_e32 v14, 0xffff0000, v192
	v_and_b32_e32 v15, 0xffff0000, v193
	v_pk_mul_f32 v[8:9], v[8:9], v[12:13]
	v_pk_fma_f32 v[10:11], v[10:11], v[12:13], v[14:15]
	s_waitcnt vmcnt(6)
	v_lshlrev_b32_e32 v16, 16, v194
	v_lshlrev_b32_e32 v17, 16, v195
	v_exp_f32_e32 v16, v16
	v_exp_f32_e32 v17, v17
	v_and_b32_e32 v4, 0xffff0000, v194
	v_and_b32_e32 v5, 0xffff0000, v195
	v_pk_mul_f32 v[8:9], v[8:9], v[16:17]
	v_pk_fma_f32 v[10:11], v[10:11], v[16:17], v[4:5]
	s_waitcnt vmcnt(5)
	v_lshlrev_b32_e32 v12, 16, v196
	v_lshlrev_b32_e32 v13, 16, v197
	v_exp_f32_e32 v12, v12
	v_exp_f32_e32 v13, v13
	v_and_b32_e32 v14, 0xffff0000, v196
	v_and_b32_e32 v15, 0xffff0000, v197
	v_pk_mul_f32 v[8:9], v[8:9], v[12:13]
	v_pk_fma_f32 v[10:11], v[10:11], v[12:13], v[14:15]
	s_waitcnt vmcnt(4)
	v_lshlrev_b32_e32 v16, 16, v198
	v_lshlrev_b32_e32 v17, 16, v199
	v_exp_f32_e32 v16, v16
	v_exp_f32_e32 v17, v17
	v_and_b32_e32 v4, 0xffff0000, v198
	v_and_b32_e32 v5, 0xffff0000, v199
	v_pk_mul_f32 v[8:9], v[8:9], v[16:17]
	v_pk_fma_f32 v[10:11], v[10:11], v[16:17], v[4:5]
	s_waitcnt vmcnt(3)
	v_lshlrev_b32_e32 v12, 16, v200
	v_lshlrev_b32_e32 v13, 16, v201
	v_exp_f32_e32 v12, v12
	v_exp_f32_e32 v13, v13
	v_and_b32_e32 v14, 0xffff0000, v200
	v_and_b32_e32 v15, 0xffff0000, v201
	v_pk_mul_f32 v[8:9], v[8:9], v[12:13]
	v_pk_fma_f32 v[10:11], v[10:11], v[12:13], v[14:15]
	s_waitcnt vmcnt(2)
	v_lshlrev_b32_e32 v16, 16, v202
	v_lshlrev_b32_e32 v17, 16, v203
	v_exp_f32_e32 v16, v16
	v_exp_f32_e32 v17, v17
	v_and_b32_e32 v4, 0xffff0000, v202
	v_and_b32_e32 v5, 0xffff0000, v203
	v_pk_mul_f32 v[8:9], v[8:9], v[16:17]
	v_pk_fma_f32 v[10:11], v[10:11], v[16:17], v[4:5]
	s_waitcnt vmcnt(1)
	v_lshlrev_b32_e32 v12, 16, v204
	v_lshlrev_b32_e32 v13, 16, v205
	v_exp_f32_e32 v12, v12
	v_exp_f32_e32 v13, v13
	v_and_b32_e32 v14, 0xffff0000, v204
	v_and_b32_e32 v15, 0xffff0000, v205
	v_pk_mul_f32 v[8:9], v[8:9], v[12:13]
	v_pk_fma_f32 v[10:11], v[10:11], v[12:13], v[14:15]
	s_waitcnt vmcnt(0)
	v_lshlrev_b32_e32 v16, 16, v206
	v_lshlrev_b32_e32 v17, 16, v207
	v_exp_f32_e32 v16, v16
	v_exp_f32_e32 v17, v17
	v_and_b32_e32 v4, 0xffff0000, v206
	v_and_b32_e32 v5, 0xffff0000, v207
	v_pk_mul_f32 v[8:9], v[8:9], v[16:17]
	v_pk_fma_f32 v[10:11], v[10:11], v[16:17], v[4:5]
	s_lshl_b32 s10, s9, 13
	s_add_u32 s0, s94, s10
	s_addc_u32 s1, s95, 0
	s_add_u32 s0, s0, 0x100000
	s_addc_u32 s1, s1, 0
	global_store_dwordx2 v2, v[8:9], s[0:1]
	global_store_dwordx2 v6, v[10:11], s[0:1]
	s_add_u32 s0, s94, 0x100000
	s_addc_u32 s1, s95, 0
	s_add_u32 s4, s94, 0x200000
	s_addc_u32 s5, s95, 0
	s_waitcnt vmcnt(0)
	s_barrier
; __device__ __forceinline__ unsigned xb_ld(unsigned* p)              { return __hip_atomic_load(p, __ATOMIC_RELAXED, __HIP_MEMORY_SCOPE_AGENT); }
; __device__ __forceinline__ void xcd_barrier_complete(unsigned* bar, unsigned x, unsigned& nloc, unsigned& nx) {
;     const unsigned G = gridDim.x * gridDim.y * gridDim.z;
;     unsigned sum, cnt, mine, sp = 0u;
;     for (;;) {
;         sum = 0u; cnt = 0u; mine = 0u;
; #pragma unroll
;         for (unsigned j = 0; j < 16; ++j) { const unsigned c = xb_ld(&bar[XB_XCNT(j)]); sum += c; cnt += (c > 0u) ? 1u : 0u; mine = (j == x) ? c : mine; }
; __device__ __forceinline__ void xcd_barrier(const XcdBarrier& b) {
;     ...
;     if (threadIdx.x == 0) {
;         unsigned* bar = b.bar;
;         __builtin_amdgcn_s_waitcnt(0);
;         unsigned nloc = b.st[0], nx = b.st[1];
;         if (nloc == 0u) { xcd_barrier_complete(bar, b.x, nloc, nx); b.st[0] = nloc; b.st[1] = nx; }
	s_mov_b64 s[8:9], exec
	v_readlane_b32 s10, v248, 6
	v_readlane_b32 s11, v248, 7
	s_and_b64 s[10:11], s[8:9], s[10:11]
	s_xor_b64 s[8:9], s[10:11], s[8:9]
	s_mov_b64 exec, s[10:11]
	s_cbranch_execz .LBB0_669
	s_add_i32 s10, 0, 0x20020
	v_mov_b32_e32 v0, s10
	s_waitcnt vmcnt(0) expcnt(0) lgkmcnt(0)
	ds_read_b32 v2, v0
	s_add_i32 s10, 0, 0x20024
	v_mov_b32_e32 v0, s10
	ds_read_b32 v0, v0
	s_waitcnt lgkmcnt(1)
	v_cmp_ne_u32_e32 vcc, 0, v2
	s_cbranch_vccnz .LBB0_632
	v_readlane_b32 s10, v248, 2
	v_readlane_b32 s11, v248, 3
	v_readlane_b32 s12, v248, 1
	s_mul_i32 s18, s11, s12
	s_mul_i32 s18, s18, s10
	s_add_u32 s10, s94, 0x40200
	s_addc_u32 s11, s95, 0
	s_add_u32 s38, s94, 0x40400
	s_addc_u32 s39, s95, 0
	s_add_u32 s42, s94, 0x40500
	s_addc_u32 s43, s95, 0
	s_add_u32 s54, s94, 0x40600
	s_addc_u32 s55, s95, 0
	s_add_u32 s56, s94, 0x40700
	s_addc_u32 s57, s95, 0
	s_add_u32 s58, s94, 0x40800
	s_addc_u32 s59, s95, 0
	s_add_u32 s60, s94, 0x40900
	s_addc_u32 s61, s95, 0
	s_add_u32 s62, s94, 0x40a00
	s_addc_u32 s63, s95, 0
	s_add_u32 s64, s94, 0x40b00
	s_addc_u32 s65, s95, 0
	s_add_u32 s66, s94, 0x40c00
	s_addc_u32 s67, s95, 0
	s_add_u32 s70, s94, 0x40d00
	s_addc_u32 s71, s95, 0
	s_add_u32 s72, s94, 0x40e00
	s_addc_u32 s73, s95, 0
	s_add_u32 s74, s94, 0x40f00
	s_addc_u32 s75, s95, 0
	s_add_u32 s76, s94, 0x41000
	s_addc_u32 s77, s95, 0
	s_add_u32 s78, s94, 0x41100
	s_addc_u32 s79, s95, 0
	s_add_u32 s34, s94, 0x41200
	s_addc_u32 s35, s95, 0
	s_add_u32 s48, s94, 0x41300
	s_addc_u32 s49, s95, 0
	s_mov_b32 s19, 1
	v_mov_b32_e32 v16, 0
	s_branch .LBB0_620

; __global__ void __launch_bounds__(NTHR, 2) hybrid_block_fwd(Args a) {
;     ...
;         const int c2 = gtid & 1023, chunk = (gtid >> 10) & (NCH - 1), b = gtid >> 16;
;         f32x2 H = (f32x2){0.f, 0.f};
; #pragma unroll 4
;         for (int j = 0; j < chunk; ++j) { const f32x2 P = ((const f32x2*)(AGGP + (size_t)(b * NCH + j) * LW))[c2], Hj = ((const f32x2*)(AGGH + (size_t)(b * NCH + j) * LW))[c2]; H = P * H + Hj; }
;         const size_t r0 = (size_t)b * SEQ + (size_t)chunk * CH_L;
;         const u32x2* pab = (const u32x2*)((const unsigned*)AF + r0 * LW) + c2;
;         const unsigned* pg = (const unsigned*)(GELU_U + r0 * LW) + c2; unsigned* po = (unsigned*)(YCAT + r0 * KC + PW) + c2;
.LBB0_669:
	s_or_b64 exec, exec, s[8:9]
	s_waitcnt lgkmcnt(0)
	v_mov_b32_e32 v0, v212
	v_readlane_b32 s8, v248, 8
	s_barrier
	s_nop 1
	v_add_u32_e32 v1, s8, v0
	v_and_b32_e32 v1, 0x3ff, v1
	v_lshlrev_b32_e32 v2, 3, v1
	v_lshlrev_b32_e32 v3, 2, v1
	v_add_u32_e32 v6, 0x100000, v2
	s_lshr_b32 s9, s8, 10
	s_and_b32 s10, s9, 63
	s_lshr_b32 s11, s9, 6
	s_lshl_b32 s21, s9, 20
	s_add_u32 s12, s92, s21
	s_addc_u32 s13, s93, 0
	s_lshl_b32 s21, s9, 19
	s_add_u32 s14, s94, s21
	s_addc_u32 s15, s95, 0
	s_add_u32 s14, s14, 0x9f00000
	s_addc_u32 s15, s15, 0
	s_mul_i32 s21, s9, 0xc0000
	s_add_u32 s18, s94, s21
	s_addc_u32 s19, s95, 0
	s_add_u32 s18, s18, 0x15f00800
	s_addc_u32 s19, s19, 0
	s_lshl_b32 s21, s11, 19
	s_add_u32 s0, s94, s21
	s_addc_u32 s1, s95, 0
	s_add_u32 s0, s0, 0x100000
	s_addc_u32 s1, s1, 0
	v_mov_b32_e32 v4, 0
	v_mov_b32_e32 v5, 0
	s_cmp_eq_u32 s10, 0
	s_cbranch_scc1 .Lp2d_prefix_done
.Lp2d_prefix_batch:
	global_load_dwordx2 v[20:21], v2, s[0:1]
	global_load_dwordx2 v[22:23], v6, s[0:1]
	s_add_u32 s0, s0, 0x2000
	s_addc_u32 s1, s1, 0
	global_load_dwordx2 v[24:25], v2, s[0:1]
	global_load_dwordx2 v[26:27], v6, s[0:1]
	s_add_u32 s0, s0, 0x2000
	s_addc_u32 s1, s1, 0
	global_load_dwordx2 v[28:29], v2, s[0:1]
	global_load_dwordx2 v[30:31], v6, s[0:1]
	s_add_u32 s0, s0, 0x2000
	s_addc_u32 s1, s1, 0
	global_load_dwordx2 v[32:33], v2, s[0:1]
	global_load_dwordx2 v[34:35], v6, s[0:1]
	s_add_u32 s0, s0, 0x2000
	s_addc_u32 s1, s1, 0
	global_load_dwordx2 v[36:37], v2, s[0:1]
	global_load_dwordx2 v[38:39], v6, s[0:1]
	s_add_u32 s0, s0, 0x2000
	s_addc_u32 s1, s1, 0
	global_load_dwordx2 v[40:41], v2, s[0:1]
	global_load_dwordx2 v[42:43], v6, s[0:1]
	s_add_u32 s0, s0, 0x2000
	s_addc_u32 s1, s1, 0
	global_load_dwordx2 v[44:45], v2, s[0:1]
	global_load_dwordx2 v[46:47], v6, s[0:1]
	s_add_u32 s0, s0, 0x2000
	s_addc_u32 s1, s1, 0
	global_load_dwordx2 v[48:49], v2, s[0:1]
	global_load_dwordx2 v[50:51], v6, s[0:1]
	s_add_u32 s0, s0, 0x2000
	s_addc_u32 s1, s1, 0
	global_load_dwordx2 v[52:53], v2, s[0:1]
	global_load_dwordx2 v[54:55], v6, s[0:1]
	s_add_u32 s0, s0, 0x2000
	s_addc_u32 s1, s1, 0
	global_load_dwordx2 v[56:57], v2, s[0:1]
	global_load_dwordx2 v[58:59], v6, s[0:1]
	s_add_u32 s0, s0, 0x2000
	s_addc_u32 s1, s1, 0
	global_load_dwordx2 v[60:61], v2, s[0:1]
	global_load_dwordx2 v[62:63], v6, s[0:1]
	s_add_u32 s0, s0, 0x2000
	s_addc_u32 s1, s1, 0
	s_waitcnt vmcnt(20)
	v_pk_fma_f32 v[4:5], v[4:5], v[20:21], v[22:23]
	s_sub_u32 s10, s10, 1
	s_cmp_eq_u32 s10, 0
	s_cbranch_scc1 .Lp2d_prefix_done
	s_waitcnt vmcnt(18)
	v_pk_fma_f32 v[4:5], v[4:5], v[24:25], v[26:27]
	s_sub_u32 s10, s10, 1
	s_cmp_eq_u32 s10, 0
	s_cbranch_scc1 .Lp2d_prefix_done
	s_waitcnt vmcnt(16)
	v_pk_fma_f32 v[4:5], v[4:5], v[28:29], v[30:31]
	s_sub_u32 s10, s10, 1
	s_cmp_eq_u32 s10, 0
	s_cbranch_scc1 .Lp2d_prefix_done
	s_waitcnt vmcnt(14)
	v_pk_fma_f32 v[4:5], v[4:5], v[32:33], v[34:35]
	s_sub_u32 s10, s10, 1
	s_cmp_eq_u32 s10, 0
	s_cbranch_scc1 .Lp2d_prefix_done
	s_waitcnt vmcnt(12)
	v_pk_fma_f32 v[4:5], v[4:5], v[36:37], v[38:39]
	s_sub_u32 s10, s10, 1
	s_cmp_eq_u32 s10, 0
	s_cbranch_scc1 .Lp2d_prefix_done
	s_waitcnt vmcnt(10)
	v_pk_fma_f32 v[4:5], v[4:5], v[40:41], v[42:43]
	s_sub_u32 s10, s10, 1
	s_cmp_eq_u32 s10, 0
	s_cbranch_scc1 .Lp2d_prefix_done
	s_waitcnt vmcnt(8)
	v_pk_fma_f32 v[4:5], v[4:5], v[44:45], v[46:47]
	s_sub_u32 s10, s10, 1
	s_cmp_eq_u32 s10, 0
	s_cbranch_scc1 .Lp2d_prefix_done
	s_waitcnt vmcnt(6)
	v_pk_fma_f32 v[4:5], v[4:5], v[48:49], v[50:51]
	s_sub_u32 s10, s10, 1
	s_cmp_eq_u32 s10, 0
	s_cbranch_scc1 .Lp2d_prefix_done
	s_waitcnt vmcnt(4)
	v_pk_fma_f32 v[4:5], v[4:5], v[52:53], v[54:55]
	s_sub_u32 s10, s10, 1
	s_cmp_eq_u32 s10, 0
	s_cbranch_scc1 .Lp2d_prefix_done
	s_waitcnt vmcnt(2)
	v_pk_fma_f32 v[4:5], v[4:5], v[56:57], v[58:59]
	s_sub_u32 s10, s10, 1
	s_cmp_eq_u32 s10, 0
	s_cbranch_scc1 .Lp2d_prefix_done
	s_waitcnt vmcnt(0)
	v_pk_fma_f32 v[4:5], v[4:5], v[60:61], v[62:63]
	s_sub_u32 s10, s10, 1
	s_cmp_eq_u32 s10, 0
	s_cbranch_scc1 .Lp2d_prefix_done
	s_branch .Lp2d_prefix_batch
.Lp2d_prefix_done:
	global_load_dwordx2 v[216:217], v2, s[12:13] nt
	s_add_u32 s12, s12, 0x2000
	s_addc_u32 s13, s13, 0
	global_load_dword v20, v3, s[14:15] nt
	s_add_u32 s14, s14, 0x1000
	s_addc_u32 s15, s15, 0
	global_load_dwordx2 v[218:219], v2, s[12:13] nt
	s_add_u32 s12, s12, 0x2000
	s_addc_u32 s13, s13, 0
	global_load_dword v21, v3, s[14:15] nt
	s_add_u32 s14, s14, 0x1000
	s_addc_u32 s15, s15, 0
	global_load_dwordx2 v[220:221], v2, s[12:13] nt
	s_add_u32 s12, s12, 0x2000
	s_addc_u32 s13, s13, 0
	global_load_dword v22, v3, s[14:15] nt
	s_add_u32 s14, s14, 0x1000
	s_addc_u32 s15, s15, 0
	global_load_dwordx2 v[222:223], v2, s[12:13] nt
	s_add_u32 s12, s12, 0x2000
	s_addc_u32 s13, s13, 0
	global_load_dword v23, v3, s[14:15] nt
	s_add_u32 s14, s14, 0x1000
	s_addc_u32 s15, s15, 0
	global_load_dwordx2 v[224:225], v2, s[12:13] nt
	s_add_u32 s12, s12, 0x2000
	s_addc_u32 s13, s13, 0
	global_load_dword v24, v3, s[14:15] nt
	s_add_u32 s14, s14, 0x1000
	s_addc_u32 s15, s15, 0
	global_load_dwordx2 v[226:227], v2, s[12:13] nt
	s_add_u32 s12, s12, 0x2000
	s_addc_u32 s13, s13, 0
	global_load_dword v25, v3, s[14:15] nt
	s_add_u32 s14, s14, 0x1000
	s_addc_u32 s15, s15, 0
	global_load_dwordx2 v[228:229], v2, s[12:13] nt
	s_add_u32 s12, s12, 0x2000
	s_addc_u32 s13, s13, 0
	global_load_dword v26, v3, s[14:15] nt
	s_add_u32 s14, s14, 0x1000
	s_addc_u32 s15, s15, 0
	global_load_dwordx2 v[230:231], v2, s[12:13] nt
	s_add_u32 s12, s12, 0x2000
	s_addc_u32 s13, s13, 0
	global_load_dword v27, v3, s[14:15] nt
	s_add_u32 s14, s14, 0x1000
	s_addc_u32 s15, s15, 0
	global_load_dwordx2 v[232:233], v2, s[12:13] nt
; __device__ __forceinline__ unsigned cvt_pk_bf16(float lo, float hi) { unsigned r; asm volatile("v_cvt_pk_bf16_f32 %0, %1, %2" : "=v"(r) : "v"(lo), "v"(hi)); return r; }
; __device__ __forceinline__ float bf_lo(unsigned w) { return __uint_as_float(w << 16); }
; __device__ __forceinline__ float bf_hi(unsigned w) { return __uint_as_float(w & 0xffff0000u); }
; __global__ void __launch_bounds__(NTHR, 2) hybrid_block_fwd(Args a) {
;     ...
; #pragma unroll 16
;         for (int i = 0; i < CH_L; ++i) {
;             const u32x2 q = pab[(size_t)i * (LW / 2)]; const f32x2 av = (f32x2){__builtin_amdgcn_exp2f(bf_lo(q.x)), __builtin_amdgcn_exp2f(bf_lo(q.y))}, bv = (f32x2){bf_hi(q.x), bf_hi(q.y)}; const unsigned gq = pg[(size_t)i * (LW / 2)];
;             H = av * H + bv;
;             po[(size_t)i * (KC / 2)] = cvt_pk_bf16(H.x * bf_lo(gq), H.y * bf_hi(gq));
	s_add_u32 s12, s12, 0x2000
	s_addc_u32 s13, s13, 0
	global_load_dword v28, v3, s[14:15] nt
	s_add_u32 s14, s14, 0x1000
	s_addc_u32 s15, s15, 0
	global_load_dwordx2 v[234:235], v2, s[12:13] nt
	s_add_u32 s12, s12, 0x2000
	s_addc_u32 s13, s13, 0
	global_load_dword v29, v3, s[14:15] nt
	s_add_u32 s14, s14, 0x1000
	s_addc_u32 s15, s15, 0
	global_load_dwordx2 v[236:237], v2, s[12:13] nt
	s_add_u32 s12, s12, 0x2000
	s_addc_u32 s13, s13, 0
	global_load_dword v30, v3, s[14:15] nt
	s_add_u32 s14, s14, 0x1000
	s_addc_u32 s15, s15, 0
	global_load_dwordx2 v[238:239], v2, s[12:13] nt
	s_add_u32 s12, s12, 0x2000
	s_addc_u32 s13, s13, 0
	global_load_dword v31, v3, s[14:15] nt
	s_add_u32 s14, s14, 0x1000
	s_addc_u32 s15, s15, 0
	global_load_dwordx2 v[240:241], v2, s[12:13] nt
	s_add_u32 s12, s12, 0x2000
	s_addc_u32 s13, s13, 0
	global_load_dword v32, v3, s[14:15] nt
	s_add_u32 s14, s14, 0x1000
	s_addc_u32 s15, s15, 0
	global_load_dwordx2 v[242:243], v2, s[12:13] nt
	s_add_u32 s12, s12, 0x2000
	s_addc_u32 s13, s13, 0
	global_load_dword v33, v3, s[14:15] nt
	s_add_u32 s14, s14, 0x1000
	s_addc_u32 s15, s15, 0
	global_load_dwordx2 v[244:245], v2, s[12:13] nt
	s_add_u32 s12, s12, 0x2000
	s_addc_u32 s13, s13, 0
	global_load_dword v34, v3, s[14:15] nt
	s_add_u32 s14, s14, 0x1000
	s_addc_u32 s15, s15, 0
	global_load_dwordx2 v[246:247], v2, s[12:13] nt
	s_add_u32 s12, s12, 0x2000
	s_addc_u32 s13, s13, 0
	global_load_dword v35, v3, s[14:15] nt
	s_add_u32 s14, s14, 0x1000
	s_addc_u32 s15, s15, 0
	s_waitcnt vmcnt(30)
	v_lshlrev_b32_e32 v8, 16, v216
	v_lshlrev_b32_e32 v9, 16, v217
	v_exp_f32_e32 v8, v8
	v_exp_f32_e32 v9, v9
	v_and_b32_e32 v10, 0xffff0000, v216
	v_and_b32_e32 v11, 0xffff0000, v217
	v_lshlrev_b32_e32 v12, 16, v20
	v_and_b32_e32 v13, 0xffff0000, v20
	v_pk_fma_f32 v[4:5], v[4:5], v[8:9], v[10:11]
	v_mul_f32_e32 v12, v4, v12
	v_mul_f32_e32 v13, v5, v13
	v_cvt_pk_bf16_f32 v12, v12, v13
	global_store_dword v3, v12, s[18:19]
	s_add_u32 s18, s18, 0x1800
	s_addc_u32 s19, s19, 0
	global_load_dwordx2 v[216:217], v2, s[12:13] nt
	s_add_u32 s12, s12, 0x2000
	s_addc_u32 s13, s13, 0
	global_load_dword v20, v3, s[14:15] nt
	s_add_u32 s14, s14, 0x1000
	s_addc_u32 s15, s15, 0
	s_waitcnt vmcnt(31)
	v_lshlrev_b32_e32 v14, 16, v218
	v_lshlrev_b32_e32 v15, 16, v219
	v_exp_f32_e32 v14, v14
	v_exp_f32_e32 v15, v15
	v_and_b32_e32 v16, 0xffff0000, v218
	v_and_b32_e32 v17, 0xffff0000, v219
	v_lshlrev_b32_e32 v18, 16, v21
	v_and_b32_e32 v19, 0xffff0000, v21
	v_pk_fma_f32 v[4:5], v[4:5], v[14:15], v[16:17]
	v_mul_f32_e32 v18, v4, v18
	v_mul_f32_e32 v19, v5, v19
	v_cvt_pk_bf16_f32 v18, v18, v19
	global_store_dword v3, v18, s[18:19]
	s_add_u32 s18, s18, 0x1800
	s_addc_u32 s19, s19, 0
	global_load_dwordx2 v[218:219], v2, s[12:13] nt
	s_add_u32 s12, s12, 0x2000
	s_addc_u32 s13, s13, 0
	global_load_dword v21, v3, s[14:15] nt
	s_add_u32 s14, s14, 0x1000
	s_addc_u32 s15, s15, 0
	s_waitcnt vmcnt(32)
	v_lshlrev_b32_e32 v8, 16, v220
	v_lshlrev_b32_e32 v9, 16, v221
	v_exp_f32_e32 v8, v8
	v_exp_f32_e32 v9, v9
	v_and_b32_e32 v10, 0xffff0000, v220
	v_and_b32_e32 v11, 0xffff0000, v221
	v_lshlrev_b32_e32 v12, 16, v22
	v_and_b32_e32 v13, 0xffff0000, v22
	v_pk_fma_f32 v[4:5], v[4:5], v[8:9], v[10:11]
	v_mul_f32_e32 v12, v4, v12
	v_mul_f32_e32 v13, v5, v13
	v_cvt_pk_bf16_f32 v12, v12, v13
	global_store_dword v3, v12, s[18:19]
	s_add_u32 s18, s18, 0x1800
	s_addc_u32 s19, s19, 0
	global_load_dwordx2 v[220:221], v2, s[12:13] nt
	s_add_u32 s12, s12, 0x2000
	s_addc_u32 s13, s13, 0
	global_load_dword v22, v3, s[14:15] nt
	s_add_u32 s14, s14, 0x1000
	s_addc_u32 s15, s15, 0
	s_waitcnt vmcnt(33)
	v_lshlrev_b32_e32 v14, 16, v222
	v_lshlrev_b32_e32 v15, 16, v223
	v_exp_f32_e32 v14, v14
	v_exp_f32_e32 v15, v15
	v_and_b32_e32 v16, 0xffff0000, v222
	v_and_b32_e32 v17, 0xffff0000, v223
	v_lshlrev_b32_e32 v18, 16, v23
	v_and_b32_e32 v19, 0xffff0000, v23
	v_pk_fma_f32 v[4:5], v[4:5], v[14:15], v[16:17]
	v_mul_f32_e32 v18, v4, v18
	v_mul_f32_e32 v19, v5, v19
	v_cvt_pk_bf16_f32 v18, v18, v19
	global_store_dword v3, v18, s[18:19]
	s_add_u32 s18, s18, 0x1800
	s_addc_u32 s19, s19, 0
	global_load_dwordx2 v[222:223], v2, s[12:13] nt
	s_add_u32 s12, s12, 0x2000
	s_addc_u32 s13, s13, 0
	global_load_dword v23, v3, s[14:15] nt
	s_add_u32 s14, s14, 0x1000
	s_addc_u32 s15, s15, 0
	s_waitcnt vmcnt(34)
	v_lshlrev_b32_e32 v8, 16, v224
	v_lshlrev_b32_e32 v9, 16, v225
	v_exp_f32_e32 v8, v8
	v_exp_f32_e32 v9, v9
	v_and_b32_e32 v10, 0xffff0000, v224
	v_and_b32_e32 v11, 0xffff0000, v225
	v_lshlrev_b32_e32 v12, 16, v24
	v_and_b32_e32 v13, 0xffff0000, v24
	v_pk_fma_f32 v[4:5], v[4:5], v[8:9], v[10:11]
	v_mul_f32_e32 v12, v4, v12
	v_mul_f32_e32 v13, v5, v13
	v_cvt_pk_bf16_f32 v12, v12, v13
	global_store_dword v3, v12, s[18:19]
	s_add_u32 s18, s18, 0x1800
	s_addc_u32 s19, s19, 0
	global_load_dwordx2 v[224:225], v2, s[12:13] nt
	s_add_u32 s12, s12, 0x2000
	s_addc_u32 s13, s13, 0
	global_load_dword v24, v3, s[14:15] nt
	s_add_u32 s14, s14, 0x1000
	s_addc_u32 s15, s15, 0
	s_waitcnt vmcnt(35)
	v_lshlrev_b32_e32 v14, 16, v226
	v_lshlrev_b32_e32 v15, 16, v227
	v_exp_f32_e32 v14, v14
	v_exp_f32_e32 v15, v15
	v_and_b32_e32 v16, 0xffff0000, v226
	v_and_b32_e32 v17, 0xffff0000, v227
	v_lshlrev_b32_e32 v18, 16, v25
	v_and_b32_e32 v19, 0xffff0000, v25
	v_pk_fma_f32 v[4:5], v[4:5], v[14:15], v[16:17]
	v_mul_f32_e32 v18, v4, v18
	v_mul_f32_e32 v19, v5, v19
	v_cvt_pk_bf16_f32 v18, v18, v19
	global_store_dword v3, v18, s[18:19]
	s_add_u32 s18, s18, 0x1800
	s_addc_u32 s19, s19, 0
	global_load_dwordx2 v[226:227], v2, s[12:13] nt
	s_add_u32 s12, s12, 0x2000
	s_addc_u32 s13, s13, 0
	global_load_dword v25, v3, s[14:15] nt
	s_add_u32 s14, s14, 0x1000
	s_addc_u32 s15, s15, 0
	s_waitcnt vmcnt(36)
; __device__ __forceinline__ unsigned cvt_pk_bf16(float lo, float hi) { unsigned r; asm volatile("v_cvt_pk_bf16_f32 %0, %1, %2" : "=v"(r) : "v"(lo), "v"(hi)); return r; }
; __device__ __forceinline__ float bf_lo(unsigned w) { return __uint_as_float(w << 16); }
; __device__ __forceinline__ float bf_hi(unsigned w) { return __uint_as_float(w & 0xffff0000u); }
; __global__ void __launch_bounds__(NTHR, 2) hybrid_block_fwd(Args a) {
;     ...
;         for (int i = 0; i < CH_L; ++i) {
;             const u32x2 q = pab[(size_t)i * (LW / 2)]; const f32x2 av = (f32x2){__builtin_amdgcn_exp2f(bf_lo(q.x)), __builtin_amdgcn_exp2f(bf_lo(q.y))}, bv = (f32x2){bf_hi(q.x), bf_hi(q.y)}; const unsigned gq = pg[(size_t)i * (LW / 2)];
;             H = av * H + bv;
;             po[(size_t)i * (KC / 2)] = cvt_pk_bf16(H.x * bf_lo(gq), H.y * bf_hi(gq));
	v_lshlrev_b32_e32 v8, 16, v228
	v_lshlrev_b32_e32 v9, 16, v229
	v_exp_f32_e32 v8, v8
	v_exp_f32_e32 v9, v9
	v_and_b32_e32 v10, 0xffff0000, v228
	v_and_b32_e32 v11, 0xffff0000, v229
	v_lshlrev_b32_e32 v12, 16, v26
	v_and_b32_e32 v13, 0xffff0000, v26
	v_pk_fma_f32 v[4:5], v[4:5], v[8:9], v[10:11]
	v_mul_f32_e32 v12, v4, v12
	v_mul_f32_e32 v13, v5, v13
	v_cvt_pk_bf16_f32 v12, v12, v13
	global_store_dword v3, v12, s[18:19]
	s_add_u32 s18, s18, 0x1800
	s_addc_u32 s19, s19, 0
	global_load_dwordx2 v[228:229], v2, s[12:13] nt
	s_add_u32 s12, s12, 0x2000
	s_addc_u32 s13, s13, 0
	global_load_dword v26, v3, s[14:15] nt
	s_add_u32 s14, s14, 0x1000
	s_addc_u32 s15, s15, 0
	s_waitcnt vmcnt(37)
	v_lshlrev_b32_e32 v14, 16, v230
	v_lshlrev_b32_e32 v15, 16, v231
	v_exp_f32_e32 v14, v14
	v_exp_f32_e32 v15, v15
	v_and_b32_e32 v16, 0xffff0000, v230
	v_and_b32_e32 v17, 0xffff0000, v231
	v_lshlrev_b32_e32 v18, 16, v27
	v_and_b32_e32 v19, 0xffff0000, v27
	v_pk_fma_f32 v[4:5], v[4:5], v[14:15], v[16:17]
	v_mul_f32_e32 v18, v4, v18
	v_mul_f32_e32 v19, v5, v19
	v_cvt_pk_bf16_f32 v18, v18, v19
	global_store_dword v3, v18, s[18:19]
	s_add_u32 s18, s18, 0x1800
	s_addc_u32 s19, s19, 0
	global_load_dwordx2 v[230:231], v2, s[12:13] nt
	s_add_u32 s12, s12, 0x2000
	s_addc_u32 s13, s13, 0
	global_load_dword v27, v3, s[14:15] nt
	s_add_u32 s14, s14, 0x1000
	s_addc_u32 s15, s15, 0
	s_waitcnt vmcnt(38)
	v_lshlrev_b32_e32 v8, 16, v232
	v_lshlrev_b32_e32 v9, 16, v233
	v_exp_f32_e32 v8, v8
	v_exp_f32_e32 v9, v9
	v_and_b32_e32 v10, 0xffff0000, v232
	v_and_b32_e32 v11, 0xffff0000, v233
	v_lshlrev_b32_e32 v12, 16, v28
	v_and_b32_e32 v13, 0xffff0000, v28
	v_pk_fma_f32 v[4:5], v[4:5], v[8:9], v[10:11]
	v_mul_f32_e32 v12, v4, v12
	v_mul_f32_e32 v13, v5, v13
	v_cvt_pk_bf16_f32 v12, v12, v13
	global_store_dword v3, v12, s[18:19]
	s_add_u32 s18, s18, 0x1800
	s_addc_u32 s19, s19, 0
	global_load_dwordx2 v[232:233], v2, s[12:13] nt
	s_add_u32 s12, s12, 0x2000
	s_addc_u32 s13, s13, 0
	global_load_dword v28, v3, s[14:15] nt
	s_add_u32 s14, s14, 0x1000
	s_addc_u32 s15, s15, 0
	s_waitcnt vmcnt(39)
	v_lshlrev_b32_e32 v14, 16, v234
	v_lshlrev_b32_e32 v15, 16, v235
	v_exp_f32_e32 v14, v14
	v_exp_f32_e32 v15, v15
	v_and_b32_e32 v16, 0xffff0000, v234
	v_and_b32_e32 v17, 0xffff0000, v235
	v_lshlrev_b32_e32 v18, 16, v29
	v_and_b32_e32 v19, 0xffff0000, v29
	v_pk_fma_f32 v[4:5], v[4:5], v[14:15], v[16:17]
	v_mul_f32_e32 v18, v4, v18
	v_mul_f32_e32 v19, v5, v19
	v_cvt_pk_bf16_f32 v18, v18, v19
	global_store_dword v3, v18, s[18:19]
	s_add_u32 s18, s18, 0x1800
	s_addc_u32 s19, s19, 0
	global_load_dwordx2 v[234:235], v2, s[12:13] nt
	s_add_u32 s12, s12, 0x2000
	s_addc_u32 s13, s13, 0
	global_load_dword v29, v3, s[14:15] nt
	s_add_u32 s14, s14, 0x1000
	s_addc_u32 s15, s15, 0
	s_waitcnt vmcnt(40)
	v_lshlrev_b32_e32 v8, 16, v236
	v_lshlrev_b32_e32 v9, 16, v237
	v_exp_f32_e32 v8, v8
	v_exp_f32_e32 v9, v9
	v_and_b32_e32 v10, 0xffff0000, v236
	v_and_b32_e32 v11, 0xffff0000, v237
	v_lshlrev_b32_e32 v12, 16, v30
	v_and_b32_e32 v13, 0xffff0000, v30
	v_pk_fma_f32 v[4:5], v[4:5], v[8:9], v[10:11]
	v_mul_f32_e32 v12, v4, v12
	v_mul_f32_e32 v13, v5, v13
	v_cvt_pk_bf16_f32 v12, v12, v13
	global_store_dword v3, v12, s[18:19]
	s_add_u32 s18, s18, 0x1800
	s_addc_u32 s19, s19, 0
	global_load_dwordx2 v[236:237], v2, s[12:13] nt
	s_add_u32 s12, s12, 0x2000
	s_addc_u32 s13, s13, 0
	global_load_dword v30, v3, s[14:15] nt
	s_add_u32 s14, s14, 0x1000
	s_addc_u32 s15, s15, 0
	s_waitcnt vmcnt(41)
	v_lshlrev_b32_e32 v14, 16, v238
	v_lshlrev_b32_e32 v15, 16, v239
	v_exp_f32_e32 v14, v14
	v_exp_f32_e32 v15, v15
	v_and_b32_e32 v16, 0xffff0000, v238
	v_and_b32_e32 v17, 0xffff0000, v239
	v_lshlrev_b32_e32 v18, 16, v31
	v_and_b32_e32 v19, 0xffff0000, v31
	v_pk_fma_f32 v[4:5], v[4:5], v[14:15], v[16:17]
	v_mul_f32_e32 v18, v4, v18
	v_mul_f32_e32 v19, v5, v19
	v_cvt_pk_bf16_f32 v18, v18, v19
	global_store_dword v3, v18, s[18:19]
	s_add_u32 s18, s18, 0x1800
	s_addc_u32 s19, s19, 0
	global_load_dwordx2 v[238:239], v2, s[12:13] nt
	s_add_u32 s12, s12, 0x2000
	s_addc_u32 s13, s13, 0
	global_load_dword v31, v3, s[14:15] nt
	s_add_u32 s14, s14, 0x1000
	s_addc_u32 s15, s15, 0
	s_waitcnt vmcnt(42)
	v_lshlrev_b32_e32 v8, 16, v240
	v_lshlrev_b32_e32 v9, 16, v241
	v_exp_f32_e32 v8, v8
	v_exp_f32_e32 v9, v9
	v_and_b32_e32 v10, 0xffff0000, v240
	v_and_b32_e32 v11, 0xffff0000, v241
	v_lshlrev_b32_e32 v12, 16, v32
	v_and_b32_e32 v13, 0xffff0000, v32
	v_pk_fma_f32 v[4:5], v[4:5], v[8:9], v[10:11]
	v_mul_f32_e32 v12, v4, v12
	v_mul_f32_e32 v13, v5, v13
	v_cvt_pk_bf16_f32 v12, v12, v13
	global_store_dword v3, v12, s[18:19]
	s_add_u32 s18, s18, 0x1800
	s_addc_u32 s19, s19, 0
	global_load_dwordx2 v[240:241], v2, s[12:13] nt
	s_add_u32 s12, s12, 0x2000
	s_addc_u32 s13, s13, 0
	global_load_dword v32, v3, s[14:15] nt
	s_add_u32 s14, s14, 0x1000
	s_addc_u32 s15, s15, 0
	s_waitcnt vmcnt(43)
	v_lshlrev_b32_e32 v14, 16, v242
	v_lshlrev_b32_e32 v15, 16, v243
	v_exp_f32_e32 v14, v14
	v_exp_f32_e32 v15, v15
	v_and_b32_e32 v16, 0xffff0000, v242
	v_and_b32_e32 v17, 0xffff0000, v243
	v_lshlrev_b32_e32 v18, 16, v33
	v_and_b32_e32 v19, 0xffff0000, v33
	v_pk_fma_f32 v[4:5], v[4:5], v[14:15], v[16:17]
	v_mul_f32_e32 v18, v4, v18
	v_mul_f32_e32 v19, v5, v19
	v_cvt_pk_bf16_f32 v18, v18, v19
	global_store_dword v3, v18, s[18:19]
	s_add_u32 s18, s18, 0x1800
	s_addc_u32 s19, s19, 0
	global_load_dwordx2 v[242:243], v2, s[12:13] nt
	s_add_u32 s12, s12, 0x2000
	s_addc_u32 s13, s13, 0
	global_load_dword v33, v3, s[14:15] nt
	s_add_u32 s14, s14, 0x1000
	s_addc_u32 s15, s15, 0
	s_waitcnt vmcnt(44)
; __device__ __forceinline__ unsigned cvt_pk_bf16(float lo, float hi) { unsigned r; asm volatile("v_cvt_pk_bf16_f32 %0, %1, %2" : "=v"(r) : "v"(lo), "v"(hi)); return r; }
; __device__ __forceinline__ float bf_lo(unsigned w) { return __uint_as_float(w << 16); }
; __device__ __forceinline__ float bf_hi(unsigned w) { return __uint_as_float(w & 0xffff0000u); }
; __global__ void __launch_bounds__(NTHR, 2) hybrid_block_fwd(Args a) {
;     ...
;         for (int i = 0; i < CH_L; ++i) {
;             const u32x2 q = pab[(size_t)i * (LW / 2)]; const f32x2 av = (f32x2){__builtin_amdgcn_exp2f(bf_lo(q.x)), __builtin_amdgcn_exp2f(bf_lo(q.y))}, bv = (f32x2){bf_hi(q.x), bf_hi(q.y)}; const unsigned gq = pg[(size_t)i * (LW / 2)];
;             H = av * H + bv;
;             po[(size_t)i * (KC / 2)] = cvt_pk_bf16(H.x * bf_lo(gq), H.y * bf_hi(gq));
;         }
	v_lshlrev_b32_e32 v8, 16, v244
	v_lshlrev_b32_e32 v9, 16, v245
	v_exp_f32_e32 v8, v8
	v_exp_f32_e32 v9, v9
	v_and_b32_e32 v10, 0xffff0000, v244
	v_and_b32_e32 v11, 0xffff0000, v245
	v_lshlrev_b32_e32 v12, 16, v34
	v_and_b32_e32 v13, 0xffff0000, v34
	v_pk_fma_f32 v[4:5], v[4:5], v[8:9], v[10:11]
	v_mul_f32_e32 v12, v4, v12
	v_mul_f32_e32 v13, v5, v13
	v_cvt_pk_bf16_f32 v12, v12, v13
	global_store_dword v3, v12, s[18:19]
	s_add_u32 s18, s18, 0x1800
	s_addc_u32 s19, s19, 0
	global_load_dwordx2 v[244:245], v2, s[12:13] nt
	s_add_u32 s12, s12, 0x2000
	s_addc_u32 s13, s13, 0
	global_load_dword v34, v3, s[14:15] nt
	s_add_u32 s14, s14, 0x1000
	s_addc_u32 s15, s15, 0
	s_waitcnt vmcnt(45)
	v_lshlrev_b32_e32 v14, 16, v246
	v_lshlrev_b32_e32 v15, 16, v247
	v_exp_f32_e32 v14, v14
	v_exp_f32_e32 v15, v15
	v_and_b32_e32 v16, 0xffff0000, v246
	v_and_b32_e32 v17, 0xffff0000, v247
	v_lshlrev_b32_e32 v18, 16, v35
	v_and_b32_e32 v19, 0xffff0000, v35
	v_pk_fma_f32 v[4:5], v[4:5], v[14:15], v[16:17]
	v_mul_f32_e32 v18, v4, v18
	v_mul_f32_e32 v19, v5, v19
	v_cvt_pk_bf16_f32 v18, v18, v19
	global_store_dword v3, v18, s[18:19]
	s_add_u32 s18, s18, 0x1800
	s_addc_u32 s19, s19, 0
	global_load_dwordx2 v[246:247], v2, s[12:13] nt
	s_add_u32 s12, s12, 0x2000
	s_addc_u32 s13, s13, 0
	global_load_dword v35, v3, s[14:15] nt
	s_add_u32 s14, s14, 0x1000
	s_addc_u32 s15, s15, 0
	s_waitcnt vmcnt(45)
	v_lshlrev_b32_e32 v8, 16, v216
	v_lshlrev_b32_e32 v9, 16, v217
	v_exp_f32_e32 v8, v8
	v_exp_f32_e32 v9, v9
	v_and_b32_e32 v10, 0xffff0000, v216
	v_and_b32_e32 v11, 0xffff0000, v217
	v_lshlrev_b32_e32 v12, 16, v20
	v_and_b32_e32 v13, 0xffff0000, v20
	v_pk_fma_f32 v[4:5], v[4:5], v[8:9], v[10:11]
	v_mul_f32_e32 v12, v4, v12
	v_mul_f32_e32 v13, v5, v13
	v_cvt_pk_bf16_f32 v12, v12, v13
	global_store_dword v3, v12, s[18:19]
	s_add_u32 s18, s18, 0x1800
	s_addc_u32 s19, s19, 0
	global_load_dwordx2 v[216:217], v2, s[12:13] nt
	s_add_u32 s12, s12, 0x2000
	s_addc_u32 s13, s13, 0
	global_load_dword v20, v3, s[14:15] nt
	s_add_u32 s14, s14, 0x1000
	s_addc_u32 s15, s15, 0
	s_waitcnt vmcnt(45)
	v_lshlrev_b32_e32 v14, 16, v218
	v_lshlrev_b32_e32 v15, 16, v219
	v_exp_f32_e32 v14, v14
	v_exp_f32_e32 v15, v15
	v_and_b32_e32 v16, 0xffff0000, v218
	v_and_b32_e32 v17, 0xffff0000, v219
	v_lshlrev_b32_e32 v18, 16, v21
	v_and_b32_e32 v19, 0xffff0000, v21
	v_pk_fma_f32 v[4:5], v[4:5], v[14:15], v[16:17]
	v_mul_f32_e32 v18, v4, v18
	v_mul_f32_e32 v19, v5, v19
	v_cvt_pk_bf16_f32 v18, v18, v19
	global_store_dword v3, v18, s[18:19]
	s_add_u32 s18, s18, 0x1800
	s_addc_u32 s19, s19, 0
	global_load_dwordx2 v[218:219], v2, s[12:13] nt
	s_add_u32 s12, s12, 0x2000
	s_addc_u32 s13, s13, 0
	global_load_dword v21, v3, s[14:15] nt
	s_add_u32 s14, s14, 0x1000
	s_addc_u32 s15, s15, 0
	s_waitcnt vmcnt(45)
	v_lshlrev_b32_e32 v8, 16, v220
	v_lshlrev_b32_e32 v9, 16, v221
	v_exp_f32_e32 v8, v8
	v_exp_f32_e32 v9, v9
	v_and_b32_e32 v10, 0xffff0000, v220
	v_and_b32_e32 v11, 0xffff0000, v221
	v_lshlrev_b32_e32 v12, 16, v22
	v_and_b32_e32 v13, 0xffff0000, v22
	v_pk_fma_f32 v[4:5], v[4:5], v[8:9], v[10:11]
	v_mul_f32_e32 v12, v4, v12
	v_mul_f32_e32 v13, v5, v13
	v_cvt_pk_bf16_f32 v12, v12, v13
	global_store_dword v3, v12, s[18:19]
	s_add_u32 s18, s18, 0x1800
	s_addc_u32 s19, s19, 0
	global_load_dwordx2 v[220:221], v2, s[12:13] nt
	s_add_u32 s12, s12, 0x2000
	s_addc_u32 s13, s13, 0
	global_load_dword v22, v3, s[14:15] nt
	s_add_u32 s14, s14, 0x1000
	s_addc_u32 s15, s15, 0
	s_waitcnt vmcnt(45)
	v_lshlrev_b32_e32 v14, 16, v222
	v_lshlrev_b32_e32 v15, 16, v223
	v_exp_f32_e32 v14, v14
	v_exp_f32_e32 v15, v15
	v_and_b32_e32 v16, 0xffff0000, v222
	v_and_b32_e32 v17, 0xffff0000, v223
	v_lshlrev_b32_e32 v18, 16, v23
	v_and_b32_e32 v19, 0xffff0000, v23
	v_pk_fma_f32 v[4:5], v[4:5], v[14:15], v[16:17]
	v_mul_f32_e32 v18, v4, v18
	v_mul_f32_e32 v19, v5, v19
	v_cvt_pk_bf16_f32 v18, v18, v19
	global_store_dword v3, v18, s[18:19]
	s_add_u32 s18, s18, 0x1800
	s_addc_u32 s19, s19, 0
	global_load_dwordx2 v[222:223], v2, s[12:13] nt
	s_add_u32 s12, s12, 0x2000
	s_addc_u32 s13, s13, 0
	global_load_dword v23, v3, s[14:15] nt
	s_add_u32 s14, s14, 0x1000
	s_addc_u32 s15, s15, 0
	s_waitcnt vmcnt(45)
	v_lshlrev_b32_e32 v8, 16, v224
	v_lshlrev_b32_e32 v9, 16, v225
	v_exp_f32_e32 v8, v8
	v_exp_f32_e32 v9, v9
	v_and_b32_e32 v10, 0xffff0000, v224
	v_and_b32_e32 v11, 0xffff0000, v225
	v_lshlrev_b32_e32 v12, 16, v24
	v_and_b32_e32 v13, 0xffff0000, v24
	v_pk_fma_f32 v[4:5], v[4:5], v[8:9], v[10:11]
	v_mul_f32_e32 v12, v4, v12
	v_mul_f32_e32 v13, v5, v13
	v_cvt_pk_bf16_f32 v12, v12, v13
	global_store_dword v3, v12, s[18:19]
	s_add_u32 s18, s18, 0x1800
	s_addc_u32 s19, s19, 0
	global_load_dwordx2 v[224:225], v2, s[12:13] nt
	s_add_u32 s12, s12, 0x2000
	s_addc_u32 s13, s13, 0
	global_load_dword v24, v3, s[14:15] nt
	s_add_u32 s14, s14, 0x1000
	s_addc_u32 s15, s15, 0
	s_waitcnt vmcnt(45)
	v_lshlrev_b32_e32 v14, 16, v226
	v_lshlrev_b32_e32 v15, 16, v227
	v_exp_f32_e32 v14, v14
	v_exp_f32_e32 v15, v15
	v_and_b32_e32 v16, 0xffff0000, v226
	v_and_b32_e32 v17, 0xffff0000, v227
	v_lshlrev_b32_e32 v18, 16, v25
	v_and_b32_e32 v19, 0xffff0000, v25
	v_pk_fma_f32 v[4:5], v[4:5], v[14:15], v[16:17]
	v_mul_f32_e32 v18, v4, v18
	v_mul_f32_e32 v19, v5, v19
	v_cvt_pk_bf16_f32 v18, v18, v19
	global_store_dword v3, v18, s[18:19]
	s_add_u32 s18, s18, 0x1800
	s_addc_u32 s19, s19, 0
	global_load_dwordx2 v[226:227], v2, s[12:13] nt
	s_add_u32 s12, s12, 0x2000
	s_addc_u32 s13, s13, 0
	global_load_dword v25, v3, s[14:15] nt
	s_add_u32 s14, s14, 0x1000
	s_addc_u32 s15, s15, 0
	s_waitcnt vmcnt(45)
; __device__ __forceinline__ unsigned cvt_pk_bf16(float lo, float hi) { unsigned r; asm volatile("v_cvt_pk_bf16_f32 %0, %1, %2" : "=v"(r) : "v"(lo), "v"(hi)); return r; }
; __device__ __forceinline__ float bf_lo(unsigned w) { return __uint_as_float(w << 16); }
; __device__ __forceinline__ float bf_hi(unsigned w) { return __uint_as_float(w & 0xffff0000u); }
; __global__ void __launch_bounds__(NTHR, 2) hybrid_block_fwd(Args a) {
;     ...
;         for (int i = 0; i < CH_L; ++i) {
;             const u32x2 q = pab[(size_t)i * (LW / 2)]; const f32x2 av = (f32x2){__builtin_amdgcn_exp2f(bf_lo(q.x)), __builtin_amdgcn_exp2f(bf_lo(q.y))}, bv = (f32x2){bf_hi(q.x), bf_hi(q.y)}; const unsigned gq = pg[(size_t)i * (LW / 2)];
;             H = av * H + bv;
;             po[(size_t)i * (KC / 2)] = cvt_pk_bf16(H.x * bf_lo(gq), H.y * bf_hi(gq));
;         }
	v_lshlrev_b32_e32 v8, 16, v228
	v_lshlrev_b32_e32 v9, 16, v229
	v_exp_f32_e32 v8, v8
	v_exp_f32_e32 v9, v9
	v_and_b32_e32 v10, 0xffff0000, v228
	v_and_b32_e32 v11, 0xffff0000, v229
	v_lshlrev_b32_e32 v12, 16, v26
	v_and_b32_e32 v13, 0xffff0000, v26
	v_pk_fma_f32 v[4:5], v[4:5], v[8:9], v[10:11]
	v_mul_f32_e32 v12, v4, v12
	v_mul_f32_e32 v13, v5, v13
	v_cvt_pk_bf16_f32 v12, v12, v13
	global_store_dword v3, v12, s[18:19]
	s_add_u32 s18, s18, 0x1800
	s_addc_u32 s19, s19, 0
	global_load_dwordx2 v[228:229], v2, s[12:13] nt
	s_add_u32 s12, s12, 0x2000
	s_addc_u32 s13, s13, 0
	global_load_dword v26, v3, s[14:15] nt
	s_add_u32 s14, s14, 0x1000
	s_addc_u32 s15, s15, 0
	s_waitcnt vmcnt(45)
	v_lshlrev_b32_e32 v14, 16, v230
	v_lshlrev_b32_e32 v15, 16, v231
	v_exp_f32_e32 v14, v14
	v_exp_f32_e32 v15, v15
	v_and_b32_e32 v16, 0xffff0000, v230
	v_and_b32_e32 v17, 0xffff0000, v231
	v_lshlrev_b32_e32 v18, 16, v27
	v_and_b32_e32 v19, 0xffff0000, v27
	v_pk_fma_f32 v[4:5], v[4:5], v[14:15], v[16:17]
	v_mul_f32_e32 v18, v4, v18
	v_mul_f32_e32 v19, v5, v19
	v_cvt_pk_bf16_f32 v18, v18, v19
	global_store_dword v3, v18, s[18:19]
	s_add_u32 s18, s18, 0x1800
	s_addc_u32 s19, s19, 0
	global_load_dwordx2 v[230:231], v2, s[12:13] nt
	s_add_u32 s12, s12, 0x2000
	s_addc_u32 s13, s13, 0
	global_load_dword v27, v3, s[14:15] nt
	s_add_u32 s14, s14, 0x1000
	s_addc_u32 s15, s15, 0
	s_waitcnt vmcnt(45)
	v_lshlrev_b32_e32 v8, 16, v232
	v_lshlrev_b32_e32 v9, 16, v233
	v_exp_f32_e32 v8, v8
	v_exp_f32_e32 v9, v9
	v_and_b32_e32 v10, 0xffff0000, v232
	v_and_b32_e32 v11, 0xffff0000, v233
	v_lshlrev_b32_e32 v12, 16, v28
	v_and_b32_e32 v13, 0xffff0000, v28
	v_pk_fma_f32 v[4:5], v[4:5], v[8:9], v[10:11]
	v_mul_f32_e32 v12, v4, v12
	v_mul_f32_e32 v13, v5, v13
	v_cvt_pk_bf16_f32 v12, v12, v13
	global_store_dword v3, v12, s[18:19]
	s_add_u32 s18, s18, 0x1800
	s_addc_u32 s19, s19, 0
	global_load_dwordx2 v[232:233], v2, s[12:13] nt
	s_add_u32 s12, s12, 0x2000
	s_addc_u32 s13, s13, 0
	global_load_dword v28, v3, s[14:15] nt
	s_add_u32 s14, s14, 0x1000
	s_addc_u32 s15, s15, 0
	s_waitcnt vmcnt(45)
	v_lshlrev_b32_e32 v14, 16, v234
	v_lshlrev_b32_e32 v15, 16, v235
	v_exp_f32_e32 v14, v14
	v_exp_f32_e32 v15, v15
	v_and_b32_e32 v16, 0xffff0000, v234
	v_and_b32_e32 v17, 0xffff0000, v235
	v_lshlrev_b32_e32 v18, 16, v29
	v_and_b32_e32 v19, 0xffff0000, v29
	v_pk_fma_f32 v[4:5], v[4:5], v[14:15], v[16:17]
	v_mul_f32_e32 v18, v4, v18
	v_mul_f32_e32 v19, v5, v19
	v_cvt_pk_bf16_f32 v18, v18, v19
	global_store_dword v3, v18, s[18:19]
	s_add_u32 s18, s18, 0x1800
	s_addc_u32 s19, s19, 0
	global_load_dwordx2 v[234:235], v2, s[12:13] nt
	s_add_u32 s12, s12, 0x2000
	s_addc_u32 s13, s13, 0
	global_load_dword v29, v3, s[14:15] nt
	s_add_u32 s14, s14, 0x1000
	s_addc_u32 s15, s15, 0
	s_waitcnt vmcnt(45)
	v_lshlrev_b32_e32 v8, 16, v236
	v_lshlrev_b32_e32 v9, 16, v237
	v_exp_f32_e32 v8, v8
	v_exp_f32_e32 v9, v9
	v_and_b32_e32 v10, 0xffff0000, v236
	v_and_b32_e32 v11, 0xffff0000, v237
	v_lshlrev_b32_e32 v12, 16, v30
	v_and_b32_e32 v13, 0xffff0000, v30
	v_pk_fma_f32 v[4:5], v[4:5], v[8:9], v[10:11]
	v_mul_f32_e32 v12, v4, v12
	v_mul_f32_e32 v13, v5, v13
	v_cvt_pk_bf16_f32 v12, v12, v13
	global_store_dword v3, v12, s[18:19]
	s_add_u32 s18, s18, 0x1800
	s_addc_u32 s19, s19, 0
	global_load_dwordx2 v[236:237], v2, s[12:13] nt
	s_add_u32 s12, s12, 0x2000
	s_addc_u32 s13, s13, 0
	global_load_dword v30, v3, s[14:15] nt
	s_add_u32 s14, s14, 0x1000
	s_addc_u32 s15, s15, 0
	s_waitcnt vmcnt(45)
	v_lshlrev_b32_e32 v14, 16, v238
	v_lshlrev_b32_e32 v15, 16, v239
	v_exp_f32_e32 v14, v14
	v_exp_f32_e32 v15, v15
	v_and_b32_e32 v16, 0xffff0000, v238
	v_and_b32_e32 v17, 0xffff0000, v239
	v_lshlrev_b32_e32 v18, 16, v31
	v_and_b32_e32 v19, 0xffff0000, v31
	v_pk_fma_f32 v[4:5], v[4:5], v[14:15], v[16:17]
	v_mul_f32_e32 v18, v4, v18
	v_mul_f32_e32 v19, v5, v19
	v_cvt_pk_bf16_f32 v18, v18, v19
	global_store_dword v3, v18, s[18:19]
	s_add_u32 s18, s18, 0x1800
	s_addc_u32 s19, s19, 0
	global_load_dwordx2 v[238:239], v2, s[12:13] nt
	s_add_u32 s12, s12, 0x2000
	s_addc_u32 s13, s13, 0
	global_load_dword v31, v3, s[14:15] nt
	s_add_u32 s14, s14, 0x1000
	s_addc_u32 s15, s15, 0
	s_waitcnt vmcnt(45)
	v_lshlrev_b32_e32 v8, 16, v240
	v_lshlrev_b32_e32 v9, 16, v241
	v_exp_f32_e32 v8, v8
	v_exp_f32_e32 v9, v9
	v_and_b32_e32 v10, 0xffff0000, v240
	v_and_b32_e32 v11, 0xffff0000, v241
	v_lshlrev_b32_e32 v12, 16, v32
	v_and_b32_e32 v13, 0xffff0000, v32
	v_pk_fma_f32 v[4:5], v[4:5], v[8:9], v[10:11]
	v_mul_f32_e32 v12, v4, v12
	v_mul_f32_e32 v13, v5, v13
	v_cvt_pk_bf16_f32 v12, v12, v13
	global_store_dword v3, v12, s[18:19]
	s_add_u32 s18, s18, 0x1800
	s_addc_u32 s19, s19, 0
	global_load_dwordx2 v[240:241], v2, s[12:13] nt
	s_add_u32 s12, s12, 0x2000
	s_addc_u32 s13, s13, 0
	global_load_dword v32, v3, s[14:15] nt
	s_add_u32 s14, s14, 0x1000
	s_addc_u32 s15, s15, 0
	s_waitcnt vmcnt(45)
	v_lshlrev_b32_e32 v14, 16, v242
	v_lshlrev_b32_e32 v15, 16, v243
	v_exp_f32_e32 v14, v14
	v_exp_f32_e32 v15, v15
	v_and_b32_e32 v16, 0xffff0000, v242
	v_and_b32_e32 v17, 0xffff0000, v243
	v_lshlrev_b32_e32 v18, 16, v33
	v_and_b32_e32 v19, 0xffff0000, v33
	v_pk_fma_f32 v[4:5], v[4:5], v[14:15], v[16:17]
	v_mul_f32_e32 v18, v4, v18
	v_mul_f32_e32 v19, v5, v19
	v_cvt_pk_bf16_f32 v18, v18, v19
	global_store_dword v3, v18, s[18:19]
	s_add_u32 s18, s18, 0x1800
	s_addc_u32 s19, s19, 0
	global_load_dwordx2 v[242:243], v2, s[12:13] nt
	s_add_u32 s12, s12, 0x2000
	s_addc_u32 s13, s13, 0
	global_load_dword v33, v3, s[14:15] nt
	s_add_u32 s14, s14, 0x1000
	s_addc_u32 s15, s15, 0
	s_waitcnt vmcnt(45)
; __device__ __forceinline__ unsigned cvt_pk_bf16(float lo, float hi) { unsigned r; asm volatile("v_cvt_pk_bf16_f32 %0, %1, %2" : "=v"(r) : "v"(lo), "v"(hi)); return r; }
; __device__ __forceinline__ float bf_lo(unsigned w) { return __uint_as_float(w << 16); }
; __device__ __forceinline__ float bf_hi(unsigned w) { return __uint_as_float(w & 0xffff0000u); }
; __global__ void __launch_bounds__(NTHR, 2) hybrid_block_fwd(Args a) {
;     ...
;         for (int i = 0; i < CH_L; ++i) {
;             const u32x2 q = pab[(size_t)i * (LW / 2)]; const f32x2 av = (f32x2){__builtin_amdgcn_exp2f(bf_lo(q.x)), __builtin_amdgcn_exp2f(bf_lo(q.y))}, bv = (f32x2){bf_hi(q.x), bf_hi(q.y)}; const unsigned gq = pg[(size_t)i * (LW / 2)];
;             H = av * H + bv;
;             po[(size_t)i * (KC / 2)] = cvt_pk_bf16(H.x * bf_lo(gq), H.y * bf_hi(gq));
;         }
	v_lshlrev_b32_e32 v8, 16, v244
	v_lshlrev_b32_e32 v9, 16, v245
	v_exp_f32_e32 v8, v8
	v_exp_f32_e32 v9, v9
	v_and_b32_e32 v10, 0xffff0000, v244
	v_and_b32_e32 v11, 0xffff0000, v245
	v_lshlrev_b32_e32 v12, 16, v34
	v_and_b32_e32 v13, 0xffff0000, v34
	v_pk_fma_f32 v[4:5], v[4:5], v[8:9], v[10:11]
	v_mul_f32_e32 v12, v4, v12
	v_mul_f32_e32 v13, v5, v13
	v_cvt_pk_bf16_f32 v12, v12, v13
	global_store_dword v3, v12, s[18:19]
	s_add_u32 s18, s18, 0x1800
	s_addc_u32 s19, s19, 0
	global_load_dwordx2 v[244:245], v2, s[12:13] nt
	s_add_u32 s12, s12, 0x2000
	s_addc_u32 s13, s13, 0
	global_load_dword v34, v3, s[14:15] nt
	s_add_u32 s14, s14, 0x1000
	s_addc_u32 s15, s15, 0
	s_waitcnt vmcnt(45)
	v_lshlrev_b32_e32 v14, 16, v246
	v_lshlrev_b32_e32 v15, 16, v247
	v_exp_f32_e32 v14, v14
	v_exp_f32_e32 v15, v15
	v_and_b32_e32 v16, 0xffff0000, v246
	v_and_b32_e32 v17, 0xffff0000, v247
	v_lshlrev_b32_e32 v18, 16, v35
	v_and_b32_e32 v19, 0xffff0000, v35
	v_pk_fma_f32 v[4:5], v[4:5], v[14:15], v[16:17]
	v_mul_f32_e32 v18, v4, v18
	v_mul_f32_e32 v19, v5, v19
	v_cvt_pk_bf16_f32 v18, v18, v19
	global_store_dword v3, v18, s[18:19]
	s_add_u32 s18, s18, 0x1800
	s_addc_u32 s19, s19, 0
	global_load_dwordx2 v[246:247], v2, s[12:13] nt
	s_add_u32 s12, s12, 0x2000
	s_addc_u32 s13, s13, 0
	global_load_dword v35, v3, s[14:15] nt
	s_add_u32 s14, s14, 0x1000
	s_addc_u32 s15, s15, 0
	s_waitcnt vmcnt(45)
	v_lshlrev_b32_e32 v8, 16, v216
	v_lshlrev_b32_e32 v9, 16, v217
	v_exp_f32_e32 v8, v8
	v_exp_f32_e32 v9, v9
	v_and_b32_e32 v10, 0xffff0000, v216
	v_and_b32_e32 v11, 0xffff0000, v217
	v_lshlrev_b32_e32 v12, 16, v20
	v_and_b32_e32 v13, 0xffff0000, v20
	v_pk_fma_f32 v[4:5], v[4:5], v[8:9], v[10:11]
	v_mul_f32_e32 v12, v4, v12
	v_mul_f32_e32 v13, v5, v13
	v_cvt_pk_bf16_f32 v12, v12, v13
	global_store_dword v3, v12, s[18:19]
	s_add_u32 s18, s18, 0x1800
	s_addc_u32 s19, s19, 0
	global_load_dwordx2 v[216:217], v2, s[12:13] nt
	s_add_u32 s12, s12, 0x2000
	s_addc_u32 s13, s13, 0
	global_load_dword v20, v3, s[14:15] nt
	s_add_u32 s14, s14, 0x1000
	s_addc_u32 s15, s15, 0
	s_waitcnt vmcnt(45)
	v_lshlrev_b32_e32 v14, 16, v218
	v_lshlrev_b32_e32 v15, 16, v219
	v_exp_f32_e32 v14, v14
	v_exp_f32_e32 v15, v15
	v_and_b32_e32 v16, 0xffff0000, v218
	v_and_b32_e32 v17, 0xffff0000, v219
	v_lshlrev_b32_e32 v18, 16, v21
	v_and_b32_e32 v19, 0xffff0000, v21
	v_pk_fma_f32 v[4:5], v[4:5], v[14:15], v[16:17]
	v_mul_f32_e32 v18, v4, v18
	v_mul_f32_e32 v19, v5, v19
	v_cvt_pk_bf16_f32 v18, v18, v19
	global_store_dword v3, v18, s[18:19]
	s_add_u32 s18, s18, 0x1800
	s_addc_u32 s19, s19, 0
	global_load_dwordx2 v[218:219], v2, s[12:13] nt
	s_add_u32 s12, s12, 0x2000
	s_addc_u32 s13, s13, 0
	global_load_dword v21, v3, s[14:15] nt
	s_add_u32 s14, s14, 0x1000
	s_addc_u32 s15, s15, 0
	s_waitcnt vmcnt(45)
	v_lshlrev_b32_e32 v8, 16, v220
	v_lshlrev_b32_e32 v9, 16, v221
	v_exp_f32_e32 v8, v8
	v_exp_f32_e32 v9, v9
	v_and_b32_e32 v10, 0xffff0000, v220
	v_and_b32_e32 v11, 0xffff0000, v221
	v_lshlrev_b32_e32 v12, 16, v22
	v_and_b32_e32 v13, 0xffff0000, v22
	v_pk_fma_f32 v[4:5], v[4:5], v[8:9], v[10:11]
	v_mul_f32_e32 v12, v4, v12
	v_mul_f32_e32 v13, v5, v13
	v_cvt_pk_bf16_f32 v12, v12, v13
	global_store_dword v3, v12, s[18:19]
	s_add_u32 s18, s18, 0x1800
	s_addc_u32 s19, s19, 0
	global_load_dwordx2 v[220:221], v2, s[12:13] nt
	s_add_u32 s12, s12, 0x2000
	s_addc_u32 s13, s13, 0
	global_load_dword v22, v3, s[14:15] nt
	s_add_u32 s14, s14, 0x1000
	s_addc_u32 s15, s15, 0
	s_waitcnt vmcnt(45)
	v_lshlrev_b32_e32 v14, 16, v222
	v_lshlrev_b32_e32 v15, 16, v223
	v_exp_f32_e32 v14, v14
	v_exp_f32_e32 v15, v15
	v_and_b32_e32 v16, 0xffff0000, v222
	v_and_b32_e32 v17, 0xffff0000, v223
	v_lshlrev_b32_e32 v18, 16, v23
	v_and_b32_e32 v19, 0xffff0000, v23
	v_pk_fma_f32 v[4:5], v[4:5], v[14:15], v[16:17]
	v_mul_f32_e32 v18, v4, v18
	v_mul_f32_e32 v19, v5, v19
	v_cvt_pk_bf16_f32 v18, v18, v19
	global_store_dword v3, v18, s[18:19]
	s_add_u32 s18, s18, 0x1800
	s_addc_u32 s19, s19, 0
	global_load_dwordx2 v[222:223], v2, s[12:13] nt
	s_add_u32 s12, s12, 0x2000
	s_addc_u32 s13, s13, 0
	global_load_dword v23, v3, s[14:15] nt
	s_add_u32 s14, s14, 0x1000
	s_addc_u32 s15, s15, 0
	s_waitcnt vmcnt(45)
	v_lshlrev_b32_e32 v8, 16, v224
	v_lshlrev_b32_e32 v9, 16, v225
	v_exp_f32_e32 v8, v8
	v_exp_f32_e32 v9, v9
	v_and_b32_e32 v10, 0xffff0000, v224
	v_and_b32_e32 v11, 0xffff0000, v225
	v_lshlrev_b32_e32 v12, 16, v24
	v_and_b32_e32 v13, 0xffff0000, v24
	v_pk_fma_f32 v[4:5], v[4:5], v[8:9], v[10:11]
	v_mul_f32_e32 v12, v4, v12
	v_mul_f32_e32 v13, v5, v13
	v_cvt_pk_bf16_f32 v12, v12, v13
	global_store_dword v3, v12, s[18:19]
	s_add_u32 s18, s18, 0x1800
	s_addc_u32 s19, s19, 0
	global_load_dwordx2 v[224:225], v2, s[12:13] nt
	s_add_u32 s12, s12, 0x2000
	s_addc_u32 s13, s13, 0
	global_load_dword v24, v3, s[14:15] nt
	s_add_u32 s14, s14, 0x1000
	s_addc_u32 s15, s15, 0
	s_waitcnt vmcnt(45)
	v_lshlrev_b32_e32 v14, 16, v226
	v_lshlrev_b32_e32 v15, 16, v227
	v_exp_f32_e32 v14, v14
	v_exp_f32_e32 v15, v15
	v_and_b32_e32 v16, 0xffff0000, v226
	v_and_b32_e32 v17, 0xffff0000, v227
	v_lshlrev_b32_e32 v18, 16, v25
	v_and_b32_e32 v19, 0xffff0000, v25
	v_pk_fma_f32 v[4:5], v[4:5], v[14:15], v[16:17]
	v_mul_f32_e32 v18, v4, v18
	v_mul_f32_e32 v19, v5, v19
	v_cvt_pk_bf16_f32 v18, v18, v19
	global_store_dword v3, v18, s[18:19]
	s_add_u32 s18, s18, 0x1800
	s_addc_u32 s19, s19, 0
	global_load_dwordx2 v[226:227], v2, s[12:13] nt
	s_add_u32 s12, s12, 0x2000
	s_addc_u32 s13, s13, 0
	global_load_dword v25, v3, s[14:15] nt
	s_add_u32 s14, s14, 0x1000
	s_addc_u32 s15, s15, 0
	s_waitcnt vmcnt(45)
; __device__ __forceinline__ unsigned cvt_pk_bf16(float lo, float hi) { unsigned r; asm volatile("v_cvt_pk_bf16_f32 %0, %1, %2" : "=v"(r) : "v"(lo), "v"(hi)); return r; }
; __device__ __forceinline__ float bf_lo(unsigned w) { return __uint_as_float(w << 16); }
; __device__ __forceinline__ float bf_hi(unsigned w) { return __uint_as_float(w & 0xffff0000u); }
; __global__ void __launch_bounds__(NTHR, 2) hybrid_block_fwd(Args a) {
;     ...
;         for (int i = 0; i < CH_L; ++i) {
;             const u32x2 q = pab[(size_t)i * (LW / 2)]; const f32x2 av = (f32x2){__builtin_amdgcn_exp2f(bf_lo(q.x)), __builtin_amdgcn_exp2f(bf_lo(q.y))}, bv = (f32x2){bf_hi(q.x), bf_hi(q.y)}; const unsigned gq = pg[(size_t)i * (LW / 2)];
;             H = av * H + bv;
;             po[(size_t)i * (KC / 2)] = cvt_pk_bf16(H.x * bf_lo(gq), H.y * bf_hi(gq));
;         }
	v_lshlrev_b32_e32 v8, 16, v228
	v_lshlrev_b32_e32 v9, 16, v229
	v_exp_f32_e32 v8, v8
	v_exp_f32_e32 v9, v9
	v_and_b32_e32 v10, 0xffff0000, v228
	v_and_b32_e32 v11, 0xffff0000, v229
	v_lshlrev_b32_e32 v12, 16, v26
	v_and_b32_e32 v13, 0xffff0000, v26
	v_pk_fma_f32 v[4:5], v[4:5], v[8:9], v[10:11]
	v_mul_f32_e32 v12, v4, v12
	v_mul_f32_e32 v13, v5, v13
	v_cvt_pk_bf16_f32 v12, v12, v13
	global_store_dword v3, v12, s[18:19]
	s_add_u32 s18, s18, 0x1800
	s_addc_u32 s19, s19, 0
	global_load_dwordx2 v[228:229], v2, s[12:13] nt
	s_add_u32 s12, s12, 0x2000
	s_addc_u32 s13, s13, 0
	global_load_dword v26, v3, s[14:15] nt
	s_add_u32 s14, s14, 0x1000
	s_addc_u32 s15, s15, 0
	s_waitcnt vmcnt(45)
	v_lshlrev_b32_e32 v14, 16, v230
	v_lshlrev_b32_e32 v15, 16, v231
	v_exp_f32_e32 v14, v14
	v_exp_f32_e32 v15, v15
	v_and_b32_e32 v16, 0xffff0000, v230
	v_and_b32_e32 v17, 0xffff0000, v231
	v_lshlrev_b32_e32 v18, 16, v27
	v_and_b32_e32 v19, 0xffff0000, v27
	v_pk_fma_f32 v[4:5], v[4:5], v[14:15], v[16:17]
	v_mul_f32_e32 v18, v4, v18
	v_mul_f32_e32 v19, v5, v19
	v_cvt_pk_bf16_f32 v18, v18, v19
	global_store_dword v3, v18, s[18:19]
	s_add_u32 s18, s18, 0x1800
	s_addc_u32 s19, s19, 0
	global_load_dwordx2 v[230:231], v2, s[12:13] nt
	s_add_u32 s12, s12, 0x2000
	s_addc_u32 s13, s13, 0
	global_load_dword v27, v3, s[14:15] nt
	s_add_u32 s14, s14, 0x1000
	s_addc_u32 s15, s15, 0
	s_waitcnt vmcnt(45)
	v_lshlrev_b32_e32 v8, 16, v232
	v_lshlrev_b32_e32 v9, 16, v233
	v_exp_f32_e32 v8, v8
	v_exp_f32_e32 v9, v9
	v_and_b32_e32 v10, 0xffff0000, v232
	v_and_b32_e32 v11, 0xffff0000, v233
	v_lshlrev_b32_e32 v12, 16, v28
	v_and_b32_e32 v13, 0xffff0000, v28
	v_pk_fma_f32 v[4:5], v[4:5], v[8:9], v[10:11]
	v_mul_f32_e32 v12, v4, v12
	v_mul_f32_e32 v13, v5, v13
	v_cvt_pk_bf16_f32 v12, v12, v13
	global_store_dword v3, v12, s[18:19]
	s_add_u32 s18, s18, 0x1800
	s_addc_u32 s19, s19, 0
	global_load_dword v28, v3, s[14:15] nt
	s_add_u32 s14, s14, 0x1000
	s_addc_u32 s15, s15, 0
	s_waitcnt vmcnt(44)
	v_lshlrev_b32_e32 v14, 16, v234
	v_lshlrev_b32_e32 v15, 16, v235
	v_exp_f32_e32 v14, v14
	v_exp_f32_e32 v15, v15
	v_and_b32_e32 v16, 0xffff0000, v234
	v_and_b32_e32 v17, 0xffff0000, v235
	v_lshlrev_b32_e32 v18, 16, v29
	v_and_b32_e32 v19, 0xffff0000, v29
	v_pk_fma_f32 v[4:5], v[4:5], v[14:15], v[16:17]
	v_mul_f32_e32 v18, v4, v18
	v_mul_f32_e32 v19, v5, v19
	v_cvt_pk_bf16_f32 v18, v18, v19
	global_store_dword v3, v18, s[18:19]
	s_add_u32 s18, s18, 0x1800
	s_addc_u32 s19, s19, 0
	global_load_dword v29, v3, s[14:15] nt
	s_add_u32 s14, s14, 0x1000
	s_addc_u32 s15, s15, 0
	s_waitcnt vmcnt(43)
	v_lshlrev_b32_e32 v8, 16, v236
	v_lshlrev_b32_e32 v9, 16, v237
	v_exp_f32_e32 v8, v8
	v_exp_f32_e32 v9, v9
	v_and_b32_e32 v10, 0xffff0000, v236
	v_and_b32_e32 v11, 0xffff0000, v237
	v_lshlrev_b32_e32 v12, 16, v30
	v_and_b32_e32 v13, 0xffff0000, v30
	v_pk_fma_f32 v[4:5], v[4:5], v[8:9], v[10:11]
	v_mul_f32_e32 v12, v4, v12
	v_mul_f32_e32 v13, v5, v13
	v_cvt_pk_bf16_f32 v12, v12, v13
	global_store_dword v3, v12, s[18:19]
	s_add_u32 s18, s18, 0x1800
	s_addc_u32 s19, s19, 0
	global_load_dword v30, v3, s[14:15] nt
	s_add_u32 s14, s14, 0x1000
	s_addc_u32 s15, s15, 0
	s_waitcnt vmcnt(42)
	v_lshlrev_b32_e32 v14, 16, v238
	v_lshlrev_b32_e32 v15, 16, v239
	v_exp_f32_e32 v14, v14
	v_exp_f32_e32 v15, v15
	v_and_b32_e32 v16, 0xffff0000, v238
	v_and_b32_e32 v17, 0xffff0000, v239
	v_lshlrev_b32_e32 v18, 16, v31
	v_and_b32_e32 v19, 0xffff0000, v31
	v_pk_fma_f32 v[4:5], v[4:5], v[14:15], v[16:17]
	v_mul_f32_e32 v18, v4, v18
	v_mul_f32_e32 v19, v5, v19
	v_cvt_pk_bf16_f32 v18, v18, v19
	global_store_dword v3, v18, s[18:19]
	s_add_u32 s18, s18, 0x1800
	s_addc_u32 s19, s19, 0
	global_load_dword v31, v3, s[14:15] nt
	s_add_u32 s14, s14, 0x1000
	s_addc_u32 s15, s15, 0
	s_waitcnt vmcnt(41)
	v_lshlrev_b32_e32 v8, 16, v240
	v_lshlrev_b32_e32 v9, 16, v241
	v_exp_f32_e32 v8, v8
	v_exp_f32_e32 v9, v9
	v_and_b32_e32 v10, 0xffff0000, v240
	v_and_b32_e32 v11, 0xffff0000, v241
	v_lshlrev_b32_e32 v12, 16, v32
	v_and_b32_e32 v13, 0xffff0000, v32
	v_pk_fma_f32 v[4:5], v[4:5], v[8:9], v[10:11]
	v_mul_f32_e32 v12, v4, v12
	v_mul_f32_e32 v13, v5, v13
	v_cvt_pk_bf16_f32 v12, v12, v13
	global_store_dword v3, v12, s[18:19]
	s_add_u32 s18, s18, 0x1800
	s_addc_u32 s19, s19, 0
	global_load_dword v32, v3, s[14:15] nt
	s_add_u32 s14, s14, 0x1000
	s_addc_u32 s15, s15, 0
	s_waitcnt vmcnt(40)
	v_lshlrev_b32_e32 v14, 16, v242
	v_lshlrev_b32_e32 v15, 16, v243
	v_exp_f32_e32 v14, v14
	v_exp_f32_e32 v15, v15
	v_and_b32_e32 v16, 0xffff0000, v242
	v_and_b32_e32 v17, 0xffff0000, v243
	v_lshlrev_b32_e32 v18, 16, v33
	v_and_b32_e32 v19, 0xffff0000, v33
	v_pk_fma_f32 v[4:5], v[4:5], v[14:15], v[16:17]
	v_mul_f32_e32 v18, v4, v18
	v_mul_f32_e32 v19, v5, v19
	v_cvt_pk_bf16_f32 v18, v18, v19
	global_store_dword v3, v18, s[18:19]
	s_add_u32 s18, s18, 0x1800
	s_addc_u32 s19, s19, 0
	global_load_dword v33, v3, s[14:15] nt
	s_add_u32 s14, s14, 0x1000
	s_addc_u32 s15, s15, 0
	s_waitcnt vmcnt(39)
	v_lshlrev_b32_e32 v8, 16, v244
	v_lshlrev_b32_e32 v9, 16, v245
	v_exp_f32_e32 v8, v8
	v_exp_f32_e32 v9, v9
	v_and_b32_e32 v10, 0xffff0000, v244
	v_and_b32_e32 v11, 0xffff0000, v245
	v_lshlrev_b32_e32 v12, 16, v34
	v_and_b32_e32 v13, 0xffff0000, v34
	v_pk_fma_f32 v[4:5], v[4:5], v[8:9], v[10:11]
	v_mul_f32_e32 v12, v4, v12
	v_mul_f32_e32 v13, v5, v13
	v_cvt_pk_bf16_f32 v12, v12, v13
	global_store_dword v3, v12, s[18:19]
	s_add_u32 s18, s18, 0x1800
	s_addc_u32 s19, s19, 0
	global_load_dword v34, v3, s[14:15] nt
	s_add_u32 s14, s14, 0x1000
	s_addc_u32 s15, s15, 0
	s_waitcnt vmcnt(38)
; __device__ __forceinline__ unsigned cvt_pk_bf16(float lo, float hi) { unsigned r; asm volatile("v_cvt_pk_bf16_f32 %0, %1, %2" : "=v"(r) : "v"(lo), "v"(hi)); return r; }
; __device__ __forceinline__ float bf_lo(unsigned w) { return __uint_as_float(w << 16); }
; __device__ __forceinline__ float bf_hi(unsigned w) { return __uint_as_float(w & 0xffff0000u); }
; __global__ void __launch_bounds__(NTHR, 2) hybrid_block_fwd(Args a) {
;     ...
;         for (int i = 0; i < CH_L; ++i) {
;             const u32x2 q = pab[(size_t)i * (LW / 2)]; const f32x2 av = (f32x2){__builtin_amdgcn_exp2f(bf_lo(q.x)), __builtin_amdgcn_exp2f(bf_lo(q.y))}, bv = (f32x2){bf_hi(q.x), bf_hi(q.y)}; const unsigned gq = pg[(size_t)i * (LW / 2)];
;             H = av * H + bv;
;             po[(size_t)i * (KC / 2)] = cvt_pk_bf16(H.x * bf_lo(gq), H.y * bf_hi(gq));
;         }
	v_lshlrev_b32_e32 v14, 16, v246
	v_lshlrev_b32_e32 v15, 16, v247
	v_exp_f32_e32 v14, v14
	v_exp_f32_e32 v15, v15
	v_and_b32_e32 v16, 0xffff0000, v246
	v_and_b32_e32 v17, 0xffff0000, v247
	v_lshlrev_b32_e32 v18, 16, v35
	v_and_b32_e32 v19, 0xffff0000, v35
	v_pk_fma_f32 v[4:5], v[4:5], v[14:15], v[16:17]
	v_mul_f32_e32 v18, v4, v18
	v_mul_f32_e32 v19, v5, v19
	v_cvt_pk_bf16_f32 v18, v18, v19
	global_store_dword v3, v18, s[18:19]
	s_add_u32 s18, s18, 0x1800
	s_addc_u32 s19, s19, 0
	global_load_dword v35, v3, s[14:15] nt
	s_add_u32 s14, s14, 0x1000
	s_addc_u32 s15, s15, 0
	s_waitcnt vmcnt(37)
	v_lshlrev_b32_e32 v8, 16, v216
	v_lshlrev_b32_e32 v9, 16, v217
	v_exp_f32_e32 v8, v8
	v_exp_f32_e32 v9, v9
	v_and_b32_e32 v10, 0xffff0000, v216
	v_and_b32_e32 v11, 0xffff0000, v217
	v_lshlrev_b32_e32 v12, 16, v20
	v_and_b32_e32 v13, 0xffff0000, v20
	v_pk_fma_f32 v[4:5], v[4:5], v[8:9], v[10:11]
	v_mul_f32_e32 v12, v4, v12
	v_mul_f32_e32 v13, v5, v13
	v_cvt_pk_bf16_f32 v12, v12, v13
	global_store_dword v3, v12, s[18:19]
	s_add_u32 s18, s18, 0x1800
	s_addc_u32 s19, s19, 0
	global_load_dword v20, v3, s[14:15] nt
	s_add_u32 s14, s14, 0x1000
	s_addc_u32 s15, s15, 0
	s_waitcnt vmcnt(36)
	v_lshlrev_b32_e32 v14, 16, v218
	v_lshlrev_b32_e32 v15, 16, v219
	v_exp_f32_e32 v14, v14
	v_exp_f32_e32 v15, v15
	v_and_b32_e32 v16, 0xffff0000, v218
	v_and_b32_e32 v17, 0xffff0000, v219
	v_lshlrev_b32_e32 v18, 16, v21
	v_and_b32_e32 v19, 0xffff0000, v21
	v_pk_fma_f32 v[4:5], v[4:5], v[14:15], v[16:17]
	v_mul_f32_e32 v18, v4, v18
	v_mul_f32_e32 v19, v5, v19
	v_cvt_pk_bf16_f32 v18, v18, v19
	global_store_dword v3, v18, s[18:19]
	s_add_u32 s18, s18, 0x1800
	s_addc_u32 s19, s19, 0
	global_load_dword v21, v3, s[14:15] nt
	s_add_u32 s14, s14, 0x1000
	s_addc_u32 s15, s15, 0
	s_waitcnt vmcnt(35)
	v_lshlrev_b32_e32 v8, 16, v220
	v_lshlrev_b32_e32 v9, 16, v221
	v_exp_f32_e32 v8, v8
	v_exp_f32_e32 v9, v9
	v_and_b32_e32 v10, 0xffff0000, v220
	v_and_b32_e32 v11, 0xffff0000, v221
	v_lshlrev_b32_e32 v12, 16, v22
	v_and_b32_e32 v13, 0xffff0000, v22
	v_pk_fma_f32 v[4:5], v[4:5], v[8:9], v[10:11]
	v_mul_f32_e32 v12, v4, v12
	v_mul_f32_e32 v13, v5, v13
	v_cvt_pk_bf16_f32 v12, v12, v13
	global_store_dword v3, v12, s[18:19]
	s_add_u32 s18, s18, 0x1800
	s_addc_u32 s19, s19, 0
	global_load_dword v22, v3, s[14:15] nt
	s_add_u32 s14, s14, 0x1000
	s_addc_u32 s15, s15, 0
	s_waitcnt vmcnt(34)
	v_lshlrev_b32_e32 v14, 16, v222
	v_lshlrev_b32_e32 v15, 16, v223
	v_exp_f32_e32 v14, v14
	v_exp_f32_e32 v15, v15
	v_and_b32_e32 v16, 0xffff0000, v222
	v_and_b32_e32 v17, 0xffff0000, v223
	v_lshlrev_b32_e32 v18, 16, v23
	v_and_b32_e32 v19, 0xffff0000, v23
	v_pk_fma_f32 v[4:5], v[4:5], v[14:15], v[16:17]
	v_mul_f32_e32 v18, v4, v18
	v_mul_f32_e32 v19, v5, v19
	v_cvt_pk_bf16_f32 v18, v18, v19
	global_store_dword v3, v18, s[18:19]
	s_add_u32 s18, s18, 0x1800
	s_addc_u32 s19, s19, 0
	global_load_dword v23, v3, s[14:15] nt
	s_add_u32 s14, s14, 0x1000
	s_addc_u32 s15, s15, 0
	s_waitcnt vmcnt(33)
	v_lshlrev_b32_e32 v8, 16, v224
	v_lshlrev_b32_e32 v9, 16, v225
	v_exp_f32_e32 v8, v8
	v_exp_f32_e32 v9, v9
	v_and_b32_e32 v10, 0xffff0000, v224
	v_and_b32_e32 v11, 0xffff0000, v225
	v_lshlrev_b32_e32 v12, 16, v24
	v_and_b32_e32 v13, 0xffff0000, v24
	v_pk_fma_f32 v[4:5], v[4:5], v[8:9], v[10:11]
	v_mul_f32_e32 v12, v4, v12
	v_mul_f32_e32 v13, v5, v13
	v_cvt_pk_bf16_f32 v12, v12, v13
	global_store_dword v3, v12, s[18:19]
	s_add_u32 s18, s18, 0x1800
	s_addc_u32 s19, s19, 0
	global_load_dword v24, v3, s[14:15] nt
	s_add_u32 s14, s14, 0x1000
	s_addc_u32 s15, s15, 0
	s_waitcnt vmcnt(32)
	v_lshlrev_b32_e32 v14, 16, v226
	v_lshlrev_b32_e32 v15, 16, v227
	v_exp_f32_e32 v14, v14
	v_exp_f32_e32 v15, v15
	v_and_b32_e32 v16, 0xffff0000, v226
	v_and_b32_e32 v17, 0xffff0000, v227
	v_lshlrev_b32_e32 v18, 16, v25
	v_and_b32_e32 v19, 0xffff0000, v25
	v_pk_fma_f32 v[4:5], v[4:5], v[14:15], v[16:17]
	v_mul_f32_e32 v18, v4, v18
	v_mul_f32_e32 v19, v5, v19
	v_cvt_pk_bf16_f32 v18, v18, v19
	global_store_dword v3, v18, s[18:19]
	s_add_u32 s18, s18, 0x1800
	s_addc_u32 s19, s19, 0
	global_load_dword v25, v3, s[14:15] nt
	s_add_u32 s14, s14, 0x1000
	s_addc_u32 s15, s15, 0
	s_waitcnt vmcnt(31)
	v_lshlrev_b32_e32 v8, 16, v228
	v_lshlrev_b32_e32 v9, 16, v229
	v_exp_f32_e32 v8, v8
	v_exp_f32_e32 v9, v9
	v_and_b32_e32 v10, 0xffff0000, v228
	v_and_b32_e32 v11, 0xffff0000, v229
	v_lshlrev_b32_e32 v12, 16, v26
	v_and_b32_e32 v13, 0xffff0000, v26
	v_pk_fma_f32 v[4:5], v[4:5], v[8:9], v[10:11]
	v_mul_f32_e32 v12, v4, v12
	v_mul_f32_e32 v13, v5, v13
	v_cvt_pk_bf16_f32 v12, v12, v13
	global_store_dword v3, v12, s[18:19]
	s_add_u32 s18, s18, 0x1800
	s_addc_u32 s19, s19, 0
	global_load_dword v26, v3, s[14:15] nt
	s_add_u32 s14, s14, 0x1000
	s_addc_u32 s15, s15, 0
	s_waitcnt vmcnt(30)
	v_lshlrev_b32_e32 v14, 16, v230
	v_lshlrev_b32_e32 v15, 16, v231
	v_exp_f32_e32 v14, v14
	v_exp_f32_e32 v15, v15
	v_and_b32_e32 v16, 0xffff0000, v230
	v_and_b32_e32 v17, 0xffff0000, v231
	v_lshlrev_b32_e32 v18, 16, v27
	v_and_b32_e32 v19, 0xffff0000, v27
	v_pk_fma_f32 v[4:5], v[4:5], v[14:15], v[16:17]
	v_mul_f32_e32 v18, v4, v18
	v_mul_f32_e32 v19, v5, v19
	v_cvt_pk_bf16_f32 v18, v18, v19
	global_store_dword v3, v18, s[18:19]
	s_add_u32 s18, s18, 0x1800
	s_addc_u32 s19, s19, 0
	global_load_dword v27, v3, s[14:15] nt
	s_add_u32 s14, s14, 0x1000
	s_addc_u32 s15, s15, 0
	s_waitcnt vmcnt(30)
	v_lshlrev_b32_e32 v8, 16, v64
	v_lshlrev_b32_e32 v9, 16, v65
	v_exp_f32_e32 v8, v8
	v_exp_f32_e32 v9, v9
	v_and_b32_e32 v10, 0xffff0000, v64
	v_and_b32_e32 v11, 0xffff0000, v65
	v_lshlrev_b32_e32 v12, 16, v28
	v_and_b32_e32 v13, 0xffff0000, v28
	v_pk_fma_f32 v[4:5], v[4:5], v[8:9], v[10:11]
	v_mul_f32_e32 v12, v4, v12
	v_mul_f32_e32 v13, v5, v13
	v_cvt_pk_bf16_f32 v12, v12, v13
	global_store_dword v3, v12, s[18:19]
	s_add_u32 s18, s18, 0x1800
	s_addc_u32 s19, s19, 0
	global_load_dword v28, v3, s[14:15] nt
	s_add_u32 s14, s14, 0x1000
	s_addc_u32 s15, s15, 0
	s_waitcnt vmcnt(30)
; __device__ __forceinline__ unsigned cvt_pk_bf16(float lo, float hi) { unsigned r; asm volatile("v_cvt_pk_bf16_f32 %0, %1, %2" : "=v"(r) : "v"(lo), "v"(hi)); return r; }
; __device__ __forceinline__ float bf_lo(unsigned w) { return __uint_as_float(w << 16); }
; __device__ __forceinline__ float bf_hi(unsigned w) { return __uint_as_float(w & 0xffff0000u); }
; __global__ void __launch_bounds__(NTHR, 2) hybrid_block_fwd(Args a) {
;     ...
;         for (int i = 0; i < CH_L; ++i) {
;             const u32x2 q = pab[(size_t)i * (LW / 2)]; const f32x2 av = (f32x2){__builtin_amdgcn_exp2f(bf_lo(q.x)), __builtin_amdgcn_exp2f(bf_lo(q.y))}, bv = (f32x2){bf_hi(q.x), bf_hi(q.y)}; const unsigned gq = pg[(size_t)i * (LW / 2)];
;             H = av * H + bv;
;             po[(size_t)i * (KC / 2)] = cvt_pk_bf16(H.x * bf_lo(gq), H.y * bf_hi(gq));
;         }
	v_lshlrev_b32_e32 v14, 16, v66
	v_lshlrev_b32_e32 v15, 16, v67
	v_exp_f32_e32 v14, v14
	v_exp_f32_e32 v15, v15
	v_and_b32_e32 v16, 0xffff0000, v66
	v_and_b32_e32 v17, 0xffff0000, v67
	v_lshlrev_b32_e32 v18, 16, v29
	v_and_b32_e32 v19, 0xffff0000, v29
	v_pk_fma_f32 v[4:5], v[4:5], v[14:15], v[16:17]
	v_mul_f32_e32 v18, v4, v18
	v_mul_f32_e32 v19, v5, v19
	v_cvt_pk_bf16_f32 v18, v18, v19
	global_store_dword v3, v18, s[18:19]
	s_add_u32 s18, s18, 0x1800
	s_addc_u32 s19, s19, 0
	global_load_dword v29, v3, s[14:15] nt
	s_add_u32 s14, s14, 0x1000
	s_addc_u32 s15, s15, 0
	s_waitcnt vmcnt(30)
	v_lshlrev_b32_e32 v8, 16, v68
	v_lshlrev_b32_e32 v9, 16, v69
	v_exp_f32_e32 v8, v8
	v_exp_f32_e32 v9, v9
	v_and_b32_e32 v10, 0xffff0000, v68
	v_and_b32_e32 v11, 0xffff0000, v69
	v_lshlrev_b32_e32 v12, 16, v30
	v_and_b32_e32 v13, 0xffff0000, v30
	v_pk_fma_f32 v[4:5], v[4:5], v[8:9], v[10:11]
	v_mul_f32_e32 v12, v4, v12
	v_mul_f32_e32 v13, v5, v13
	v_cvt_pk_bf16_f32 v12, v12, v13
	global_store_dword v3, v12, s[18:19]
	s_add_u32 s18, s18, 0x1800
	s_addc_u32 s19, s19, 0
	global_load_dword v30, v3, s[14:15] nt
	s_add_u32 s14, s14, 0x1000
	s_addc_u32 s15, s15, 0
	s_waitcnt vmcnt(30)
	v_lshlrev_b32_e32 v14, 16, v70
	v_lshlrev_b32_e32 v15, 16, v71
	v_exp_f32_e32 v14, v14
	v_exp_f32_e32 v15, v15
	v_and_b32_e32 v16, 0xffff0000, v70
	v_and_b32_e32 v17, 0xffff0000, v71
	v_lshlrev_b32_e32 v18, 16, v31
	v_and_b32_e32 v19, 0xffff0000, v31
	v_pk_fma_f32 v[4:5], v[4:5], v[14:15], v[16:17]
	v_mul_f32_e32 v18, v4, v18
	v_mul_f32_e32 v19, v5, v19
	v_cvt_pk_bf16_f32 v18, v18, v19
	global_store_dword v3, v18, s[18:19]
	s_add_u32 s18, s18, 0x1800
	s_addc_u32 s19, s19, 0
	global_load_dword v31, v3, s[14:15] nt
	s_add_u32 s14, s14, 0x1000
	s_addc_u32 s15, s15, 0
	s_waitcnt vmcnt(30)
	v_lshlrev_b32_e32 v8, 16, v72
	v_lshlrev_b32_e32 v9, 16, v73
	v_exp_f32_e32 v8, v8
	v_exp_f32_e32 v9, v9
	v_and_b32_e32 v10, 0xffff0000, v72
	v_and_b32_e32 v11, 0xffff0000, v73
	v_lshlrev_b32_e32 v12, 16, v32
	v_and_b32_e32 v13, 0xffff0000, v32
	v_pk_fma_f32 v[4:5], v[4:5], v[8:9], v[10:11]
	v_mul_f32_e32 v12, v4, v12
	v_mul_f32_e32 v13, v5, v13
	v_cvt_pk_bf16_f32 v12, v12, v13
	global_store_dword v3, v12, s[18:19]
	s_add_u32 s18, s18, 0x1800
	s_addc_u32 s19, s19, 0
	global_load_dword v32, v3, s[14:15] nt
	s_add_u32 s14, s14, 0x1000
	s_addc_u32 s15, s15, 0
	s_waitcnt vmcnt(30)
	v_lshlrev_b32_e32 v14, 16, v74
	v_lshlrev_b32_e32 v15, 16, v75
	v_exp_f32_e32 v14, v14
	v_exp_f32_e32 v15, v15
	v_and_b32_e32 v16, 0xffff0000, v74
	v_and_b32_e32 v17, 0xffff0000, v75
	v_lshlrev_b32_e32 v18, 16, v33
	v_and_b32_e32 v19, 0xffff0000, v33
	v_pk_fma_f32 v[4:5], v[4:5], v[14:15], v[16:17]
	v_mul_f32_e32 v18, v4, v18
	v_mul_f32_e32 v19, v5, v19
	v_cvt_pk_bf16_f32 v18, v18, v19
	global_store_dword v3, v18, s[18:19]
	s_add_u32 s18, s18, 0x1800
	s_addc_u32 s19, s19, 0
	global_load_dword v33, v3, s[14:15] nt
	s_add_u32 s14, s14, 0x1000
	s_addc_u32 s15, s15, 0
	s_waitcnt vmcnt(30)
	v_lshlrev_b32_e32 v8, 16, v76
	v_lshlrev_b32_e32 v9, 16, v77
	v_exp_f32_e32 v8, v8
	v_exp_f32_e32 v9, v9
	v_and_b32_e32 v10, 0xffff0000, v76
	v_and_b32_e32 v11, 0xffff0000, v77
	v_lshlrev_b32_e32 v12, 16, v34
	v_and_b32_e32 v13, 0xffff0000, v34
	v_pk_fma_f32 v[4:5], v[4:5], v[8:9], v[10:11]
	v_mul_f32_e32 v12, v4, v12
	v_mul_f32_e32 v13, v5, v13
	v_cvt_pk_bf16_f32 v12, v12, v13
	global_store_dword v3, v12, s[18:19]
	s_add_u32 s18, s18, 0x1800
	s_addc_u32 s19, s19, 0
	global_load_dword v34, v3, s[14:15] nt
	s_add_u32 s14, s14, 0x1000
	s_addc_u32 s15, s15, 0
	s_waitcnt vmcnt(30)
	v_lshlrev_b32_e32 v14, 16, v78
	v_lshlrev_b32_e32 v15, 16, v79
	v_exp_f32_e32 v14, v14
	v_exp_f32_e32 v15, v15
	v_and_b32_e32 v16, 0xffff0000, v78
	v_and_b32_e32 v17, 0xffff0000, v79
	v_lshlrev_b32_e32 v18, 16, v35
	v_and_b32_e32 v19, 0xffff0000, v35
	v_pk_fma_f32 v[4:5], v[4:5], v[14:15], v[16:17]
	v_mul_f32_e32 v18, v4, v18
	v_mul_f32_e32 v19, v5, v19
	v_cvt_pk_bf16_f32 v18, v18, v19
	global_store_dword v3, v18, s[18:19]
	s_add_u32 s18, s18, 0x1800
	s_addc_u32 s19, s19, 0
	global_load_dword v35, v3, s[14:15] nt
	s_add_u32 s14, s14, 0x1000
	s_addc_u32 s15, s15, 0
	s_waitcnt vmcnt(30)
	v_lshlrev_b32_e32 v8, 16, v80
	v_lshlrev_b32_e32 v9, 16, v81
	v_exp_f32_e32 v8, v8
	v_exp_f32_e32 v9, v9
	v_and_b32_e32 v10, 0xffff0000, v80
	v_and_b32_e32 v11, 0xffff0000, v81
	v_lshlrev_b32_e32 v12, 16, v20
	v_and_b32_e32 v13, 0xffff0000, v20
	v_pk_fma_f32 v[4:5], v[4:5], v[8:9], v[10:11]
	v_mul_f32_e32 v12, v4, v12
	v_mul_f32_e32 v13, v5, v13
	v_cvt_pk_bf16_f32 v12, v12, v13
	global_store_dword v3, v12, s[18:19]
	s_add_u32 s18, s18, 0x1800
	s_addc_u32 s19, s19, 0
	global_load_dword v20, v3, s[14:15] nt
	s_add_u32 s14, s14, 0x1000
	s_addc_u32 s15, s15, 0
	s_waitcnt vmcnt(30)
	v_lshlrev_b32_e32 v14, 16, v82
	v_lshlrev_b32_e32 v15, 16, v83
	v_exp_f32_e32 v14, v14
	v_exp_f32_e32 v15, v15
	v_and_b32_e32 v16, 0xffff0000, v82
	v_and_b32_e32 v17, 0xffff0000, v83
	v_lshlrev_b32_e32 v18, 16, v21
	v_and_b32_e32 v19, 0xffff0000, v21
	v_pk_fma_f32 v[4:5], v[4:5], v[14:15], v[16:17]
	v_mul_f32_e32 v18, v4, v18
	v_mul_f32_e32 v19, v5, v19
	v_cvt_pk_bf16_f32 v18, v18, v19
	global_store_dword v3, v18, s[18:19]
	s_add_u32 s18, s18, 0x1800
	s_addc_u32 s19, s19, 0
	global_load_dword v21, v3, s[14:15] nt
	s_add_u32 s14, s14, 0x1000
	s_addc_u32 s15, s15, 0
	s_waitcnt vmcnt(30)
	v_lshlrev_b32_e32 v8, 16, v84
	v_lshlrev_b32_e32 v9, 16, v85
	v_exp_f32_e32 v8, v8
	v_exp_f32_e32 v9, v9
	v_and_b32_e32 v10, 0xffff0000, v84
	v_and_b32_e32 v11, 0xffff0000, v85
	v_lshlrev_b32_e32 v12, 16, v22
	v_and_b32_e32 v13, 0xffff0000, v22
	v_pk_fma_f32 v[4:5], v[4:5], v[8:9], v[10:11]
	v_mul_f32_e32 v12, v4, v12
	v_mul_f32_e32 v13, v5, v13
	v_cvt_pk_bf16_f32 v12, v12, v13
	global_store_dword v3, v12, s[18:19]
	s_add_u32 s18, s18, 0x1800
	s_addc_u32 s19, s19, 0
	global_load_dword v22, v3, s[14:15] nt
	s_add_u32 s14, s14, 0x1000
	s_addc_u32 s15, s15, 0
	s_waitcnt vmcnt(30)
; __device__ __forceinline__ unsigned cvt_pk_bf16(float lo, float hi) { unsigned r; asm volatile("v_cvt_pk_bf16_f32 %0, %1, %2" : "=v"(r) : "v"(lo), "v"(hi)); return r; }
; __device__ __forceinline__ float bf_lo(unsigned w) { return __uint_as_float(w << 16); }
; __device__ __forceinline__ float bf_hi(unsigned w) { return __uint_as_float(w & 0xffff0000u); }
; __global__ void __launch_bounds__(NTHR, 2) hybrid_block_fwd(Args a) {
;     ...
;         for (int i = 0; i < CH_L; ++i) {
;             const u32x2 q = pab[(size_t)i * (LW / 2)]; const f32x2 av = (f32x2){__builtin_amdgcn_exp2f(bf_lo(q.x)), __builtin_amdgcn_exp2f(bf_lo(q.y))}, bv = (f32x2){bf_hi(q.x), bf_hi(q.y)}; const unsigned gq = pg[(size_t)i * (LW / 2)];
;             H = av * H + bv;
;             po[(size_t)i * (KC / 2)] = cvt_pk_bf16(H.x * bf_lo(gq), H.y * bf_hi(gq));
;         }
	v_lshlrev_b32_e32 v14, 16, v86
	v_lshlrev_b32_e32 v15, 16, v87
	v_exp_f32_e32 v14, v14
	v_exp_f32_e32 v15, v15
	v_and_b32_e32 v16, 0xffff0000, v86
	v_and_b32_e32 v17, 0xffff0000, v87
	v_lshlrev_b32_e32 v18, 16, v23
	v_and_b32_e32 v19, 0xffff0000, v23
	v_pk_fma_f32 v[4:5], v[4:5], v[14:15], v[16:17]
	v_mul_f32_e32 v18, v4, v18
	v_mul_f32_e32 v19, v5, v19
	v_cvt_pk_bf16_f32 v18, v18, v19
	global_store_dword v3, v18, s[18:19]
	s_add_u32 s18, s18, 0x1800
	s_addc_u32 s19, s19, 0
	global_load_dword v23, v3, s[14:15] nt
	s_add_u32 s14, s14, 0x1000
	s_addc_u32 s15, s15, 0
	s_waitcnt vmcnt(30)
	v_lshlrev_b32_e32 v8, 16, v88
	v_lshlrev_b32_e32 v9, 16, v89
	v_exp_f32_e32 v8, v8
	v_exp_f32_e32 v9, v9
	v_and_b32_e32 v10, 0xffff0000, v88
	v_and_b32_e32 v11, 0xffff0000, v89
	v_lshlrev_b32_e32 v12, 16, v24
	v_and_b32_e32 v13, 0xffff0000, v24
	v_pk_fma_f32 v[4:5], v[4:5], v[8:9], v[10:11]
	v_mul_f32_e32 v12, v4, v12
	v_mul_f32_e32 v13, v5, v13
	v_cvt_pk_bf16_f32 v12, v12, v13
	global_store_dword v3, v12, s[18:19]
	s_add_u32 s18, s18, 0x1800
	s_addc_u32 s19, s19, 0
	global_load_dword v24, v3, s[14:15] nt
	s_add_u32 s14, s14, 0x1000
	s_addc_u32 s15, s15, 0
	s_waitcnt vmcnt(30)
	v_lshlrev_b32_e32 v14, 16, v90
	v_lshlrev_b32_e32 v15, 16, v91
	v_exp_f32_e32 v14, v14
	v_exp_f32_e32 v15, v15
	v_and_b32_e32 v16, 0xffff0000, v90
	v_and_b32_e32 v17, 0xffff0000, v91
	v_lshlrev_b32_e32 v18, 16, v25
	v_and_b32_e32 v19, 0xffff0000, v25
	v_pk_fma_f32 v[4:5], v[4:5], v[14:15], v[16:17]
	v_mul_f32_e32 v18, v4, v18
	v_mul_f32_e32 v19, v5, v19
	v_cvt_pk_bf16_f32 v18, v18, v19
	global_store_dword v3, v18, s[18:19]
	s_add_u32 s18, s18, 0x1800
	s_addc_u32 s19, s19, 0
	global_load_dword v25, v3, s[14:15] nt
	s_add_u32 s14, s14, 0x1000
	s_addc_u32 s15, s15, 0
	s_waitcnt vmcnt(30)
	v_lshlrev_b32_e32 v8, 16, v92
	v_lshlrev_b32_e32 v9, 16, v93
	v_exp_f32_e32 v8, v8
	v_exp_f32_e32 v9, v9
	v_and_b32_e32 v10, 0xffff0000, v92
	v_and_b32_e32 v11, 0xffff0000, v93
	v_lshlrev_b32_e32 v12, 16, v26
	v_and_b32_e32 v13, 0xffff0000, v26
	v_pk_fma_f32 v[4:5], v[4:5], v[8:9], v[10:11]
	v_mul_f32_e32 v12, v4, v12
	v_mul_f32_e32 v13, v5, v13
	v_cvt_pk_bf16_f32 v12, v12, v13
	global_store_dword v3, v12, s[18:19]
	s_add_u32 s18, s18, 0x1800
	s_addc_u32 s19, s19, 0
	global_load_dword v26, v3, s[14:15] nt
	s_add_u32 s14, s14, 0x1000
	s_addc_u32 s15, s15, 0
	s_waitcnt vmcnt(30)
	v_lshlrev_b32_e32 v14, 16, v94
	v_lshlrev_b32_e32 v15, 16, v95
	v_exp_f32_e32 v14, v14
	v_exp_f32_e32 v15, v15
	v_and_b32_e32 v16, 0xffff0000, v94
	v_and_b32_e32 v17, 0xffff0000, v95
	v_lshlrev_b32_e32 v18, 16, v27
	v_and_b32_e32 v19, 0xffff0000, v27
	v_pk_fma_f32 v[4:5], v[4:5], v[14:15], v[16:17]
	v_mul_f32_e32 v18, v4, v18
	v_mul_f32_e32 v19, v5, v19
	v_cvt_pk_bf16_f32 v18, v18, v19
	global_store_dword v3, v18, s[18:19]
	s_add_u32 s18, s18, 0x1800
	s_addc_u32 s19, s19, 0
	global_load_dword v27, v3, s[14:15] nt
	s_add_u32 s14, s14, 0x1000
	s_addc_u32 s15, s15, 0
	s_waitcnt vmcnt(30)
	v_lshlrev_b32_e32 v8, 16, v96
	v_lshlrev_b32_e32 v9, 16, v97
	v_exp_f32_e32 v8, v8
	v_exp_f32_e32 v9, v9
	v_and_b32_e32 v10, 0xffff0000, v96
	v_and_b32_e32 v11, 0xffff0000, v97
	v_lshlrev_b32_e32 v12, 16, v28
	v_and_b32_e32 v13, 0xffff0000, v28
	v_pk_fma_f32 v[4:5], v[4:5], v[8:9], v[10:11]
	v_mul_f32_e32 v12, v4, v12
	v_mul_f32_e32 v13, v5, v13
	v_cvt_pk_bf16_f32 v12, v12, v13
	global_store_dword v3, v12, s[18:19]
	s_add_u32 s18, s18, 0x1800
	s_addc_u32 s19, s19, 0
	global_load_dword v28, v3, s[14:15] nt
	s_add_u32 s14, s14, 0x1000
	s_addc_u32 s15, s15, 0
	s_waitcnt vmcnt(30)
	v_lshlrev_b32_e32 v14, 16, v98
	v_lshlrev_b32_e32 v15, 16, v99
	v_exp_f32_e32 v14, v14
	v_exp_f32_e32 v15, v15
	v_and_b32_e32 v16, 0xffff0000, v98
	v_and_b32_e32 v17, 0xffff0000, v99
	v_lshlrev_b32_e32 v18, 16, v29
	v_and_b32_e32 v19, 0xffff0000, v29
	v_pk_fma_f32 v[4:5], v[4:5], v[14:15], v[16:17]
	v_mul_f32_e32 v18, v4, v18
	v_mul_f32_e32 v19, v5, v19
	v_cvt_pk_bf16_f32 v18, v18, v19
	global_store_dword v3, v18, s[18:19]
	s_add_u32 s18, s18, 0x1800
	s_addc_u32 s19, s19, 0
	global_load_dword v29, v3, s[14:15] nt
	s_add_u32 s14, s14, 0x1000
	s_addc_u32 s15, s15, 0
	s_waitcnt vmcnt(30)
	v_lshlrev_b32_e32 v8, 16, v100
	v_lshlrev_b32_e32 v9, 16, v101
	v_exp_f32_e32 v8, v8
	v_exp_f32_e32 v9, v9
	v_and_b32_e32 v10, 0xffff0000, v100
	v_and_b32_e32 v11, 0xffff0000, v101
	v_lshlrev_b32_e32 v12, 16, v30
	v_and_b32_e32 v13, 0xffff0000, v30
	v_pk_fma_f32 v[4:5], v[4:5], v[8:9], v[10:11]
	v_mul_f32_e32 v12, v4, v12
	v_mul_f32_e32 v13, v5, v13
	v_cvt_pk_bf16_f32 v12, v12, v13
	global_store_dword v3, v12, s[18:19]
	s_add_u32 s18, s18, 0x1800
	s_addc_u32 s19, s19, 0
	global_load_dword v30, v3, s[14:15] nt
	s_add_u32 s14, s14, 0x1000
	s_addc_u32 s15, s15, 0
	s_waitcnt vmcnt(30)
	v_lshlrev_b32_e32 v14, 16, v102
	v_lshlrev_b32_e32 v15, 16, v103
	v_exp_f32_e32 v14, v14
	v_exp_f32_e32 v15, v15
	v_and_b32_e32 v16, 0xffff0000, v102
	v_and_b32_e32 v17, 0xffff0000, v103
	v_lshlrev_b32_e32 v18, 16, v31
	v_and_b32_e32 v19, 0xffff0000, v31
	v_pk_fma_f32 v[4:5], v[4:5], v[14:15], v[16:17]
	v_mul_f32_e32 v18, v4, v18
	v_mul_f32_e32 v19, v5, v19
	v_cvt_pk_bf16_f32 v18, v18, v19
	global_store_dword v3, v18, s[18:19]
	s_add_u32 s18, s18, 0x1800
	s_addc_u32 s19, s19, 0
	global_load_dword v31, v3, s[14:15] nt
	s_add_u32 s14, s14, 0x1000
	s_addc_u32 s15, s15, 0
	s_waitcnt vmcnt(30)
	v_lshlrev_b32_e32 v8, 16, v104
	v_lshlrev_b32_e32 v9, 16, v105
	v_exp_f32_e32 v8, v8
	v_exp_f32_e32 v9, v9
	v_and_b32_e32 v10, 0xffff0000, v104
	v_and_b32_e32 v11, 0xffff0000, v105
	v_lshlrev_b32_e32 v12, 16, v32
	v_and_b32_e32 v13, 0xffff0000, v32
	v_pk_fma_f32 v[4:5], v[4:5], v[8:9], v[10:11]
	v_mul_f32_e32 v12, v4, v12
	v_mul_f32_e32 v13, v5, v13
	v_cvt_pk_bf16_f32 v12, v12, v13
	global_store_dword v3, v12, s[18:19]
	s_add_u32 s18, s18, 0x1800
	s_addc_u32 s19, s19, 0
	global_load_dword v32, v3, s[14:15] nt
	s_add_u32 s14, s14, 0x1000
	s_addc_u32 s15, s15, 0
	s_waitcnt vmcnt(30)
; __device__ __forceinline__ unsigned cvt_pk_bf16(float lo, float hi) { unsigned r; asm volatile("v_cvt_pk_bf16_f32 %0, %1, %2" : "=v"(r) : "v"(lo), "v"(hi)); return r; }
; __device__ __forceinline__ float bf_lo(unsigned w) { return __uint_as_float(w << 16); }
; __device__ __forceinline__ float bf_hi(unsigned w) { return __uint_as_float(w & 0xffff0000u); }
; __global__ void __launch_bounds__(NTHR, 2) hybrid_block_fwd(Args a) {
;     ...
;         for (int i = 0; i < CH_L; ++i) {
;             const u32x2 q = pab[(size_t)i * (LW / 2)]; const f32x2 av = (f32x2){__builtin_amdgcn_exp2f(bf_lo(q.x)), __builtin_amdgcn_exp2f(bf_lo(q.y))}, bv = (f32x2){bf_hi(q.x), bf_hi(q.y)}; const unsigned gq = pg[(size_t)i * (LW / 2)];
;             H = av * H + bv;
;             po[(size_t)i * (KC / 2)] = cvt_pk_bf16(H.x * bf_lo(gq), H.y * bf_hi(gq));
;         }
	v_lshlrev_b32_e32 v14, 16, v106
	v_lshlrev_b32_e32 v15, 16, v107
	v_exp_f32_e32 v14, v14
	v_exp_f32_e32 v15, v15
	v_and_b32_e32 v16, 0xffff0000, v106
	v_and_b32_e32 v17, 0xffff0000, v107
	v_lshlrev_b32_e32 v18, 16, v33
	v_and_b32_e32 v19, 0xffff0000, v33
	v_pk_fma_f32 v[4:5], v[4:5], v[14:15], v[16:17]
	v_mul_f32_e32 v18, v4, v18
	v_mul_f32_e32 v19, v5, v19
	v_cvt_pk_bf16_f32 v18, v18, v19
	global_store_dword v3, v18, s[18:19]
	s_add_u32 s18, s18, 0x1800
	s_addc_u32 s19, s19, 0
	global_load_dword v33, v3, s[14:15] nt
	s_add_u32 s14, s14, 0x1000
	s_addc_u32 s15, s15, 0
	s_waitcnt vmcnt(30)
	v_lshlrev_b32_e32 v8, 16, v108
	v_lshlrev_b32_e32 v9, 16, v109
	v_exp_f32_e32 v8, v8
	v_exp_f32_e32 v9, v9
	v_and_b32_e32 v10, 0xffff0000, v108
	v_and_b32_e32 v11, 0xffff0000, v109
	v_lshlrev_b32_e32 v12, 16, v34
	v_and_b32_e32 v13, 0xffff0000, v34
	v_pk_fma_f32 v[4:5], v[4:5], v[8:9], v[10:11]
	v_mul_f32_e32 v12, v4, v12
	v_mul_f32_e32 v13, v5, v13
	v_cvt_pk_bf16_f32 v12, v12, v13
	global_store_dword v3, v12, s[18:19]
	s_add_u32 s18, s18, 0x1800
	s_addc_u32 s19, s19, 0
	global_load_dword v34, v3, s[14:15] nt
	s_add_u32 s14, s14, 0x1000
	s_addc_u32 s15, s15, 0
	s_waitcnt vmcnt(30)
	v_lshlrev_b32_e32 v14, 16, v110
	v_lshlrev_b32_e32 v15, 16, v111
	v_exp_f32_e32 v14, v14
	v_exp_f32_e32 v15, v15
	v_and_b32_e32 v16, 0xffff0000, v110
	v_and_b32_e32 v17, 0xffff0000, v111
	v_lshlrev_b32_e32 v18, 16, v35
	v_and_b32_e32 v19, 0xffff0000, v35
	v_pk_fma_f32 v[4:5], v[4:5], v[14:15], v[16:17]
	v_mul_f32_e32 v18, v4, v18
	v_mul_f32_e32 v19, v5, v19
	v_cvt_pk_bf16_f32 v18, v18, v19
	global_store_dword v3, v18, s[18:19]
	s_add_u32 s18, s18, 0x1800
	s_addc_u32 s19, s19, 0
	global_load_dword v35, v3, s[14:15] nt
	s_add_u32 s14, s14, 0x1000
	s_addc_u32 s15, s15, 0
	s_waitcnt vmcnt(30)
	v_lshlrev_b32_e32 v8, 16, v112
	v_lshlrev_b32_e32 v9, 16, v113
	v_exp_f32_e32 v8, v8
	v_exp_f32_e32 v9, v9
	v_and_b32_e32 v10, 0xffff0000, v112
	v_and_b32_e32 v11, 0xffff0000, v113
	v_lshlrev_b32_e32 v12, 16, v20
	v_and_b32_e32 v13, 0xffff0000, v20
	v_pk_fma_f32 v[4:5], v[4:5], v[8:9], v[10:11]
	v_mul_f32_e32 v12, v4, v12
	v_mul_f32_e32 v13, v5, v13
	v_cvt_pk_bf16_f32 v12, v12, v13
	global_store_dword v3, v12, s[18:19]
	s_add_u32 s18, s18, 0x1800
	s_addc_u32 s19, s19, 0
	global_load_dword v20, v3, s[14:15] nt
	s_add_u32 s14, s14, 0x1000
	s_addc_u32 s15, s15, 0
	s_waitcnt vmcnt(30)
	v_lshlrev_b32_e32 v14, 16, v114
	v_lshlrev_b32_e32 v15, 16, v115
	v_exp_f32_e32 v14, v14
	v_exp_f32_e32 v15, v15
	v_and_b32_e32 v16, 0xffff0000, v114
	v_and_b32_e32 v17, 0xffff0000, v115
	v_lshlrev_b32_e32 v18, 16, v21
	v_and_b32_e32 v19, 0xffff0000, v21
	v_pk_fma_f32 v[4:5], v[4:5], v[14:15], v[16:17]
	v_mul_f32_e32 v18, v4, v18
	v_mul_f32_e32 v19, v5, v19
	v_cvt_pk_bf16_f32 v18, v18, v19
	global_store_dword v3, v18, s[18:19]
	s_add_u32 s18, s18, 0x1800
	s_addc_u32 s19, s19, 0
	global_load_dword v21, v3, s[14:15] nt
	s_add_u32 s14, s14, 0x1000
	s_addc_u32 s15, s15, 0
	s_waitcnt vmcnt(30)
	v_lshlrev_b32_e32 v8, 16, v116
	v_lshlrev_b32_e32 v9, 16, v117
	v_exp_f32_e32 v8, v8
	v_exp_f32_e32 v9, v9
	v_and_b32_e32 v10, 0xffff0000, v116
	v_and_b32_e32 v11, 0xffff0000, v117
	v_lshlrev_b32_e32 v12, 16, v22
	v_and_b32_e32 v13, 0xffff0000, v22
	v_pk_fma_f32 v[4:5], v[4:5], v[8:9], v[10:11]
	v_mul_f32_e32 v12, v4, v12
	v_mul_f32_e32 v13, v5, v13
	v_cvt_pk_bf16_f32 v12, v12, v13
	global_store_dword v3, v12, s[18:19]
	s_add_u32 s18, s18, 0x1800
	s_addc_u32 s19, s19, 0
	global_load_dword v22, v3, s[14:15] nt
	s_add_u32 s14, s14, 0x1000
	s_addc_u32 s15, s15, 0
	s_waitcnt vmcnt(30)
	v_lshlrev_b32_e32 v14, 16, v118
	v_lshlrev_b32_e32 v15, 16, v119
	v_exp_f32_e32 v14, v14
	v_exp_f32_e32 v15, v15
	v_and_b32_e32 v16, 0xffff0000, v118
	v_and_b32_e32 v17, 0xffff0000, v119
	v_lshlrev_b32_e32 v18, 16, v23
	v_and_b32_e32 v19, 0xffff0000, v23
	v_pk_fma_f32 v[4:5], v[4:5], v[14:15], v[16:17]
	v_mul_f32_e32 v18, v4, v18
	v_mul_f32_e32 v19, v5, v19
	v_cvt_pk_bf16_f32 v18, v18, v19
	global_store_dword v3, v18, s[18:19]
	s_add_u32 s18, s18, 0x1800
	s_addc_u32 s19, s19, 0
	global_load_dword v23, v3, s[14:15] nt
	s_add_u32 s14, s14, 0x1000
	s_addc_u32 s15, s15, 0
	s_waitcnt vmcnt(30)
	v_lshlrev_b32_e32 v8, 16, v120
	v_lshlrev_b32_e32 v9, 16, v121
	v_exp_f32_e32 v8, v8
	v_exp_f32_e32 v9, v9
	v_and_b32_e32 v10, 0xffff0000, v120
	v_and_b32_e32 v11, 0xffff0000, v121
	v_lshlrev_b32_e32 v12, 16, v24
	v_and_b32_e32 v13, 0xffff0000, v24
	v_pk_fma_f32 v[4:5], v[4:5], v[8:9], v[10:11]
	v_mul_f32_e32 v12, v4, v12
	v_mul_f32_e32 v13, v5, v13
	v_cvt_pk_bf16_f32 v12, v12, v13
	global_store_dword v3, v12, s[18:19]
	s_add_u32 s18, s18, 0x1800
	s_addc_u32 s19, s19, 0
	global_load_dword v24, v3, s[14:15] nt
	s_add_u32 s14, s14, 0x1000
	s_addc_u32 s15, s15, 0
	s_waitcnt vmcnt(30)
	v_lshlrev_b32_e32 v14, 16, v122
	v_lshlrev_b32_e32 v15, 16, v123
	v_exp_f32_e32 v14, v14
	v_exp_f32_e32 v15, v15
	v_and_b32_e32 v16, 0xffff0000, v122
	v_and_b32_e32 v17, 0xffff0000, v123
	v_lshlrev_b32_e32 v18, 16, v25
	v_and_b32_e32 v19, 0xffff0000, v25
	v_pk_fma_f32 v[4:5], v[4:5], v[14:15], v[16:17]
	v_mul_f32_e32 v18, v4, v18
	v_mul_f32_e32 v19, v5, v19
	v_cvt_pk_bf16_f32 v18, v18, v19
	global_store_dword v3, v18, s[18:19]
	s_add_u32 s18, s18, 0x1800
	s_addc_u32 s19, s19, 0
	global_load_dword v25, v3, s[14:15] nt
	s_add_u32 s14, s14, 0x1000
	s_addc_u32 s15, s15, 0
	s_waitcnt vmcnt(30)
	v_lshlrev_b32_e32 v8, 16, v124
	v_lshlrev_b32_e32 v9, 16, v125
	v_exp_f32_e32 v8, v8
	v_exp_f32_e32 v9, v9
	v_and_b32_e32 v10, 0xffff0000, v124
	v_and_b32_e32 v11, 0xffff0000, v125
	v_lshlrev_b32_e32 v12, 16, v26
	v_and_b32_e32 v13, 0xffff0000, v26
	v_pk_fma_f32 v[4:5], v[4:5], v[8:9], v[10:11]
	v_mul_f32_e32 v12, v4, v12
	v_mul_f32_e32 v13, v5, v13
	v_cvt_pk_bf16_f32 v12, v12, v13
	global_store_dword v3, v12, s[18:19]
	s_add_u32 s18, s18, 0x1800
	s_addc_u32 s19, s19, 0
	global_load_dword v26, v3, s[14:15] nt
	s_add_u32 s14, s14, 0x1000
	s_addc_u32 s15, s15, 0
	s_waitcnt vmcnt(30)
; __device__ __forceinline__ unsigned cvt_pk_bf16(float lo, float hi) { unsigned r; asm volatile("v_cvt_pk_bf16_f32 %0, %1, %2" : "=v"(r) : "v"(lo), "v"(hi)); return r; }
; __device__ __forceinline__ float bf_lo(unsigned w) { return __uint_as_float(w << 16); }
; __device__ __forceinline__ float bf_hi(unsigned w) { return __uint_as_float(w & 0xffff0000u); }
; __global__ void __launch_bounds__(NTHR, 2) hybrid_block_fwd(Args a) {
;     ...
;         for (int i = 0; i < CH_L; ++i) {
;             const u32x2 q = pab[(size_t)i * (LW / 2)]; const f32x2 av = (f32x2){__builtin_amdgcn_exp2f(bf_lo(q.x)), __builtin_amdgcn_exp2f(bf_lo(q.y))}, bv = (f32x2){bf_hi(q.x), bf_hi(q.y)}; const unsigned gq = pg[(size_t)i * (LW / 2)];
;             H = av * H + bv;
;             po[(size_t)i * (KC / 2)] = cvt_pk_bf16(H.x * bf_lo(gq), H.y * bf_hi(gq));
;         }
	v_lshlrev_b32_e32 v14, 16, v126
	v_lshlrev_b32_e32 v15, 16, v127
	v_exp_f32_e32 v14, v14
	v_exp_f32_e32 v15, v15
	v_and_b32_e32 v16, 0xffff0000, v126
	v_and_b32_e32 v17, 0xffff0000, v127
	v_lshlrev_b32_e32 v18, 16, v27
	v_and_b32_e32 v19, 0xffff0000, v27
	v_pk_fma_f32 v[4:5], v[4:5], v[14:15], v[16:17]
	v_mul_f32_e32 v18, v4, v18
	v_mul_f32_e32 v19, v5, v19
	v_cvt_pk_bf16_f32 v18, v18, v19
	global_store_dword v3, v18, s[18:19]
	s_add_u32 s18, s18, 0x1800
	s_addc_u32 s19, s19, 0
	global_load_dword v27, v3, s[14:15] nt
	s_add_u32 s14, s14, 0x1000
	s_addc_u32 s15, s15, 0
	s_waitcnt vmcnt(30)
	v_lshlrev_b32_e32 v8, 16, v128
	v_lshlrev_b32_e32 v9, 16, v129
	v_exp_f32_e32 v8, v8
	v_exp_f32_e32 v9, v9
	v_and_b32_e32 v10, 0xffff0000, v128
	v_and_b32_e32 v11, 0xffff0000, v129
	v_lshlrev_b32_e32 v12, 16, v28
	v_and_b32_e32 v13, 0xffff0000, v28
	v_pk_fma_f32 v[4:5], v[4:5], v[8:9], v[10:11]
	v_mul_f32_e32 v12, v4, v12
	v_mul_f32_e32 v13, v5, v13
	v_cvt_pk_bf16_f32 v12, v12, v13
	global_store_dword v3, v12, s[18:19]
	s_add_u32 s18, s18, 0x1800
	s_addc_u32 s19, s19, 0
	global_load_dword v28, v3, s[14:15] nt
	s_add_u32 s14, s14, 0x1000
	s_addc_u32 s15, s15, 0
	s_waitcnt vmcnt(30)
	v_lshlrev_b32_e32 v14, 16, v130
	v_lshlrev_b32_e32 v15, 16, v131
	v_exp_f32_e32 v14, v14
	v_exp_f32_e32 v15, v15
	v_and_b32_e32 v16, 0xffff0000, v130
	v_and_b32_e32 v17, 0xffff0000, v131
	v_lshlrev_b32_e32 v18, 16, v29
	v_and_b32_e32 v19, 0xffff0000, v29
	v_pk_fma_f32 v[4:5], v[4:5], v[14:15], v[16:17]
	v_mul_f32_e32 v18, v4, v18
	v_mul_f32_e32 v19, v5, v19
	v_cvt_pk_bf16_f32 v18, v18, v19
	global_store_dword v3, v18, s[18:19]
	s_add_u32 s18, s18, 0x1800
	s_addc_u32 s19, s19, 0
	global_load_dword v29, v3, s[14:15] nt
	s_add_u32 s14, s14, 0x1000
	s_addc_u32 s15, s15, 0
	s_waitcnt vmcnt(30)
	v_lshlrev_b32_e32 v8, 16, v132
	v_lshlrev_b32_e32 v9, 16, v133
	v_exp_f32_e32 v8, v8
	v_exp_f32_e32 v9, v9
	v_and_b32_e32 v10, 0xffff0000, v132
	v_and_b32_e32 v11, 0xffff0000, v133
	v_lshlrev_b32_e32 v12, 16, v30
	v_and_b32_e32 v13, 0xffff0000, v30
	v_pk_fma_f32 v[4:5], v[4:5], v[8:9], v[10:11]
	v_mul_f32_e32 v12, v4, v12
	v_mul_f32_e32 v13, v5, v13
	v_cvt_pk_bf16_f32 v12, v12, v13
	global_store_dword v3, v12, s[18:19]
	s_add_u32 s18, s18, 0x1800
	s_addc_u32 s19, s19, 0
	global_load_dword v30, v3, s[14:15] nt
	s_add_u32 s14, s14, 0x1000
	s_addc_u32 s15, s15, 0
	s_waitcnt vmcnt(30)
	v_lshlrev_b32_e32 v14, 16, v134
	v_lshlrev_b32_e32 v15, 16, v135
	v_exp_f32_e32 v14, v14
	v_exp_f32_e32 v15, v15
	v_and_b32_e32 v16, 0xffff0000, v134
	v_and_b32_e32 v17, 0xffff0000, v135
	v_lshlrev_b32_e32 v18, 16, v31
	v_and_b32_e32 v19, 0xffff0000, v31
	v_pk_fma_f32 v[4:5], v[4:5], v[14:15], v[16:17]
	v_mul_f32_e32 v18, v4, v18
	v_mul_f32_e32 v19, v5, v19
	v_cvt_pk_bf16_f32 v18, v18, v19
	global_store_dword v3, v18, s[18:19]
	s_add_u32 s18, s18, 0x1800
	s_addc_u32 s19, s19, 0
	global_load_dword v31, v3, s[14:15] nt
	s_add_u32 s14, s14, 0x1000
	s_addc_u32 s15, s15, 0
	s_waitcnt vmcnt(30)
	v_lshlrev_b32_e32 v8, 16, v136
	v_lshlrev_b32_e32 v9, 16, v137
	v_exp_f32_e32 v8, v8
	v_exp_f32_e32 v9, v9
	v_and_b32_e32 v10, 0xffff0000, v136
	v_and_b32_e32 v11, 0xffff0000, v137
	v_lshlrev_b32_e32 v12, 16, v32
	v_and_b32_e32 v13, 0xffff0000, v32
	v_pk_fma_f32 v[4:5], v[4:5], v[8:9], v[10:11]
	v_mul_f32_e32 v12, v4, v12
	v_mul_f32_e32 v13, v5, v13
	v_cvt_pk_bf16_f32 v12, v12, v13
	global_store_dword v3, v12, s[18:19]
	s_add_u32 s18, s18, 0x1800
	s_addc_u32 s19, s19, 0
	global_load_dword v32, v3, s[14:15] nt
	s_add_u32 s14, s14, 0x1000
	s_addc_u32 s15, s15, 0
	s_waitcnt vmcnt(30)
	v_lshlrev_b32_e32 v14, 16, v138
	v_lshlrev_b32_e32 v15, 16, v139
	v_exp_f32_e32 v14, v14
	v_exp_f32_e32 v15, v15
	v_and_b32_e32 v16, 0xffff0000, v138
	v_and_b32_e32 v17, 0xffff0000, v139
	v_lshlrev_b32_e32 v18, 16, v33
	v_and_b32_e32 v19, 0xffff0000, v33
	v_pk_fma_f32 v[4:5], v[4:5], v[14:15], v[16:17]
	v_mul_f32_e32 v18, v4, v18
	v_mul_f32_e32 v19, v5, v19
	v_cvt_pk_bf16_f32 v18, v18, v19
	global_store_dword v3, v18, s[18:19]
	s_add_u32 s18, s18, 0x1800
	s_addc_u32 s19, s19, 0
	global_load_dword v33, v3, s[14:15] nt
	s_add_u32 s14, s14, 0x1000
	s_addc_u32 s15, s15, 0
	s_waitcnt vmcnt(30)
	v_lshlrev_b32_e32 v8, 16, v140
	v_lshlrev_b32_e32 v9, 16, v141
	v_exp_f32_e32 v8, v8
	v_exp_f32_e32 v9, v9
	v_and_b32_e32 v10, 0xffff0000, v140
	v_and_b32_e32 v11, 0xffff0000, v141
	v_lshlrev_b32_e32 v12, 16, v34
	v_and_b32_e32 v13, 0xffff0000, v34
	v_pk_fma_f32 v[4:5], v[4:5], v[8:9], v[10:11]
	v_mul_f32_e32 v12, v4, v12
	v_mul_f32_e32 v13, v5, v13
	v_cvt_pk_bf16_f32 v12, v12, v13
	global_store_dword v3, v12, s[18:19]
	s_add_u32 s18, s18, 0x1800
	s_addc_u32 s19, s19, 0
	global_load_dword v34, v3, s[14:15] nt
	s_add_u32 s14, s14, 0x1000
	s_addc_u32 s15, s15, 0
	s_waitcnt vmcnt(30)
	v_lshlrev_b32_e32 v14, 16, v142
	v_lshlrev_b32_e32 v15, 16, v143
	v_exp_f32_e32 v14, v14
	v_exp_f32_e32 v15, v15
	v_and_b32_e32 v16, 0xffff0000, v142
	v_and_b32_e32 v17, 0xffff0000, v143
	v_lshlrev_b32_e32 v18, 16, v35
	v_and_b32_e32 v19, 0xffff0000, v35
	v_pk_fma_f32 v[4:5], v[4:5], v[14:15], v[16:17]
	v_mul_f32_e32 v18, v4, v18
	v_mul_f32_e32 v19, v5, v19
	v_cvt_pk_bf16_f32 v18, v18, v19
	global_store_dword v3, v18, s[18:19]
	s_add_u32 s18, s18, 0x1800
	s_addc_u32 s19, s19, 0
	global_load_dword v35, v3, s[14:15] nt
	s_add_u32 s14, s14, 0x1000
	s_addc_u32 s15, s15, 0
	s_waitcnt vmcnt(30)
	v_lshlrev_b32_e32 v8, 16, v144
	v_lshlrev_b32_e32 v9, 16, v145
	v_exp_f32_e32 v8, v8
	v_exp_f32_e32 v9, v9
	v_and_b32_e32 v10, 0xffff0000, v144
	v_and_b32_e32 v11, 0xffff0000, v145
	v_lshlrev_b32_e32 v12, 16, v20
	v_and_b32_e32 v13, 0xffff0000, v20
	v_pk_fma_f32 v[4:5], v[4:5], v[8:9], v[10:11]
	v_mul_f32_e32 v12, v4, v12
	v_mul_f32_e32 v13, v5, v13
	v_cvt_pk_bf16_f32 v12, v12, v13
	global_store_dword v3, v12, s[18:19]
	s_add_u32 s18, s18, 0x1800
	s_addc_u32 s19, s19, 0
	global_load_dword v20, v3, s[14:15] nt
	s_add_u32 s14, s14, 0x1000
	s_addc_u32 s15, s15, 0
	s_waitcnt vmcnt(30)
; __device__ __forceinline__ unsigned cvt_pk_bf16(float lo, float hi) { unsigned r; asm volatile("v_cvt_pk_bf16_f32 %0, %1, %2" : "=v"(r) : "v"(lo), "v"(hi)); return r; }
; __device__ __forceinline__ float bf_lo(unsigned w) { return __uint_as_float(w << 16); }
; __device__ __forceinline__ float bf_hi(unsigned w) { return __uint_as_float(w & 0xffff0000u); }
; __global__ void __launch_bounds__(NTHR, 2) hybrid_block_fwd(Args a) {
;     ...
;         for (int i = 0; i < CH_L; ++i) {
;             const u32x2 q = pab[(size_t)i * (LW / 2)]; const f32x2 av = (f32x2){__builtin_amdgcn_exp2f(bf_lo(q.x)), __builtin_amdgcn_exp2f(bf_lo(q.y))}, bv = (f32x2){bf_hi(q.x), bf_hi(q.y)}; const unsigned gq = pg[(size_t)i * (LW / 2)];
;             H = av * H + bv;
;             po[(size_t)i * (KC / 2)] = cvt_pk_bf16(H.x * bf_lo(gq), H.y * bf_hi(gq));
;         }
	v_lshlrev_b32_e32 v14, 16, v146
	v_lshlrev_b32_e32 v15, 16, v147
	v_exp_f32_e32 v14, v14
	v_exp_f32_e32 v15, v15
	v_and_b32_e32 v16, 0xffff0000, v146
	v_and_b32_e32 v17, 0xffff0000, v147
	v_lshlrev_b32_e32 v18, 16, v21
	v_and_b32_e32 v19, 0xffff0000, v21
	v_pk_fma_f32 v[4:5], v[4:5], v[14:15], v[16:17]
	v_mul_f32_e32 v18, v4, v18
	v_mul_f32_e32 v19, v5, v19
	v_cvt_pk_bf16_f32 v18, v18, v19
	global_store_dword v3, v18, s[18:19]
	s_add_u32 s18, s18, 0x1800
	s_addc_u32 s19, s19, 0
	global_load_dword v21, v3, s[14:15] nt
	s_add_u32 s14, s14, 0x1000
	s_addc_u32 s15, s15, 0
	s_waitcnt vmcnt(30)
	v_lshlrev_b32_e32 v8, 16, v148
	v_lshlrev_b32_e32 v9, 16, v149
	v_exp_f32_e32 v8, v8
	v_exp_f32_e32 v9, v9
	v_and_b32_e32 v10, 0xffff0000, v148
	v_and_b32_e32 v11, 0xffff0000, v149
	v_lshlrev_b32_e32 v12, 16, v22
	v_and_b32_e32 v13, 0xffff0000, v22
	v_pk_fma_f32 v[4:5], v[4:5], v[8:9], v[10:11]
	v_mul_f32_e32 v12, v4, v12
	v_mul_f32_e32 v13, v5, v13
	v_cvt_pk_bf16_f32 v12, v12, v13
	global_store_dword v3, v12, s[18:19]
	s_add_u32 s18, s18, 0x1800
	s_addc_u32 s19, s19, 0
	global_load_dword v22, v3, s[14:15] nt
	s_add_u32 s14, s14, 0x1000
	s_addc_u32 s15, s15, 0
	s_waitcnt vmcnt(30)
	v_lshlrev_b32_e32 v14, 16, v150
	v_lshlrev_b32_e32 v15, 16, v151
	v_exp_f32_e32 v14, v14
	v_exp_f32_e32 v15, v15
	v_and_b32_e32 v16, 0xffff0000, v150
	v_and_b32_e32 v17, 0xffff0000, v151
	v_lshlrev_b32_e32 v18, 16, v23
	v_and_b32_e32 v19, 0xffff0000, v23
	v_pk_fma_f32 v[4:5], v[4:5], v[14:15], v[16:17]
	v_mul_f32_e32 v18, v4, v18
	v_mul_f32_e32 v19, v5, v19
	v_cvt_pk_bf16_f32 v18, v18, v19
	global_store_dword v3, v18, s[18:19]
	s_add_u32 s18, s18, 0x1800
	s_addc_u32 s19, s19, 0
	global_load_dword v23, v3, s[14:15] nt
	s_add_u32 s14, s14, 0x1000
	s_addc_u32 s15, s15, 0
	s_waitcnt vmcnt(30)
	v_lshlrev_b32_e32 v8, 16, v152
	v_lshlrev_b32_e32 v9, 16, v153
	v_exp_f32_e32 v8, v8
	v_exp_f32_e32 v9, v9
	v_and_b32_e32 v10, 0xffff0000, v152
	v_and_b32_e32 v11, 0xffff0000, v153
	v_lshlrev_b32_e32 v12, 16, v24
	v_and_b32_e32 v13, 0xffff0000, v24
	v_pk_fma_f32 v[4:5], v[4:5], v[8:9], v[10:11]
	v_mul_f32_e32 v12, v4, v12
	v_mul_f32_e32 v13, v5, v13
	v_cvt_pk_bf16_f32 v12, v12, v13
	global_store_dword v3, v12, s[18:19]
	s_add_u32 s18, s18, 0x1800
	s_addc_u32 s19, s19, 0
	global_load_dword v24, v3, s[14:15] nt
	s_add_u32 s14, s14, 0x1000
	s_addc_u32 s15, s15, 0
	s_waitcnt vmcnt(30)
	v_lshlrev_b32_e32 v14, 16, v154
	v_lshlrev_b32_e32 v15, 16, v155
	v_exp_f32_e32 v14, v14
	v_exp_f32_e32 v15, v15
	v_and_b32_e32 v16, 0xffff0000, v154
	v_and_b32_e32 v17, 0xffff0000, v155
	v_lshlrev_b32_e32 v18, 16, v25
	v_and_b32_e32 v19, 0xffff0000, v25
	v_pk_fma_f32 v[4:5], v[4:5], v[14:15], v[16:17]
	v_mul_f32_e32 v18, v4, v18
	v_mul_f32_e32 v19, v5, v19
	v_cvt_pk_bf16_f32 v18, v18, v19
	global_store_dword v3, v18, s[18:19]
	s_add_u32 s18, s18, 0x1800
	s_addc_u32 s19, s19, 0
	global_load_dword v25, v3, s[14:15] nt
	s_add_u32 s14, s14, 0x1000
	s_addc_u32 s15, s15, 0
	s_waitcnt vmcnt(30)
	v_lshlrev_b32_e32 v8, 16, v156
	v_lshlrev_b32_e32 v9, 16, v157
	v_exp_f32_e32 v8, v8
	v_exp_f32_e32 v9, v9
	v_and_b32_e32 v10, 0xffff0000, v156
	v_and_b32_e32 v11, 0xffff0000, v157
	v_lshlrev_b32_e32 v12, 16, v26
	v_and_b32_e32 v13, 0xffff0000, v26
	v_pk_fma_f32 v[4:5], v[4:5], v[8:9], v[10:11]
	v_mul_f32_e32 v12, v4, v12
	v_mul_f32_e32 v13, v5, v13
	v_cvt_pk_bf16_f32 v12, v12, v13
	global_store_dword v3, v12, s[18:19]
	s_add_u32 s18, s18, 0x1800
	s_addc_u32 s19, s19, 0
	global_load_dword v26, v3, s[14:15] nt
	s_add_u32 s14, s14, 0x1000
	s_addc_u32 s15, s15, 0
	s_waitcnt vmcnt(30)
	v_lshlrev_b32_e32 v14, 16, v158
	v_lshlrev_b32_e32 v15, 16, v159
	v_exp_f32_e32 v14, v14
	v_exp_f32_e32 v15, v15
	v_and_b32_e32 v16, 0xffff0000, v158
	v_and_b32_e32 v17, 0xffff0000, v159
	v_lshlrev_b32_e32 v18, 16, v27
	v_and_b32_e32 v19, 0xffff0000, v27
	v_pk_fma_f32 v[4:5], v[4:5], v[14:15], v[16:17]
	v_mul_f32_e32 v18, v4, v18
	v_mul_f32_e32 v19, v5, v19
	v_cvt_pk_bf16_f32 v18, v18, v19
	global_store_dword v3, v18, s[18:19]
	s_add_u32 s18, s18, 0x1800
	s_addc_u32 s19, s19, 0
	global_load_dword v27, v3, s[14:15] nt
	s_add_u32 s14, s14, 0x1000
	s_addc_u32 s15, s15, 0
	s_waitcnt vmcnt(30)
	v_lshlrev_b32_e32 v8, 16, v160
	v_lshlrev_b32_e32 v9, 16, v161
	v_exp_f32_e32 v8, v8
	v_exp_f32_e32 v9, v9
	v_and_b32_e32 v10, 0xffff0000, v160
	v_and_b32_e32 v11, 0xffff0000, v161
	v_lshlrev_b32_e32 v12, 16, v28
	v_and_b32_e32 v13, 0xffff0000, v28
	v_pk_fma_f32 v[4:5], v[4:5], v[8:9], v[10:11]
	v_mul_f32_e32 v12, v4, v12
	v_mul_f32_e32 v13, v5, v13
	v_cvt_pk_bf16_f32 v12, v12, v13
	global_store_dword v3, v12, s[18:19]
	s_add_u32 s18, s18, 0x1800
	s_addc_u32 s19, s19, 0
	global_load_dword v28, v3, s[14:15] nt
	s_add_u32 s14, s14, 0x1000
	s_addc_u32 s15, s15, 0
	s_waitcnt vmcnt(30)
	v_lshlrev_b32_e32 v14, 16, v162
	v_lshlrev_b32_e32 v15, 16, v163
	v_exp_f32_e32 v14, v14
	v_exp_f32_e32 v15, v15
	v_and_b32_e32 v16, 0xffff0000, v162
	v_and_b32_e32 v17, 0xffff0000, v163
	v_lshlrev_b32_e32 v18, 16, v29
	v_and_b32_e32 v19, 0xffff0000, v29
	v_pk_fma_f32 v[4:5], v[4:5], v[14:15], v[16:17]
	v_mul_f32_e32 v18, v4, v18
	v_mul_f32_e32 v19, v5, v19
	v_cvt_pk_bf16_f32 v18, v18, v19
	global_store_dword v3, v18, s[18:19]
	s_add_u32 s18, s18, 0x1800
	s_addc_u32 s19, s19, 0
	global_load_dword v29, v3, s[14:15] nt
	s_add_u32 s14, s14, 0x1000
	s_addc_u32 s15, s15, 0
	s_waitcnt vmcnt(30)
	v_lshlrev_b32_e32 v8, 16, v164
	v_lshlrev_b32_e32 v9, 16, v165
	v_exp_f32_e32 v8, v8
	v_exp_f32_e32 v9, v9
	v_and_b32_e32 v10, 0xffff0000, v164
	v_and_b32_e32 v11, 0xffff0000, v165
	v_lshlrev_b32_e32 v12, 16, v30
	v_and_b32_e32 v13, 0xffff0000, v30
	v_pk_fma_f32 v[4:5], v[4:5], v[8:9], v[10:11]
	v_mul_f32_e32 v12, v4, v12
	v_mul_f32_e32 v13, v5, v13
	v_cvt_pk_bf16_f32 v12, v12, v13
	global_store_dword v3, v12, s[18:19]
	s_add_u32 s18, s18, 0x1800
	s_addc_u32 s19, s19, 0
	global_load_dword v30, v3, s[14:15] nt
	s_add_u32 s14, s14, 0x1000
	s_addc_u32 s15, s15, 0
	s_waitcnt vmcnt(30)
; __device__ __forceinline__ unsigned cvt_pk_bf16(float lo, float hi) { unsigned r; asm volatile("v_cvt_pk_bf16_f32 %0, %1, %2" : "=v"(r) : "v"(lo), "v"(hi)); return r; }
; __device__ __forceinline__ float bf_lo(unsigned w) { return __uint_as_float(w << 16); }
; __device__ __forceinline__ float bf_hi(unsigned w) { return __uint_as_float(w & 0xffff0000u); }
; __global__ void __launch_bounds__(NTHR, 2) hybrid_block_fwd(Args a) {
;     ...
;         for (int i = 0; i < CH_L; ++i) {
;             const u32x2 q = pab[(size_t)i * (LW / 2)]; const f32x2 av = (f32x2){__builtin_amdgcn_exp2f(bf_lo(q.x)), __builtin_amdgcn_exp2f(bf_lo(q.y))}, bv = (f32x2){bf_hi(q.x), bf_hi(q.y)}; const unsigned gq = pg[(size_t)i * (LW / 2)];
;             H = av * H + bv;
;             po[(size_t)i * (KC / 2)] = cvt_pk_bf16(H.x * bf_lo(gq), H.y * bf_hi(gq));
;         }
	v_lshlrev_b32_e32 v14, 16, v166
	v_lshlrev_b32_e32 v15, 16, v167
	v_exp_f32_e32 v14, v14
	v_exp_f32_e32 v15, v15
	v_and_b32_e32 v16, 0xffff0000, v166
	v_and_b32_e32 v17, 0xffff0000, v167
	v_lshlrev_b32_e32 v18, 16, v31
	v_and_b32_e32 v19, 0xffff0000, v31
	v_pk_fma_f32 v[4:5], v[4:5], v[14:15], v[16:17]
	v_mul_f32_e32 v18, v4, v18
	v_mul_f32_e32 v19, v5, v19
	v_cvt_pk_bf16_f32 v18, v18, v19
	global_store_dword v3, v18, s[18:19]
	s_add_u32 s18, s18, 0x1800
	s_addc_u32 s19, s19, 0
	global_load_dword v31, v3, s[14:15] nt
	s_add_u32 s14, s14, 0x1000
	s_addc_u32 s15, s15, 0
	s_waitcnt vmcnt(30)
	v_lshlrev_b32_e32 v8, 16, v168
	v_lshlrev_b32_e32 v9, 16, v169
	v_exp_f32_e32 v8, v8
	v_exp_f32_e32 v9, v9
	v_and_b32_e32 v10, 0xffff0000, v168
	v_and_b32_e32 v11, 0xffff0000, v169
	v_lshlrev_b32_e32 v12, 16, v32
	v_and_b32_e32 v13, 0xffff0000, v32
	v_pk_fma_f32 v[4:5], v[4:5], v[8:9], v[10:11]
	v_mul_f32_e32 v12, v4, v12
	v_mul_f32_e32 v13, v5, v13
	v_cvt_pk_bf16_f32 v12, v12, v13
	global_store_dword v3, v12, s[18:19]
	s_add_u32 s18, s18, 0x1800
	s_addc_u32 s19, s19, 0
	global_load_dword v32, v3, s[14:15] nt
	s_add_u32 s14, s14, 0x1000
	s_addc_u32 s15, s15, 0
	s_waitcnt vmcnt(30)
	v_lshlrev_b32_e32 v14, 16, v170
	v_lshlrev_b32_e32 v15, 16, v171
	v_exp_f32_e32 v14, v14
	v_exp_f32_e32 v15, v15
	v_and_b32_e32 v16, 0xffff0000, v170
	v_and_b32_e32 v17, 0xffff0000, v171
	v_lshlrev_b32_e32 v18, 16, v33
	v_and_b32_e32 v19, 0xffff0000, v33
	v_pk_fma_f32 v[4:5], v[4:5], v[14:15], v[16:17]
	v_mul_f32_e32 v18, v4, v18
	v_mul_f32_e32 v19, v5, v19
	v_cvt_pk_bf16_f32 v18, v18, v19
	global_store_dword v3, v18, s[18:19]
	s_add_u32 s18, s18, 0x1800
	s_addc_u32 s19, s19, 0
	global_load_dword v33, v3, s[14:15] nt
	s_add_u32 s14, s14, 0x1000
	s_addc_u32 s15, s15, 0
	s_waitcnt vmcnt(30)
	v_lshlrev_b32_e32 v8, 16, v172
	v_lshlrev_b32_e32 v9, 16, v173
	v_exp_f32_e32 v8, v8
	v_exp_f32_e32 v9, v9
	v_and_b32_e32 v10, 0xffff0000, v172
	v_and_b32_e32 v11, 0xffff0000, v173
	v_lshlrev_b32_e32 v12, 16, v34
	v_and_b32_e32 v13, 0xffff0000, v34
	v_pk_fma_f32 v[4:5], v[4:5], v[8:9], v[10:11]
	v_mul_f32_e32 v12, v4, v12
	v_mul_f32_e32 v13, v5, v13
	v_cvt_pk_bf16_f32 v12, v12, v13
	global_store_dword v3, v12, s[18:19]
	s_add_u32 s18, s18, 0x1800
	s_addc_u32 s19, s19, 0
	global_load_dword v34, v3, s[14:15] nt
	s_add_u32 s14, s14, 0x1000
	s_addc_u32 s15, s15, 0
	s_waitcnt vmcnt(30)
	v_lshlrev_b32_e32 v14, 16, v174
	v_lshlrev_b32_e32 v15, 16, v175
	v_exp_f32_e32 v14, v14
	v_exp_f32_e32 v15, v15
	v_and_b32_e32 v16, 0xffff0000, v174
	v_and_b32_e32 v17, 0xffff0000, v175
	v_lshlrev_b32_e32 v18, 16, v35
	v_and_b32_e32 v19, 0xffff0000, v35
	v_pk_fma_f32 v[4:5], v[4:5], v[14:15], v[16:17]
	v_mul_f32_e32 v18, v4, v18
	v_mul_f32_e32 v19, v5, v19
	v_cvt_pk_bf16_f32 v18, v18, v19
	global_store_dword v3, v18, s[18:19]
	s_add_u32 s18, s18, 0x1800
	s_addc_u32 s19, s19, 0
	global_load_dword v35, v3, s[14:15] nt
	s_add_u32 s14, s14, 0x1000
	s_addc_u32 s15, s15, 0
	s_waitcnt vmcnt(30)
	v_lshlrev_b32_e32 v8, 16, v176
	v_lshlrev_b32_e32 v9, 16, v177
	v_exp_f32_e32 v8, v8
	v_exp_f32_e32 v9, v9
	v_and_b32_e32 v10, 0xffff0000, v176
	v_and_b32_e32 v11, 0xffff0000, v177
	v_lshlrev_b32_e32 v12, 16, v20
	v_and_b32_e32 v13, 0xffff0000, v20
	v_pk_fma_f32 v[4:5], v[4:5], v[8:9], v[10:11]
	v_mul_f32_e32 v12, v4, v12
	v_mul_f32_e32 v13, v5, v13
	v_cvt_pk_bf16_f32 v12, v12, v13
	global_store_dword v3, v12, s[18:19]
	s_add_u32 s18, s18, 0x1800
	s_addc_u32 s19, s19, 0
	s_waitcnt vmcnt(29)
	v_lshlrev_b32_e32 v14, 16, v178
	v_lshlrev_b32_e32 v15, 16, v179
	v_exp_f32_e32 v14, v14
	v_exp_f32_e32 v15, v15
	v_and_b32_e32 v16, 0xffff0000, v178
	v_and_b32_e32 v17, 0xffff0000, v179
	v_lshlrev_b32_e32 v18, 16, v21
	v_and_b32_e32 v19, 0xffff0000, v21
	v_pk_fma_f32 v[4:5], v[4:5], v[14:15], v[16:17]
	v_mul_f32_e32 v18, v4, v18
	v_mul_f32_e32 v19, v5, v19
	v_cvt_pk_bf16_f32 v18, v18, v19
	global_store_dword v3, v18, s[18:19]
	s_add_u32 s18, s18, 0x1800
	s_addc_u32 s19, s19, 0
	s_waitcnt vmcnt(28)
	v_lshlrev_b32_e32 v8, 16, v180
	v_lshlrev_b32_e32 v9, 16, v181
	v_exp_f32_e32 v8, v8
	v_exp_f32_e32 v9, v9
	v_and_b32_e32 v10, 0xffff0000, v180
	v_and_b32_e32 v11, 0xffff0000, v181
	v_lshlrev_b32_e32 v12, 16, v22
	v_and_b32_e32 v13, 0xffff0000, v22
	v_pk_fma_f32 v[4:5], v[4:5], v[8:9], v[10:11]
	v_mul_f32_e32 v12, v4, v12
	v_mul_f32_e32 v13, v5, v13
	v_cvt_pk_bf16_f32 v12, v12, v13
	global_store_dword v3, v12, s[18:19]
	s_add_u32 s18, s18, 0x1800
	s_addc_u32 s19, s19, 0
	s_waitcnt vmcnt(27)
	v_lshlrev_b32_e32 v14, 16, v182
	v_lshlrev_b32_e32 v15, 16, v183
	v_exp_f32_e32 v14, v14
	v_exp_f32_e32 v15, v15
	v_and_b32_e32 v16, 0xffff0000, v182
	v_and_b32_e32 v17, 0xffff0000, v183
	v_lshlrev_b32_e32 v18, 16, v23
	v_and_b32_e32 v19, 0xffff0000, v23
	v_pk_fma_f32 v[4:5], v[4:5], v[14:15], v[16:17]
	v_mul_f32_e32 v18, v4, v18
	v_mul_f32_e32 v19, v5, v19
	v_cvt_pk_bf16_f32 v18, v18, v19
	global_store_dword v3, v18, s[18:19]
	s_add_u32 s18, s18, 0x1800
	s_addc_u32 s19, s19, 0
	s_waitcnt vmcnt(26)
	v_lshlrev_b32_e32 v8, 16, v184
	v_lshlrev_b32_e32 v9, 16, v185
	v_exp_f32_e32 v8, v8
	v_exp_f32_e32 v9, v9
	v_and_b32_e32 v10, 0xffff0000, v184
	v_and_b32_e32 v11, 0xffff0000, v185
	v_lshlrev_b32_e32 v12, 16, v24
	v_and_b32_e32 v13, 0xffff0000, v24
	v_pk_fma_f32 v[4:5], v[4:5], v[8:9], v[10:11]
	v_mul_f32_e32 v12, v4, v12
	v_mul_f32_e32 v13, v5, v13
	v_cvt_pk_bf16_f32 v12, v12, v13
	global_store_dword v3, v12, s[18:19]
	s_add_u32 s18, s18, 0x1800
	s_addc_u32 s19, s19, 0
	s_waitcnt vmcnt(25)
; __device__ __forceinline__ unsigned cvt_pk_bf16(float lo, float hi) { unsigned r; asm volatile("v_cvt_pk_bf16_f32 %0, %1, %2" : "=v"(r) : "v"(lo), "v"(hi)); return r; }
; __device__ __forceinline__ float bf_lo(unsigned w) { return __uint_as_float(w << 16); }
; __device__ __forceinline__ float bf_hi(unsigned w) { return __uint_as_float(w & 0xffff0000u); }
; __device__ __forceinline__ void xcd_barrier(const XcdBarrier& b) {
;     asm volatile("s_waitcnt vmcnt(0)" ::: "memory");
;     __syncthreads();
;     if (threadIdx.x == 0) {
;         unsigned* bar = b.bar;
;         __builtin_amdgcn_s_waitcnt(0);
;         unsigned nloc = b.st[0], nx = b.st[1];
;         if (nloc == 0u) { xcd_barrier_complete(bar, b.x, nloc, nx); b.st[0] = nloc; b.st[1] = nx; }
; __global__ void __launch_bounds__(NTHR, 2) hybrid_block_fwd(Args a) {
;     ...
;         for (int i = 0; i < CH_L; ++i) {
;             const u32x2 q = pab[(size_t)i * (LW / 2)]; const f32x2 av = (f32x2){__builtin_amdgcn_exp2f(bf_lo(q.x)), __builtin_amdgcn_exp2f(bf_lo(q.y))}, bv = (f32x2){bf_hi(q.x), bf_hi(q.y)}; const unsigned gq = pg[(size_t)i * (LW / 2)];
;             H = av * H + bv;
;             po[(size_t)i * (KC / 2)] = cvt_pk_bf16(H.x * bf_lo(gq), H.y * bf_hi(gq));
;         }
	v_lshlrev_b32_e32 v14, 16, v186
	v_lshlrev_b32_e32 v15, 16, v187
	v_exp_f32_e32 v14, v14
	v_exp_f32_e32 v15, v15
	v_and_b32_e32 v16, 0xffff0000, v186
	v_and_b32_e32 v17, 0xffff0000, v187
	v_lshlrev_b32_e32 v18, 16, v25
	v_and_b32_e32 v19, 0xffff0000, v25
	v_pk_fma_f32 v[4:5], v[4:5], v[14:15], v[16:17]
	v_mul_f32_e32 v18, v4, v18
	v_mul_f32_e32 v19, v5, v19
	v_cvt_pk_bf16_f32 v18, v18, v19
	global_store_dword v3, v18, s[18:19]
	s_add_u32 s18, s18, 0x1800
	s_addc_u32 s19, s19, 0
	s_waitcnt vmcnt(24)
	v_lshlrev_b32_e32 v8, 16, v188
	v_lshlrev_b32_e32 v9, 16, v189
	v_exp_f32_e32 v8, v8
	v_exp_f32_e32 v9, v9
	v_and_b32_e32 v10, 0xffff0000, v188
	v_and_b32_e32 v11, 0xffff0000, v189
	v_lshlrev_b32_e32 v12, 16, v26
	v_and_b32_e32 v13, 0xffff0000, v26
	v_pk_fma_f32 v[4:5], v[4:5], v[8:9], v[10:11]
	v_mul_f32_e32 v12, v4, v12
	v_mul_f32_e32 v13, v5, v13
	v_cvt_pk_bf16_f32 v12, v12, v13
	global_store_dword v3, v12, s[18:19]
	s_add_u32 s18, s18, 0x1800
	s_addc_u32 s19, s19, 0
	s_waitcnt vmcnt(23)
	v_lshlrev_b32_e32 v14, 16, v190
	v_lshlrev_b32_e32 v15, 16, v191
	v_exp_f32_e32 v14, v14
	v_exp_f32_e32 v15, v15
	v_and_b32_e32 v16, 0xffff0000, v190
	v_and_b32_e32 v17, 0xffff0000, v191
	v_lshlrev_b32_e32 v18, 16, v27
	v_and_b32_e32 v19, 0xffff0000, v27
	v_pk_fma_f32 v[4:5], v[4:5], v[14:15], v[16:17]
	v_mul_f32_e32 v18, v4, v18
	v_mul_f32_e32 v19, v5, v19
	v_cvt_pk_bf16_f32 v18, v18, v19
	global_store_dword v3, v18, s[18:19]
	s_add_u32 s18, s18, 0x1800
	s_addc_u32 s19, s19, 0
	s_waitcnt vmcnt(22)
	v_lshlrev_b32_e32 v8, 16, v192
	v_lshlrev_b32_e32 v9, 16, v193
	v_exp_f32_e32 v8, v8
	v_exp_f32_e32 v9, v9
	v_and_b32_e32 v10, 0xffff0000, v192
	v_and_b32_e32 v11, 0xffff0000, v193
	v_lshlrev_b32_e32 v12, 16, v28
	v_and_b32_e32 v13, 0xffff0000, v28
	v_pk_fma_f32 v[4:5], v[4:5], v[8:9], v[10:11]
	v_mul_f32_e32 v12, v4, v12
	v_mul_f32_e32 v13, v5, v13
	v_cvt_pk_bf16_f32 v12, v12, v13
	global_store_dword v3, v12, s[18:19]
	s_add_u32 s18, s18, 0x1800
	s_addc_u32 s19, s19, 0
	s_waitcnt vmcnt(21)
	v_lshlrev_b32_e32 v14, 16, v194
	v_lshlrev_b32_e32 v15, 16, v195
	v_exp_f32_e32 v14, v14
	v_exp_f32_e32 v15, v15
	v_and_b32_e32 v16, 0xffff0000, v194
	v_and_b32_e32 v17, 0xffff0000, v195
	v_lshlrev_b32_e32 v18, 16, v29
	v_and_b32_e32 v19, 0xffff0000, v29
	v_pk_fma_f32 v[4:5], v[4:5], v[14:15], v[16:17]
	v_mul_f32_e32 v18, v4, v18
	v_mul_f32_e32 v19, v5, v19
	v_cvt_pk_bf16_f32 v18, v18, v19
	global_store_dword v3, v18, s[18:19]
	s_add_u32 s18, s18, 0x1800
	s_addc_u32 s19, s19, 0
	s_waitcnt vmcnt(20)
	v_lshlrev_b32_e32 v8, 16, v196
	v_lshlrev_b32_e32 v9, 16, v197
	v_exp_f32_e32 v8, v8
	v_exp_f32_e32 v9, v9
	v_and_b32_e32 v10, 0xffff0000, v196
	v_and_b32_e32 v11, 0xffff0000, v197
	v_lshlrev_b32_e32 v12, 16, v30
	v_and_b32_e32 v13, 0xffff0000, v30
	v_pk_fma_f32 v[4:5], v[4:5], v[8:9], v[10:11]
	v_mul_f32_e32 v12, v4, v12
	v_mul_f32_e32 v13, v5, v13
	v_cvt_pk_bf16_f32 v12, v12, v13
	global_store_dword v3, v12, s[18:19]
	s_add_u32 s18, s18, 0x1800
	s_addc_u32 s19, s19, 0
	s_waitcnt vmcnt(19)
	v_lshlrev_b32_e32 v14, 16, v198
	v_lshlrev_b32_e32 v15, 16, v199
	v_exp_f32_e32 v14, v14
	v_exp_f32_e32 v15, v15
	v_and_b32_e32 v16, 0xffff0000, v198
	v_and_b32_e32 v17, 0xffff0000, v199
	v_lshlrev_b32_e32 v18, 16, v31
	v_and_b32_e32 v19, 0xffff0000, v31
	v_pk_fma_f32 v[4:5], v[4:5], v[14:15], v[16:17]
	v_mul_f32_e32 v18, v4, v18
	v_mul_f32_e32 v19, v5, v19
	v_cvt_pk_bf16_f32 v18, v18, v19
	global_store_dword v3, v18, s[18:19]
	s_add_u32 s18, s18, 0x1800
	s_addc_u32 s19, s19, 0
	s_waitcnt vmcnt(18)
	v_lshlrev_b32_e32 v8, 16, v200
	v_lshlrev_b32_e32 v9, 16, v201
	v_exp_f32_e32 v8, v8
	v_exp_f32_e32 v9, v9
	v_and_b32_e32 v10, 0xffff0000, v200
	v_and_b32_e32 v11, 0xffff0000, v201
	v_lshlrev_b32_e32 v12, 16, v32
	v_and_b32_e32 v13, 0xffff0000, v32
	v_pk_fma_f32 v[4:5], v[4:5], v[8:9], v[10:11]
	v_mul_f32_e32 v12, v4, v12
	v_mul_f32_e32 v13, v5, v13
	v_cvt_pk_bf16_f32 v12, v12, v13
	global_store_dword v3, v12, s[18:19]
	s_add_u32 s18, s18, 0x1800
	s_addc_u32 s19, s19, 0
	s_waitcnt vmcnt(17)
	v_lshlrev_b32_e32 v14, 16, v202
	v_lshlrev_b32_e32 v15, 16, v203
	v_exp_f32_e32 v14, v14
	v_exp_f32_e32 v15, v15
	v_and_b32_e32 v16, 0xffff0000, v202
	v_and_b32_e32 v17, 0xffff0000, v203
	v_lshlrev_b32_e32 v18, 16, v33
	v_and_b32_e32 v19, 0xffff0000, v33
	v_pk_fma_f32 v[4:5], v[4:5], v[14:15], v[16:17]
	v_mul_f32_e32 v18, v4, v18
	v_mul_f32_e32 v19, v5, v19
	v_cvt_pk_bf16_f32 v18, v18, v19
	global_store_dword v3, v18, s[18:19]
	s_add_u32 s18, s18, 0x1800
	s_addc_u32 s19, s19, 0
	s_waitcnt vmcnt(16)
	v_lshlrev_b32_e32 v8, 16, v204
	v_lshlrev_b32_e32 v9, 16, v205
	v_exp_f32_e32 v8, v8
	v_exp_f32_e32 v9, v9
	v_and_b32_e32 v10, 0xffff0000, v204
	v_and_b32_e32 v11, 0xffff0000, v205
	v_lshlrev_b32_e32 v12, 16, v34
	v_and_b32_e32 v13, 0xffff0000, v34
	v_pk_fma_f32 v[4:5], v[4:5], v[8:9], v[10:11]
	v_mul_f32_e32 v12, v4, v12
	v_mul_f32_e32 v13, v5, v13
	v_cvt_pk_bf16_f32 v12, v12, v13
	global_store_dword v3, v12, s[18:19]
	s_add_u32 s18, s18, 0x1800
	s_addc_u32 s19, s19, 0
	s_waitcnt vmcnt(15)
	v_lshlrev_b32_e32 v14, 16, v206
	v_lshlrev_b32_e32 v15, 16, v207
	v_exp_f32_e32 v14, v14
	v_exp_f32_e32 v15, v15
	v_and_b32_e32 v16, 0xffff0000, v206
	v_and_b32_e32 v17, 0xffff0000, v207
	v_lshlrev_b32_e32 v18, 16, v35
	v_and_b32_e32 v19, 0xffff0000, v35
	v_pk_fma_f32 v[4:5], v[4:5], v[14:15], v[16:17]
	v_mul_f32_e32 v18, v4, v18
	v_mul_f32_e32 v19, v5, v19
	v_cvt_pk_bf16_f32 v18, v18, v19
	global_store_dword v3, v18, s[18:19]
	s_add_u32 s18, s18, 0x1800
	s_addc_u32 s19, s19, 0
	s_waitcnt vmcnt(0)
	s_barrier
	s_mov_b64 s[0:1], exec
	v_readlane_b32 s4, v248, 6
	v_readlane_b32 s5, v248, 7
	s_and_b64 s[4:5], s[0:1], s[4:5]
	s_mov_b64 exec, s[4:5]
	s_cbranch_execz .LBB0_735
	s_add_i32 s4, 0, 0x20020
	v_mov_b32_e32 v0, s4
	s_waitcnt vmcnt(0) expcnt(0) lgkmcnt(0)
	ds_read_b32 v2, v0
	s_add_i32 s4, 0, 0x20024
	v_mov_b32_e32 v0, s4
	ds_read_b32 v0, v0
	s_waitcnt lgkmcnt(1)
	v_cmp_ne_u32_e32 vcc, 0, v2
	s_cbranch_vccnz .LBB0_699
	v_readlane_b32 s4, v248, 2
	v_readlane_b32 s5, v248, 3
	v_readlane_b32 s8, v248, 1
	s_mul_i32 s18, s5, s8
	s_mul_i32 s18, s18, s4
	s_add_u32 s4, s94, 0x40200
	s_addc_u32 s5, s95, 0
	s_add_u32 s8, s94, 0x40400
	s_addc_u32 s9, s95, 0
	s_add_u32 s10, s94, 0x40500
	s_addc_u32 s11, s95, 0
	s_add_u32 s38, s94, 0x40600
	s_addc_u32 s39, s95, 0
	s_add_u32 s42, s94, 0x40700
	s_addc_u32 s43, s95, 0
	s_add_u32 s54, s94, 0x40800
	s_addc_u32 s55, s95, 0
	s_add_u32 s56, s94, 0x40900
	s_addc_u32 s57, s95, 0
	s_add_u32 s58, s94, 0x40a00
	s_addc_u32 s59, s95, 0
	s_add_u32 s60, s94, 0x40b00
	s_addc_u32 s61, s95, 0
	s_add_u32 s62, s94, 0x40c00
	s_addc_u32 s63, s95, 0
	s_add_u32 s64, s94, 0x40d00
	s_addc_u32 s65, s95, 0
	s_add_u32 s66, s94, 0x40e00
	s_addc_u32 s67, s95, 0
	s_add_u32 s70, s94, 0x40f00
	s_addc_u32 s71, s95, 0
	s_add_u32 s72, s94, 0x41000
	s_addc_u32 s73, s95, 0
	s_add_u32 s74, s94, 0x41100
	s_addc_u32 s75, s95, 0
	s_add_u32 s34, s94, 0x41200
	s_addc_u32 s35, s95, 0
	s_add_u32 s48, s94, 0x41300
	s_addc_u32 s49, s95, 0
	s_mov_b32 s19, 1
	v_mov_b32_e32 v16, 0
	s_branch .LBB0_687
